# cross-lane reductions (lane^16 / lane^32 hops) via v_permlane16/32_swap instead of ds_bpermute round trips: attention row max, fused-LN row stats, rms
# baseline (speedup 1.0000x reference)
.LBB0_435:
	s_nop 0
	v_max3_f32 v121, v50, s50, v51
	v_max3_f32 v121, v121, v52, v53
	v_max3_f32 v121, v121, v54, v55
	v_max3_f32 v121, v121, v56, v57
	v_max3_f32 v121, v121, v58, v59
	v_max3_f32 v121, v121, v60, v61
	v_max3_f32 v121, v121, v62, v63
	v_max3_f32 v121, v121, v64, v65
	s_nop 1
	v_max3_f32 v121, v121, v34, v35
	v_max3_f32 v121, v121, v36, v37
	v_max3_f32 v121, v121, v38, v39
	v_max3_f32 v121, v121, v40, v41
	v_max3_f32 v121, v121, v42, v43
	v_max3_f32 v121, v121, v44, v45
	v_max3_f32 v121, v121, v46, v47
	v_max3_f32 v121, v121, v48, v49
	v_mov_b32_e32 v122, v121
	s_nop 1
	v_permlane32_swap_b32_e32 v122, v121
	v_max3_f32 v121, v120, v121, v122
	v_cmp_gt_f32_e32 vcc, v121, v120
	s_cbranch_vccz .LBB0_437
	v_sub_f32_e32 v120, v120, v121
	v_exp_f32_e32 v120, v120
	s_nop 0
	v_pk_mul_f32 v[32:33], v[32:33], v[120:121] op_sel_hi:[1,0]
	v_pk_mul_f32 v[30:31], v[30:31], v[120:121] op_sel_hi:[1,0]
	v_pk_mul_f32 v[28:29], v[28:29], v[120:121] op_sel_hi:[1,0]
	v_pk_mul_f32 v[26:27], v[26:27], v[120:121] op_sel_hi:[1,0]
	v_pk_mul_f32 v[24:25], v[24:25], v[120:121] op_sel_hi:[1,0]
	v_pk_mul_f32 v[22:23], v[22:23], v[120:121] op_sel_hi:[1,0]
	v_pk_mul_f32 v[20:21], v[20:21], v[120:121] op_sel_hi:[1,0]
	v_pk_mul_f32 v[18:19], v[18:19], v[120:121] op_sel_hi:[1,0]
	v_pk_mul_f32 v[16:17], v[16:17], v[120:121] op_sel_hi:[1,0]
	v_pk_mul_f32 v[14:15], v[14:15], v[120:121] op_sel_hi:[1,0]
	v_pk_mul_f32 v[12:13], v[12:13], v[120:121] op_sel_hi:[1,0]
	v_pk_mul_f32 v[10:11], v[10:11], v[120:121] op_sel_hi:[1,0]
	v_pk_mul_f32 v[8:9], v[8:9], v[120:121] op_sel_hi:[1,0]
	v_pk_mul_f32 v[6:7], v[6:7], v[120:121] op_sel_hi:[1,0]
	v_pk_mul_f32 v[4:5], v[4:5], v[120:121] op_sel_hi:[1,0]
	v_pk_mul_f32 v[2:3], v[2:3], v[120:121] op_sel_hi:[1,0]
	v_mul_f32_e32 v109, v109, v120

.LBB0_445:
	s_nop 0
	v_max3_f32 v119, v50, s50, v51
	v_max3_f32 v119, v119, v52, v53
	v_max3_f32 v119, v119, v54, v55
	v_max3_f32 v119, v119, v56, v57
	v_max3_f32 v119, v119, v58, v59
	v_max3_f32 v119, v119, v60, v61
	v_max3_f32 v119, v119, v62, v63
	v_max3_f32 v119, v119, v64, v65
	s_nop 1
	v_max3_f32 v119, v119, v34, v35
	v_max3_f32 v119, v119, v36, v37
	v_max3_f32 v119, v119, v38, v39
	v_max3_f32 v119, v119, v40, v41
	v_max3_f32 v119, v119, v42, v43
	v_max3_f32 v119, v119, v44, v45
	v_max3_f32 v119, v119, v46, v47
	v_max3_f32 v119, v119, v48, v49
	v_mov_b32_e32 v121, v119
	s_nop 1
	v_permlane32_swap_b32_e32 v121, v119
	v_max3_f32 v119, v120, v119, v121
	v_cmp_gt_f32_e32 vcc, v119, v120
	s_cbranch_vccz .LBB0_426
	v_sub_f32_e32 v120, v120, v119
	v_exp_f32_e32 v120, v120
	s_nop 0
	v_pk_mul_f32 v[32:33], v[32:33], v[120:121] op_sel_hi:[1,0]
	v_pk_mul_f32 v[30:31], v[30:31], v[120:121] op_sel_hi:[1,0]
	v_pk_mul_f32 v[28:29], v[28:29], v[120:121] op_sel_hi:[1,0]
	v_pk_mul_f32 v[26:27], v[26:27], v[120:121] op_sel_hi:[1,0]
	v_pk_mul_f32 v[24:25], v[24:25], v[120:121] op_sel_hi:[1,0]
	v_pk_mul_f32 v[22:23], v[22:23], v[120:121] op_sel_hi:[1,0]
	v_pk_mul_f32 v[20:21], v[20:21], v[120:121] op_sel_hi:[1,0]
	v_pk_mul_f32 v[18:19], v[18:19], v[120:121] op_sel_hi:[1,0]
	v_pk_mul_f32 v[16:17], v[16:17], v[120:121] op_sel_hi:[1,0]
	v_pk_mul_f32 v[14:15], v[14:15], v[120:121] op_sel_hi:[1,0]
	v_pk_mul_f32 v[12:13], v[12:13], v[120:121] op_sel_hi:[1,0]
	v_pk_mul_f32 v[10:11], v[10:11], v[120:121] op_sel_hi:[1,0]
	v_pk_mul_f32 v[8:9], v[8:9], v[120:121] op_sel_hi:[1,0]
	v_pk_mul_f32 v[6:7], v[6:7], v[120:121] op_sel_hi:[1,0]
	v_pk_mul_f32 v[4:5], v[4:5], v[120:121] op_sel_hi:[1,0]
	v_pk_mul_f32 v[2:3], v[2:3], v[120:121] op_sel_hi:[1,0]
	v_mul_f32_e32 v109, v109, v120
	s_branch .LBB0_426

; __device__ __forceinline__ float shx(float v, int mask, int lane) { return __int_as_float(__builtin_amdgcn_ds_bpermute((lane ^ mask) << 2, __float_as_int(v))); }
; __device__ __forceinline__ u32x4 pk8(f32x4 a, f32x4 b) { const u32x2 x = pk4(a), y = pk4(b); return (u32x4){x.x, x.y, y.x, y.y}; }
; #define UNPK(w) (f32x4){__uint_as_float((w).x << 16), __uint_as_float((w).x & 0xffff0000u), __uint_as_float((w).y << 16), __uint_as_float((w).y & 0xffff0000u)}
; #define UNPK(w) (f32x4){__uint_as_float((w).x << 16), __uint_as_float((w).x & 0xffff0000u), __uint_as_float((w).y << 16), __uint_as_float((w).y & 0xffff0000u)}
; __device__ __forceinline__ float wave_sum(float v, int lane) {
; #pragma unroll
;     for (int o = 1; o < 64; o <<= 1) v += shx(v, o, lane);
;     return v;
; __global__ void __launch_bounds__(NTHR, 2) fwd(Args args) {
;     ...
;                 for (int row = gw; row < R; row += NGW) {
; #pragma unroll
;                     for (int hh = 0; hh < 8; ++hh) { const size_t o = (size_t)row * 4096 + hh * 512 + lane * 8; const u32x4 ow = __builtin_nontemporal_load((const u32x4*)(O2 + o)), gw4 = __builtin_nontemporal_load((const u32x4*)(SG + o));
;                         const f32x4 v0 = UNPK(((u32x2){ow.x, ow.y})), v1 = UNPK(((u32x2){ow.z, ow.w}));
;                         const float ss = wave_sum((v0[0] * v0[0] + v0[1] * v0[1]) + (v0[2] * v0[2] + v0[3] * v0[3]) + (v1[0] * v1[0] + v1[1] * v1[1]) + (v1[2] * v1[2] + v1[3] * v1[3]), lane);
;                         const float rs = 1.f / sqrtf(ss * (1.f / 512.f) + LN_EPS);
;                         const f32x4 ga = UNPK(((u32x2){gw4.x, gw4.y})), gb2 = UNPK(((u32x2){gw4.z, gw4.w}));
;                         *(u32x4*)(RO + o) = pk8(v0 * rs * ga, v1 * rs * gb2); }
.LBB0_769:
	s_mov_b64 s[98:99], 0x1d400000
	v_lshl_add_u64 v[28:29], v[6:7], 0, s[98:99]
	s_mov_b32 s98, 0xf9400000
	s_mov_b32 s99, -1
	v_lshl_add_u64 v[30:31], v[6:7], 0, s[98:99]
	s_mov_b64 s[98:99], 0x1000
	v_lshl_add_u64 v[160:161], v[28:29], 0, s[98:99]
	v_lshl_add_u64 v[162:163], v[30:31], 0, s[98:99]
	v_lshl_add_u64 v[164:165], v[6:7], 0, s[98:99]
	global_load_dwordx4 v[32:35], v[28:29], off nt
	global_load_dwordx4 v[36:39], v[30:31], off nt
	global_load_dwordx4 v[40:43], v[28:29], off offset:1024 nt
	global_load_dwordx4 v[44:47], v[30:31], off offset:1024 nt
	global_load_dwordx4 v[48:51], v[28:29], off offset:2048 nt
	global_load_dwordx4 v[52:55], v[30:31], off offset:2048 nt
	global_load_dwordx4 v[56:59], v[28:29], off offset:3072 nt
	global_load_dwordx4 v[60:63], v[30:31], off offset:3072 nt
	global_load_dwordx4 v[64:67], v[160:161], off nt
	global_load_dwordx4 v[68:71], v[162:163], off nt
	global_load_dwordx4 v[72:75], v[160:161], off offset:1024 nt
	global_load_dwordx4 v[76:79], v[162:163], off offset:1024 nt
	global_load_dwordx4 v[80:83], v[160:161], off offset:2048 nt
	global_load_dwordx4 v[84:87], v[162:163], off offset:2048 nt
	global_load_dwordx4 v[88:91], v[160:161], off offset:3072 nt
	global_load_dwordx4 v[92:95], v[162:163], off offset:3072 nt
	s_waitcnt vmcnt(14)
	v_lshlrev_b32_e32 v2, 16, v32
	v_and_b32_e32 v3, 0xffff0000, v32
	v_lshlrev_b32_e32 v32, 16, v33
	v_and_b32_e32 v33, 0xffff0000, v33
	v_mul_f32_e32 v0, v3, v3
	v_mul_f32_e32 v22, v33, v33
	v_fmac_f32_e32 v0, v2, v2
	v_fmac_f32_e32 v22, v32, v32
	v_add_f32_e32 v0, v0, v22
	v_lshlrev_b32_e32 v23, 16, v35
	v_lshlrev_b32_e32 v22, 16, v34
	v_and_b32_e32 v35, 0xffff0000, v35
	v_and_b32_e32 v34, 0xffff0000, v34
	v_pk_mul_f32 v[24:25], v[34:35], v[34:35]
	s_nop 0
	v_pk_fma_f32 v[24:25], v[22:23], v[22:23], v[24:25]
	s_nop 0
	v_add_f32_e32 v0, v24, v0
	v_add_f32_e32 v0, v25, v0
	ds_bpermute_b32 v24, v12, v0
	s_waitcnt lgkmcnt(0)
	v_add_f32_e32 v0, v0, v24
	ds_bpermute_b32 v24, v13, v0
	s_waitcnt lgkmcnt(0)
	v_add_f32_e32 v0, v0, v24
	ds_bpermute_b32 v24, v14, v0
	s_waitcnt lgkmcnt(0)
	v_add_f32_e32 v0, v0, v24
	ds_bpermute_b32 v24, v15, v0
	s_waitcnt lgkmcnt(0)
	v_add_f32_e32 v0, v0, v24
	v_mov_b32_e32 v24, v0
	s_nop 1
	v_permlane16_swap_b32_e32 v24, v0
	v_add_f32_e32 v0, v0, v24
	v_mov_b32_e32 v24, v0
	s_nop 1
	v_permlane32_swap_b32_e32 v24, v0
	v_add_f32_e32 v0, v0, v24
	v_fmamk_f32 v0, v0, 0x3b000000, v244
	v_cmp_gt_f32_e32 vcc, s83, v0
	v_mul_f32_e32 v24, 0x4f800000, v0
	s_nop 0
	v_cndmask_b32_e32 v0, v0, v24, vcc
	v_sqrt_f32_e32 v24, v0
	s_nop 0
	v_add_u32_e32 v25, -1, v24
	v_fma_f32 v26, -v25, v24, v0
	v_cmp_ge_f32_e64 s[2:3], 0, v26
	v_add_u32_e32 v26, 1, v24
	s_nop 0
	v_cndmask_b32_e64 v25, v24, v25, s[2:3]
	v_fma_f32 v24, -v26, v24, v0
	v_cmp_lt_f32_e64 s[2:3], 0, v24
	s_nop 1
	v_cndmask_b32_e64 v24, v25, v26, s[2:3]
	v_mul_f32_e32 v25, 0x37800000, v24
	v_cndmask_b32_e32 v24, v24, v25, vcc
	v_cmp_class_f32_e32 vcc, v0, v245
	s_nop 1
	v_cndmask_b32_e32 v0, v24, v0, vcc
	v_div_scale_f32 v24, s[2:3], v0, v0, 1.0
	v_rcp_f32_e32 v25, v24
	s_nop 0
	v_fma_f32 v26, -v24, v25, 1.0
	v_fmac_f32_e32 v25, v26, v25
	v_div_scale_f32 v26, vcc, 1.0, v0, 1.0
	v_mul_f32_e32 v27, v26, v25
	v_fma_f32 v28, -v24, v27, v26
	v_fmac_f32_e32 v27, v28, v25
	v_fma_f32 v24, -v24, v27, v26
	v_div_fmas_f32 v24, v24, v25, v27
	v_div_fixup_f32 v0, v24, v0, 1.0
	v_lshlrev_b32_e32 v24, 16, v36
	v_and_b32_e32 v25, 0xffff0000, v36
	v_lshlrev_b32_e32 v36, 16, v37
	v_and_b32_e32 v37, 0xffff0000, v37
	v_pk_mul_f32 v[32:33], v[32:33], v[0:1] op_sel_hi:[1,0]
	v_lshlrev_b32_e32 v26, 16, v38
	v_pk_mul_f32 v[36:37], v[32:33], v[36:37]
	v_mov_b32_e32 v32, v22
	v_mov_b32_e32 v33, v34
	v_mov_b32_e32 v34, v23
	v_and_b32_e32 v27, 0xffff0000, v38
	v_lshlrev_b32_e32 v38, 16, v39
	v_and_b32_e32 v39, 0xffff0000, v39
	v_pk_mul_f32 v[32:33], v[0:1], v[32:33] op_sel_hi:[0,1]
	v_pk_mul_f32 v[34:35], v[0:1], v[34:35] op_sel_hi:[0,1]
	v_pk_mul_f32 v[2:3], v[2:3], v[0:1] op_sel_hi:[1,0]
	v_pk_mul_f32 v[38:39], v[34:35], v[38:39]
	v_pk_mul_f32 v[34:35], v[32:33], v[26:27]
	v_pk_mul_f32 v[2:3], v[2:3], v[24:25]
	s_nop 0
	v_cvt_pk_bf16_f32 v32, v2, v3
	v_cvt_pk_bf16_f32 v33, v36, v37
	v_cvt_pk_bf16_f32 v34, v34, v35
	v_cvt_pk_bf16_f32 v35, v38, v39
	s_waitcnt vmcnt(12)
	v_lshlrev_b32_e32 v2, 16, v40
	v_and_b32_e32 v3, 0xffff0000, v40
	v_lshlrev_b32_e32 v40, 16, v41
	v_and_b32_e32 v41, 0xffff0000, v41
	v_mul_f32_e32 v0, v3, v3
	v_mul_f32_e32 v22, v41, v41
	v_fmac_f32_e32 v0, v2, v2
	v_fmac_f32_e32 v22, v40, v40
	v_add_f32_e32 v0, v0, v22
	v_lshlrev_b32_e32 v23, 16, v43
	v_lshlrev_b32_e32 v22, 16, v42
	v_and_b32_e32 v43, 0xffff0000, v43
	v_and_b32_e32 v42, 0xffff0000, v42
	v_pk_mul_f32 v[24:25], v[42:43], v[42:43]
	s_nop 0
	v_pk_fma_f32 v[24:25], v[22:23], v[22:23], v[24:25]
	s_nop 0
	v_add_f32_e32 v0, v24, v0
	v_add_f32_e32 v0, v25, v0
	ds_bpermute_b32 v24, v12, v0
	s_waitcnt lgkmcnt(0)
	v_add_f32_e32 v0, v0, v24
	ds_bpermute_b32 v24, v13, v0
	s_waitcnt lgkmcnt(0)
	v_add_f32_e32 v0, v0, v24
	ds_bpermute_b32 v24, v14, v0
	s_waitcnt lgkmcnt(0)
	v_add_f32_e32 v0, v0, v24
	ds_bpermute_b32 v24, v15, v0
	s_waitcnt lgkmcnt(0)
; __device__ __forceinline__ float shx(float v, int mask, int lane) { return __int_as_float(__builtin_amdgcn_ds_bpermute((lane ^ mask) << 2, __float_as_int(v))); }
; __device__ __forceinline__ u32x4 pk8(f32x4 a, f32x4 b) { const u32x2 x = pk4(a), y = pk4(b); return (u32x4){x.x, x.y, y.x, y.y}; }
; #define UNPK(w) (f32x4){__uint_as_float((w).x << 16), __uint_as_float((w).x & 0xffff0000u), __uint_as_float((w).y << 16), __uint_as_float((w).y & 0xffff0000u)}
; #define UNPK(w) (f32x4){__uint_as_float((w).x << 16), __uint_as_float((w).x & 0xffff0000u), __uint_as_float((w).y << 16), __uint_as_float((w).y & 0xffff0000u)}
; __device__ __forceinline__ float wave_sum(float v, int lane) {
; #pragma unroll
;     for (int o = 1; o < 64; o <<= 1) v += shx(v, o, lane);
;     return v;
; __global__ void __launch_bounds__(NTHR, 2) fwd(Args args) {
;     ...
;                     for (int hh = 0; hh < 8; ++hh) { const size_t o = (size_t)row * 4096 + hh * 512 + lane * 8; const u32x4 ow = __builtin_nontemporal_load((const u32x4*)(O2 + o)), gw4 = __builtin_nontemporal_load((const u32x4*)(SG + o));
;                         const f32x4 v0 = UNPK(((u32x2){ow.x, ow.y})), v1 = UNPK(((u32x2){ow.z, ow.w}));
;                         const float ss = wave_sum((v0[0] * v0[0] + v0[1] * v0[1]) + (v0[2] * v0[2] + v0[3] * v0[3]) + (v1[0] * v1[0] + v1[1] * v1[1]) + (v1[2] * v1[2] + v1[3] * v1[3]), lane);
;                         const float rs = 1.f / sqrtf(ss * (1.f / 512.f) + LN_EPS);
;                         const f32x4 ga = UNPK(((u32x2){gw4.x, gw4.y})), gb2 = UNPK(((u32x2){gw4.z, gw4.w}));
;                         *(u32x4*)(RO + o) = pk8(v0 * rs * ga, v1 * rs * gb2); }
	v_add_f32_e32 v0, v0, v24
	v_mov_b32_e32 v24, v0
	s_nop 1
	v_permlane16_swap_b32_e32 v24, v0
	v_add_f32_e32 v0, v0, v24
	v_mov_b32_e32 v24, v0
	s_nop 1
	v_permlane32_swap_b32_e32 v24, v0
	v_add_f32_e32 v0, v0, v24
	v_fmamk_f32 v0, v0, 0x3b000000, v244
	v_cmp_gt_f32_e32 vcc, s83, v0
	v_mul_f32_e32 v24, 0x4f800000, v0
	s_nop 0
	v_cndmask_b32_e32 v0, v0, v24, vcc
	v_sqrt_f32_e32 v24, v0
	s_nop 0
	v_add_u32_e32 v25, -1, v24
	v_fma_f32 v26, -v25, v24, v0
	v_cmp_ge_f32_e64 s[2:3], 0, v26
	v_add_u32_e32 v26, 1, v24
	s_nop 0
	v_cndmask_b32_e64 v25, v24, v25, s[2:3]
	v_fma_f32 v24, -v26, v24, v0
	v_cmp_lt_f32_e64 s[2:3], 0, v24
	s_nop 1
	v_cndmask_b32_e64 v24, v25, v26, s[2:3]
	v_mul_f32_e32 v25, 0x37800000, v24
	v_cndmask_b32_e32 v24, v24, v25, vcc
	v_cmp_class_f32_e32 vcc, v0, v245
	s_nop 1
	v_cndmask_b32_e32 v0, v24, v0, vcc
	v_div_scale_f32 v24, s[2:3], v0, v0, 1.0
	v_rcp_f32_e32 v25, v24
	s_nop 0
	v_fma_f32 v26, -v24, v25, 1.0
	v_fmac_f32_e32 v25, v26, v25
	v_div_scale_f32 v26, vcc, 1.0, v0, 1.0
	v_mul_f32_e32 v27, v26, v25
	v_fma_f32 v28, -v24, v27, v26
	v_fmac_f32_e32 v27, v28, v25
	v_fma_f32 v24, -v24, v27, v26
	v_div_fmas_f32 v24, v24, v25, v27
	v_div_fixup_f32 v0, v24, v0, 1.0
	v_lshlrev_b32_e32 v24, 16, v44
	v_and_b32_e32 v25, 0xffff0000, v44
	v_lshlrev_b32_e32 v44, 16, v45
	v_and_b32_e32 v45, 0xffff0000, v45
	v_pk_mul_f32 v[40:41], v[40:41], v[0:1] op_sel_hi:[1,0]
	v_lshlrev_b32_e32 v26, 16, v46
	v_pk_mul_f32 v[44:45], v[40:41], v[44:45]
	v_mov_b32_e32 v40, v22
	v_mov_b32_e32 v41, v42
	v_mov_b32_e32 v42, v23
	v_and_b32_e32 v27, 0xffff0000, v46
	v_lshlrev_b32_e32 v46, 16, v47
	v_and_b32_e32 v47, 0xffff0000, v47
	v_pk_mul_f32 v[40:41], v[0:1], v[40:41] op_sel_hi:[0,1]
	v_pk_mul_f32 v[42:43], v[0:1], v[42:43] op_sel_hi:[0,1]
	v_pk_mul_f32 v[2:3], v[2:3], v[0:1] op_sel_hi:[1,0]
	v_pk_mul_f32 v[46:47], v[42:43], v[46:47]
	v_pk_mul_f32 v[42:43], v[40:41], v[26:27]
	v_pk_mul_f32 v[2:3], v[2:3], v[24:25]
	s_nop 0
	v_cvt_pk_bf16_f32 v40, v2, v3
	v_cvt_pk_bf16_f32 v41, v44, v45
	v_cvt_pk_bf16_f32 v42, v42, v43
	v_cvt_pk_bf16_f32 v43, v46, v47
	s_waitcnt vmcnt(10)
	v_lshlrev_b32_e32 v2, 16, v48
	v_and_b32_e32 v3, 0xffff0000, v48
	v_lshlrev_b32_e32 v48, 16, v49
	v_and_b32_e32 v49, 0xffff0000, v49
	v_mul_f32_e32 v0, v3, v3
	v_mul_f32_e32 v22, v49, v49
	v_fmac_f32_e32 v0, v2, v2
	v_fmac_f32_e32 v22, v48, v48
	v_add_f32_e32 v0, v0, v22
	v_lshlrev_b32_e32 v23, 16, v51
	v_lshlrev_b32_e32 v22, 16, v50
	v_and_b32_e32 v51, 0xffff0000, v51
	v_and_b32_e32 v50, 0xffff0000, v50
	v_pk_mul_f32 v[24:25], v[50:51], v[50:51]
	s_nop 0
	v_pk_fma_f32 v[24:25], v[22:23], v[22:23], v[24:25]
	s_nop 0
	v_add_f32_e32 v0, v24, v0
	v_add_f32_e32 v0, v25, v0
	ds_bpermute_b32 v24, v12, v0
	s_waitcnt lgkmcnt(0)
	v_add_f32_e32 v0, v0, v24
	ds_bpermute_b32 v24, v13, v0
	s_waitcnt lgkmcnt(0)
	v_add_f32_e32 v0, v0, v24
	ds_bpermute_b32 v24, v14, v0
	s_waitcnt lgkmcnt(0)
	v_add_f32_e32 v0, v0, v24
	ds_bpermute_b32 v24, v15, v0
	s_waitcnt lgkmcnt(0)
	v_add_f32_e32 v0, v0, v24
	v_mov_b32_e32 v24, v0
	s_nop 1
	v_permlane16_swap_b32_e32 v24, v0
	v_add_f32_e32 v0, v0, v24
	v_mov_b32_e32 v24, v0
	s_nop 1
	v_permlane32_swap_b32_e32 v24, v0
	v_add_f32_e32 v0, v0, v24
	v_fmamk_f32 v0, v0, 0x3b000000, v244
	v_cmp_gt_f32_e32 vcc, s83, v0
	v_mul_f32_e32 v24, 0x4f800000, v0
	s_nop 0
	v_cndmask_b32_e32 v0, v0, v24, vcc
	v_sqrt_f32_e32 v24, v0
	s_nop 0
	v_add_u32_e32 v25, -1, v24
	v_fma_f32 v26, -v25, v24, v0
	v_cmp_ge_f32_e64 s[2:3], 0, v26
	v_add_u32_e32 v26, 1, v24
	s_nop 0
	v_cndmask_b32_e64 v25, v24, v25, s[2:3]
	v_fma_f32 v24, -v26, v24, v0
	v_cmp_lt_f32_e64 s[2:3], 0, v24
	s_nop 1
	v_cndmask_b32_e64 v24, v25, v26, s[2:3]
	v_mul_f32_e32 v25, 0x37800000, v24
	v_cndmask_b32_e32 v24, v24, v25, vcc
	v_cmp_class_f32_e32 vcc, v0, v245
	s_nop 1
	v_cndmask_b32_e32 v0, v24, v0, vcc
	v_div_scale_f32 v24, s[2:3], v0, v0, 1.0
	v_rcp_f32_e32 v25, v24
	s_nop 0
	v_fma_f32 v26, -v24, v25, 1.0
	v_fmac_f32_e32 v25, v26, v25
	v_div_scale_f32 v26, vcc, 1.0, v0, 1.0
	v_mul_f32_e32 v27, v26, v25
	v_fma_f32 v28, -v24, v27, v26
	v_fmac_f32_e32 v27, v28, v25
	v_fma_f32 v24, -v24, v27, v26
	v_div_fmas_f32 v24, v24, v25, v27
	v_div_fixup_f32 v0, v24, v0, 1.0
	v_lshlrev_b32_e32 v24, 16, v52
	v_and_b32_e32 v25, 0xffff0000, v52
	v_lshlrev_b32_e32 v52, 16, v53
	v_and_b32_e32 v53, 0xffff0000, v53
	v_pk_mul_f32 v[48:49], v[48:49], v[0:1] op_sel_hi:[1,0]
	v_lshlrev_b32_e32 v26, 16, v54
	v_pk_mul_f32 v[52:53], v[48:49], v[52:53]
	v_mov_b32_e32 v48, v22
	v_mov_b32_e32 v49, v50
	v_mov_b32_e32 v50, v23
	v_and_b32_e32 v27, 0xffff0000, v54
	v_lshlrev_b32_e32 v54, 16, v55
	v_and_b32_e32 v55, 0xffff0000, v55
	v_pk_mul_f32 v[48:49], v[0:1], v[48:49] op_sel_hi:[0,1]
	v_pk_mul_f32 v[50:51], v[0:1], v[50:51] op_sel_hi:[0,1]
	v_pk_mul_f32 v[2:3], v[2:3], v[0:1] op_sel_hi:[1,0]
	v_pk_mul_f32 v[54:55], v[50:51], v[54:55]
	v_pk_mul_f32 v[50:51], v[48:49], v[26:27]
	v_pk_mul_f32 v[2:3], v[2:3], v[24:25]
	s_nop 0
	v_cvt_pk_bf16_f32 v48, v2, v3
	v_cvt_pk_bf16_f32 v49, v52, v53
	v_cvt_pk_bf16_f32 v50, v50, v51
	v_cvt_pk_bf16_f32 v51, v54, v55
	s_waitcnt vmcnt(8)
	v_lshlrev_b32_e32 v2, 16, v56
	v_and_b32_e32 v3, 0xffff0000, v56
	v_lshlrev_b32_e32 v56, 16, v57
	v_and_b32_e32 v57, 0xffff0000, v57
	v_mul_f32_e32 v0, v3, v3
	v_mul_f32_e32 v22, v57, v57
	v_fmac_f32_e32 v0, v2, v2
	v_fmac_f32_e32 v22, v56, v56
	v_add_f32_e32 v0, v0, v22
	v_lshlrev_b32_e32 v23, 16, v59
	v_lshlrev_b32_e32 v22, 16, v58
	v_and_b32_e32 v59, 0xffff0000, v59
	v_and_b32_e32 v58, 0xffff0000, v58
	v_pk_mul_f32 v[24:25], v[58:59], v[58:59]
	s_nop 0
	v_pk_fma_f32 v[24:25], v[22:23], v[22:23], v[24:25]
	s_nop 0
	v_add_f32_e32 v0, v24, v0
	v_add_f32_e32 v0, v25, v0
	ds_bpermute_b32 v24, v12, v0
	s_waitcnt lgkmcnt(0)
; __device__ __forceinline__ float shx(float v, int mask, int lane) { return __int_as_float(__builtin_amdgcn_ds_bpermute((lane ^ mask) << 2, __float_as_int(v))); }
; __device__ __forceinline__ u32x4 pk8(f32x4 a, f32x4 b) { const u32x2 x = pk4(a), y = pk4(b); return (u32x4){x.x, x.y, y.x, y.y}; }
; #define UNPK(w) (f32x4){__uint_as_float((w).x << 16), __uint_as_float((w).x & 0xffff0000u), __uint_as_float((w).y << 16), __uint_as_float((w).y & 0xffff0000u)}
; #define UNPK(w) (f32x4){__uint_as_float((w).x << 16), __uint_as_float((w).x & 0xffff0000u), __uint_as_float((w).y << 16), __uint_as_float((w).y & 0xffff0000u)}
; __device__ __forceinline__ float wave_sum(float v, int lane) {
; #pragma unroll
;     for (int o = 1; o < 64; o <<= 1) v += shx(v, o, lane);
;     return v;
; __global__ void __launch_bounds__(NTHR, 2) fwd(Args args) {
;     ...
;                     for (int hh = 0; hh < 8; ++hh) { const size_t o = (size_t)row * 4096 + hh * 512 + lane * 8; const u32x4 ow = __builtin_nontemporal_load((const u32x4*)(O2 + o)), gw4 = __builtin_nontemporal_load((const u32x4*)(SG + o));
;                         const f32x4 v0 = UNPK(((u32x2){ow.x, ow.y})), v1 = UNPK(((u32x2){ow.z, ow.w}));
;                         const float ss = wave_sum((v0[0] * v0[0] + v0[1] * v0[1]) + (v0[2] * v0[2] + v0[3] * v0[3]) + (v1[0] * v1[0] + v1[1] * v1[1]) + (v1[2] * v1[2] + v1[3] * v1[3]), lane);
;                         const float rs = 1.f / sqrtf(ss * (1.f / 512.f) + LN_EPS);
;                         const f32x4 ga = UNPK(((u32x2){gw4.x, gw4.y})), gb2 = UNPK(((u32x2){gw4.z, gw4.w}));
;                         *(u32x4*)(RO + o) = pk8(v0 * rs * ga, v1 * rs * gb2); }
	v_add_f32_e32 v0, v0, v24
	ds_bpermute_b32 v24, v13, v0
	s_waitcnt lgkmcnt(0)
	v_add_f32_e32 v0, v0, v24
	ds_bpermute_b32 v24, v14, v0
	s_waitcnt lgkmcnt(0)
	v_add_f32_e32 v0, v0, v24
	ds_bpermute_b32 v24, v15, v0
	s_waitcnt lgkmcnt(0)
	v_add_f32_e32 v0, v0, v24
	v_mov_b32_e32 v24, v0
	s_nop 1
	v_permlane16_swap_b32_e32 v24, v0
	v_add_f32_e32 v0, v0, v24
	v_mov_b32_e32 v24, v0
	s_nop 1
	v_permlane32_swap_b32_e32 v24, v0
	v_add_f32_e32 v0, v0, v24
	v_fmamk_f32 v0, v0, 0x3b000000, v244
	v_cmp_gt_f32_e32 vcc, s83, v0
	v_mul_f32_e32 v24, 0x4f800000, v0
	s_nop 0
	v_cndmask_b32_e32 v0, v0, v24, vcc
	v_sqrt_f32_e32 v24, v0
	s_nop 0
	v_add_u32_e32 v25, -1, v24
	v_fma_f32 v26, -v25, v24, v0
	v_cmp_ge_f32_e64 s[2:3], 0, v26
	v_add_u32_e32 v26, 1, v24
	s_nop 0
	v_cndmask_b32_e64 v25, v24, v25, s[2:3]
	v_fma_f32 v24, -v26, v24, v0
	v_cmp_lt_f32_e64 s[2:3], 0, v24
	s_nop 1
	v_cndmask_b32_e64 v24, v25, v26, s[2:3]
	v_mul_f32_e32 v25, 0x37800000, v24
	v_cndmask_b32_e32 v24, v24, v25, vcc
	v_cmp_class_f32_e32 vcc, v0, v245
	s_nop 1
	v_cndmask_b32_e32 v0, v24, v0, vcc
	v_div_scale_f32 v24, s[2:3], v0, v0, 1.0
	v_rcp_f32_e32 v25, v24
	s_nop 0
	v_fma_f32 v26, -v24, v25, 1.0
	v_fmac_f32_e32 v25, v26, v25
	v_div_scale_f32 v26, vcc, 1.0, v0, 1.0
	v_mul_f32_e32 v27, v26, v25
	v_fma_f32 v28, -v24, v27, v26
	v_fmac_f32_e32 v27, v28, v25
	v_fma_f32 v24, -v24, v27, v26
	v_div_fmas_f32 v24, v24, v25, v27
	v_div_fixup_f32 v0, v24, v0, 1.0
	v_lshlrev_b32_e32 v24, 16, v60
	v_and_b32_e32 v25, 0xffff0000, v60
	v_lshlrev_b32_e32 v60, 16, v61
	v_and_b32_e32 v61, 0xffff0000, v61
	v_pk_mul_f32 v[56:57], v[56:57], v[0:1] op_sel_hi:[1,0]
	v_lshlrev_b32_e32 v26, 16, v62
	v_pk_mul_f32 v[60:61], v[56:57], v[60:61]
	v_mov_b32_e32 v56, v22
	v_mov_b32_e32 v57, v58
	v_mov_b32_e32 v58, v23
	v_and_b32_e32 v27, 0xffff0000, v62
	v_lshlrev_b32_e32 v62, 16, v63
	v_and_b32_e32 v63, 0xffff0000, v63
	v_pk_mul_f32 v[56:57], v[0:1], v[56:57] op_sel_hi:[0,1]
	v_pk_mul_f32 v[58:59], v[0:1], v[58:59] op_sel_hi:[0,1]
	v_pk_mul_f32 v[2:3], v[2:3], v[0:1] op_sel_hi:[1,0]
	v_pk_mul_f32 v[62:63], v[58:59], v[62:63]
	v_pk_mul_f32 v[58:59], v[56:57], v[26:27]
	v_pk_mul_f32 v[2:3], v[2:3], v[24:25]
	s_nop 0
	v_cvt_pk_bf16_f32 v56, v2, v3
	v_cvt_pk_bf16_f32 v57, v60, v61
	v_cvt_pk_bf16_f32 v58, v58, v59
	v_cvt_pk_bf16_f32 v59, v62, v63
	s_waitcnt vmcnt(6)
	v_lshlrev_b32_e32 v2, 16, v64
	v_and_b32_e32 v3, 0xffff0000, v64
	v_lshlrev_b32_e32 v64, 16, v65
	v_and_b32_e32 v65, 0xffff0000, v65
	v_mul_f32_e32 v0, v3, v3
	v_mul_f32_e32 v22, v65, v65
	v_fmac_f32_e32 v0, v2, v2
	v_fmac_f32_e32 v22, v64, v64
	v_add_f32_e32 v0, v0, v22
	v_lshlrev_b32_e32 v23, 16, v67
	v_lshlrev_b32_e32 v22, 16, v66
	v_and_b32_e32 v67, 0xffff0000, v67
	v_and_b32_e32 v66, 0xffff0000, v66
	v_pk_mul_f32 v[24:25], v[66:67], v[66:67]
	s_nop 0
	v_pk_fma_f32 v[24:25], v[22:23], v[22:23], v[24:25]
	s_nop 0
	v_add_f32_e32 v0, v24, v0
	v_add_f32_e32 v0, v25, v0
	ds_bpermute_b32 v24, v12, v0
	s_waitcnt lgkmcnt(0)
	v_add_f32_e32 v0, v0, v24
	ds_bpermute_b32 v24, v13, v0
	s_waitcnt lgkmcnt(0)
	v_add_f32_e32 v0, v0, v24
	ds_bpermute_b32 v24, v14, v0
	s_waitcnt lgkmcnt(0)
	v_add_f32_e32 v0, v0, v24
	ds_bpermute_b32 v24, v15, v0
	s_waitcnt lgkmcnt(0)
	v_add_f32_e32 v0, v0, v24
	v_mov_b32_e32 v24, v0
	s_nop 1
	v_permlane16_swap_b32_e32 v24, v0
	v_add_f32_e32 v0, v0, v24
	v_mov_b32_e32 v24, v0
	s_nop 1
	v_permlane32_swap_b32_e32 v24, v0
	v_add_f32_e32 v0, v0, v24
	v_fmamk_f32 v0, v0, 0x3b000000, v244
	v_cmp_gt_f32_e32 vcc, s83, v0
	v_mul_f32_e32 v24, 0x4f800000, v0
	s_nop 0
	v_cndmask_b32_e32 v0, v0, v24, vcc
	v_sqrt_f32_e32 v24, v0
	s_nop 0
	v_add_u32_e32 v25, -1, v24
	v_fma_f32 v26, -v25, v24, v0
	v_cmp_ge_f32_e64 s[2:3], 0, v26
	v_add_u32_e32 v26, 1, v24
	s_nop 0
	v_cndmask_b32_e64 v25, v24, v25, s[2:3]
	v_fma_f32 v24, -v26, v24, v0
	v_cmp_lt_f32_e64 s[2:3], 0, v24
	s_nop 1
	v_cndmask_b32_e64 v24, v25, v26, s[2:3]
	v_mul_f32_e32 v25, 0x37800000, v24
	v_cndmask_b32_e32 v24, v24, v25, vcc
	v_cmp_class_f32_e32 vcc, v0, v245
	s_nop 1
	v_cndmask_b32_e32 v0, v24, v0, vcc
	v_div_scale_f32 v24, s[2:3], v0, v0, 1.0
	v_rcp_f32_e32 v25, v24
	s_nop 0
	v_fma_f32 v26, -v24, v25, 1.0
	v_fmac_f32_e32 v25, v26, v25
	v_div_scale_f32 v26, vcc, 1.0, v0, 1.0
	v_mul_f32_e32 v27, v26, v25
	v_fma_f32 v28, -v24, v27, v26
	v_fmac_f32_e32 v27, v28, v25
	v_fma_f32 v24, -v24, v27, v26
	v_div_fmas_f32 v24, v24, v25, v27
	v_div_fixup_f32 v0, v24, v0, 1.0
	v_lshlrev_b32_e32 v24, 16, v68
	v_and_b32_e32 v25, 0xffff0000, v68
	v_lshlrev_b32_e32 v68, 16, v69
	v_and_b32_e32 v69, 0xffff0000, v69
	v_pk_mul_f32 v[64:65], v[64:65], v[0:1] op_sel_hi:[1,0]
	v_lshlrev_b32_e32 v26, 16, v70
	v_pk_mul_f32 v[68:69], v[64:65], v[68:69]
	v_mov_b32_e32 v64, v22
	v_mov_b32_e32 v65, v66
	v_mov_b32_e32 v66, v23
	v_and_b32_e32 v27, 0xffff0000, v70
	v_lshlrev_b32_e32 v70, 16, v71
	v_and_b32_e32 v71, 0xffff0000, v71
	v_pk_mul_f32 v[64:65], v[0:1], v[64:65] op_sel_hi:[0,1]
	v_pk_mul_f32 v[66:67], v[0:1], v[66:67] op_sel_hi:[0,1]
	v_pk_mul_f32 v[2:3], v[2:3], v[0:1] op_sel_hi:[1,0]
	v_pk_mul_f32 v[70:71], v[66:67], v[70:71]
	v_pk_mul_f32 v[66:67], v[64:65], v[26:27]
	v_pk_mul_f32 v[2:3], v[2:3], v[24:25]
	s_nop 0
	v_cvt_pk_bf16_f32 v64, v2, v3
	v_cvt_pk_bf16_f32 v65, v68, v69
	v_cvt_pk_bf16_f32 v66, v66, v67
	v_cvt_pk_bf16_f32 v67, v70, v71
	s_waitcnt vmcnt(4)
	v_lshlrev_b32_e32 v2, 16, v72
	v_and_b32_e32 v3, 0xffff0000, v72
	v_lshlrev_b32_e32 v72, 16, v73
	v_and_b32_e32 v73, 0xffff0000, v73
	v_mul_f32_e32 v0, v3, v3
	v_mul_f32_e32 v22, v73, v73
	v_fmac_f32_e32 v0, v2, v2
	v_fmac_f32_e32 v22, v72, v72
	v_add_f32_e32 v0, v0, v22
	v_lshlrev_b32_e32 v23, 16, v75
	v_lshlrev_b32_e32 v22, 16, v74
	v_and_b32_e32 v75, 0xffff0000, v75
	v_and_b32_e32 v74, 0xffff0000, v74
	v_pk_mul_f32 v[24:25], v[74:75], v[74:75]
	s_nop 0
	v_pk_fma_f32 v[24:25], v[22:23], v[22:23], v[24:25]
	s_nop 0
	v_add_f32_e32 v0, v24, v0
	v_add_f32_e32 v0, v25, v0
	ds_bpermute_b32 v24, v12, v0
	s_waitcnt lgkmcnt(0)
; __device__ __forceinline__ float shx(float v, int mask, int lane) { return __int_as_float(__builtin_amdgcn_ds_bpermute((lane ^ mask) << 2, __float_as_int(v))); }
; __device__ __forceinline__ u32x4 pk8(f32x4 a, f32x4 b) { const u32x2 x = pk4(a), y = pk4(b); return (u32x4){x.x, x.y, y.x, y.y}; }
; #define UNPK(w) (f32x4){__uint_as_float((w).x << 16), __uint_as_float((w).x & 0xffff0000u), __uint_as_float((w).y << 16), __uint_as_float((w).y & 0xffff0000u)}
; #define UNPK(w) (f32x4){__uint_as_float((w).x << 16), __uint_as_float((w).x & 0xffff0000u), __uint_as_float((w).y << 16), __uint_as_float((w).y & 0xffff0000u)}
; __device__ __forceinline__ float wave_sum(float v, int lane) {
; #pragma unroll
;     for (int o = 1; o < 64; o <<= 1) v += shx(v, o, lane);
;     return v;
; __global__ void __launch_bounds__(NTHR, 2) fwd(Args args) {
;     ...
;                     for (int hh = 0; hh < 8; ++hh) { const size_t o = (size_t)row * 4096 + hh * 512 + lane * 8; const u32x4 ow = __builtin_nontemporal_load((const u32x4*)(O2 + o)), gw4 = __builtin_nontemporal_load((const u32x4*)(SG + o));
;                         const f32x4 v0 = UNPK(((u32x2){ow.x, ow.y})), v1 = UNPK(((u32x2){ow.z, ow.w}));
;                         const float ss = wave_sum((v0[0] * v0[0] + v0[1] * v0[1]) + (v0[2] * v0[2] + v0[3] * v0[3]) + (v1[0] * v1[0] + v1[1] * v1[1]) + (v1[2] * v1[2] + v1[3] * v1[3]), lane);
;                         const float rs = 1.f / sqrtf(ss * (1.f / 512.f) + LN_EPS);
;                         const f32x4 ga = UNPK(((u32x2){gw4.x, gw4.y})), gb2 = UNPK(((u32x2){gw4.z, gw4.w}));
;                         *(u32x4*)(RO + o) = pk8(v0 * rs * ga, v1 * rs * gb2); }
	v_add_f32_e32 v0, v0, v24
	ds_bpermute_b32 v24, v13, v0
	s_waitcnt lgkmcnt(0)
	v_add_f32_e32 v0, v0, v24
	ds_bpermute_b32 v24, v14, v0
	s_waitcnt lgkmcnt(0)
	v_add_f32_e32 v0, v0, v24
	ds_bpermute_b32 v24, v15, v0
	s_waitcnt lgkmcnt(0)
	v_add_f32_e32 v0, v0, v24
	v_mov_b32_e32 v24, v0
	s_nop 1
	v_permlane16_swap_b32_e32 v24, v0
	v_add_f32_e32 v0, v0, v24
	v_mov_b32_e32 v24, v0
	s_nop 1
	v_permlane32_swap_b32_e32 v24, v0
	v_add_f32_e32 v0, v0, v24
	v_fmamk_f32 v0, v0, 0x3b000000, v244
	v_cmp_gt_f32_e32 vcc, s83, v0
	v_mul_f32_e32 v24, 0x4f800000, v0
	s_nop 0
	v_cndmask_b32_e32 v0, v0, v24, vcc
	v_sqrt_f32_e32 v24, v0
	s_nop 0
	v_add_u32_e32 v25, -1, v24
	v_fma_f32 v26, -v25, v24, v0
	v_cmp_ge_f32_e64 s[2:3], 0, v26
	v_add_u32_e32 v26, 1, v24
	s_nop 0
	v_cndmask_b32_e64 v25, v24, v25, s[2:3]
	v_fma_f32 v24, -v26, v24, v0
	v_cmp_lt_f32_e64 s[2:3], 0, v24
	s_nop 1
	v_cndmask_b32_e64 v24, v25, v26, s[2:3]
	v_mul_f32_e32 v25, 0x37800000, v24
	v_cndmask_b32_e32 v24, v24, v25, vcc
	v_cmp_class_f32_e32 vcc, v0, v245
	s_nop 1
	v_cndmask_b32_e32 v0, v24, v0, vcc
	v_div_scale_f32 v24, s[2:3], v0, v0, 1.0
	v_rcp_f32_e32 v25, v24
	s_nop 0
	v_fma_f32 v26, -v24, v25, 1.0
	v_fmac_f32_e32 v25, v26, v25
	v_div_scale_f32 v26, vcc, 1.0, v0, 1.0
	v_mul_f32_e32 v27, v26, v25
	v_fma_f32 v28, -v24, v27, v26
	v_fmac_f32_e32 v27, v28, v25
	v_fma_f32 v24, -v24, v27, v26
	v_div_fmas_f32 v24, v24, v25, v27
	v_div_fixup_f32 v0, v24, v0, 1.0
	v_lshlrev_b32_e32 v24, 16, v76
	v_and_b32_e32 v25, 0xffff0000, v76
	v_lshlrev_b32_e32 v76, 16, v77
	v_and_b32_e32 v77, 0xffff0000, v77
	v_pk_mul_f32 v[72:73], v[72:73], v[0:1] op_sel_hi:[1,0]
	v_lshlrev_b32_e32 v26, 16, v78
	v_pk_mul_f32 v[76:77], v[72:73], v[76:77]
	v_mov_b32_e32 v72, v22
	v_mov_b32_e32 v73, v74
	v_mov_b32_e32 v74, v23
	v_and_b32_e32 v27, 0xffff0000, v78
	v_lshlrev_b32_e32 v78, 16, v79
	v_and_b32_e32 v79, 0xffff0000, v79
	v_pk_mul_f32 v[72:73], v[0:1], v[72:73] op_sel_hi:[0,1]
	v_pk_mul_f32 v[74:75], v[0:1], v[74:75] op_sel_hi:[0,1]
	v_pk_mul_f32 v[2:3], v[2:3], v[0:1] op_sel_hi:[1,0]
	v_pk_mul_f32 v[78:79], v[74:75], v[78:79]
	v_pk_mul_f32 v[74:75], v[72:73], v[26:27]
	v_pk_mul_f32 v[2:3], v[2:3], v[24:25]
	s_nop 0
	v_cvt_pk_bf16_f32 v72, v2, v3
	v_cvt_pk_bf16_f32 v73, v76, v77
	v_cvt_pk_bf16_f32 v74, v74, v75
	v_cvt_pk_bf16_f32 v75, v78, v79
	s_waitcnt vmcnt(2)
	v_lshlrev_b32_e32 v2, 16, v80
	v_and_b32_e32 v3, 0xffff0000, v80
	v_lshlrev_b32_e32 v80, 16, v81
	v_and_b32_e32 v81, 0xffff0000, v81
	v_mul_f32_e32 v0, v3, v3
	v_mul_f32_e32 v22, v81, v81
	v_fmac_f32_e32 v0, v2, v2
	v_fmac_f32_e32 v22, v80, v80
	v_add_f32_e32 v0, v0, v22
	v_lshlrev_b32_e32 v23, 16, v83
	v_lshlrev_b32_e32 v22, 16, v82
	v_and_b32_e32 v83, 0xffff0000, v83
	v_and_b32_e32 v82, 0xffff0000, v82
	v_pk_mul_f32 v[24:25], v[82:83], v[82:83]
	s_nop 0
	v_pk_fma_f32 v[24:25], v[22:23], v[22:23], v[24:25]
	s_nop 0
	v_add_f32_e32 v0, v24, v0
	v_add_f32_e32 v0, v25, v0
	ds_bpermute_b32 v24, v12, v0
	s_waitcnt lgkmcnt(0)
	v_add_f32_e32 v0, v0, v24
	ds_bpermute_b32 v24, v13, v0
	s_waitcnt lgkmcnt(0)
	v_add_f32_e32 v0, v0, v24
	ds_bpermute_b32 v24, v14, v0
	s_waitcnt lgkmcnt(0)
	v_add_f32_e32 v0, v0, v24
	ds_bpermute_b32 v24, v15, v0
	s_waitcnt lgkmcnt(0)
	v_add_f32_e32 v0, v0, v24
	v_mov_b32_e32 v24, v0
	s_nop 1
	v_permlane16_swap_b32_e32 v24, v0
	v_add_f32_e32 v0, v0, v24
	v_mov_b32_e32 v24, v0
	s_nop 1
	v_permlane32_swap_b32_e32 v24, v0
	v_add_f32_e32 v0, v0, v24
	v_fmamk_f32 v0, v0, 0x3b000000, v244
	v_cmp_gt_f32_e32 vcc, s83, v0
	v_mul_f32_e32 v24, 0x4f800000, v0
	s_nop 0
	v_cndmask_b32_e32 v0, v0, v24, vcc
	v_sqrt_f32_e32 v24, v0
	s_nop 0
	v_add_u32_e32 v25, -1, v24
	v_fma_f32 v26, -v25, v24, v0
	v_cmp_ge_f32_e64 s[2:3], 0, v26
	v_add_u32_e32 v26, 1, v24
	s_nop 0
	v_cndmask_b32_e64 v25, v24, v25, s[2:3]
	v_fma_f32 v24, -v26, v24, v0
	v_cmp_lt_f32_e64 s[2:3], 0, v24
	s_nop 1
	v_cndmask_b32_e64 v24, v25, v26, s[2:3]
	v_mul_f32_e32 v25, 0x37800000, v24
	v_cndmask_b32_e32 v24, v24, v25, vcc
	v_cmp_class_f32_e32 vcc, v0, v245
	s_nop 1
	v_cndmask_b32_e32 v0, v24, v0, vcc
	v_div_scale_f32 v24, s[2:3], v0, v0, 1.0
	v_rcp_f32_e32 v25, v24
	s_nop 0
	v_fma_f32 v26, -v24, v25, 1.0
	v_fmac_f32_e32 v25, v26, v25
	v_div_scale_f32 v26, vcc, 1.0, v0, 1.0
	v_mul_f32_e32 v27, v26, v25
	v_fma_f32 v28, -v24, v27, v26
	v_fmac_f32_e32 v27, v28, v25
	v_fma_f32 v24, -v24, v27, v26
	v_div_fmas_f32 v24, v24, v25, v27
	v_div_fixup_f32 v0, v24, v0, 1.0
	v_lshlrev_b32_e32 v24, 16, v84
	v_and_b32_e32 v25, 0xffff0000, v84
	v_lshlrev_b32_e32 v84, 16, v85
	v_and_b32_e32 v85, 0xffff0000, v85
	v_pk_mul_f32 v[80:81], v[80:81], v[0:1] op_sel_hi:[1,0]
	v_lshlrev_b32_e32 v26, 16, v86
	v_pk_mul_f32 v[84:85], v[80:81], v[84:85]
	v_mov_b32_e32 v80, v22
	v_mov_b32_e32 v81, v82
	v_mov_b32_e32 v82, v23
	v_and_b32_e32 v27, 0xffff0000, v86
	v_lshlrev_b32_e32 v86, 16, v87
	v_and_b32_e32 v87, 0xffff0000, v87
	v_pk_mul_f32 v[80:81], v[0:1], v[80:81] op_sel_hi:[0,1]
	v_pk_mul_f32 v[82:83], v[0:1], v[82:83] op_sel_hi:[0,1]
	v_pk_mul_f32 v[2:3], v[2:3], v[0:1] op_sel_hi:[1,0]
	v_pk_mul_f32 v[86:87], v[82:83], v[86:87]
	v_pk_mul_f32 v[82:83], v[80:81], v[26:27]
	v_pk_mul_f32 v[2:3], v[2:3], v[24:25]
	s_nop 0
	v_cvt_pk_bf16_f32 v80, v2, v3
	v_cvt_pk_bf16_f32 v81, v84, v85
	v_cvt_pk_bf16_f32 v82, v82, v83
	v_cvt_pk_bf16_f32 v83, v86, v87
	s_waitcnt vmcnt(0)
; __device__ __forceinline__ float shx(float v, int mask, int lane) { return __int_as_float(__builtin_amdgcn_ds_bpermute((lane ^ mask) << 2, __float_as_int(v))); }
; __device__ __forceinline__ u32x4 pk8(f32x4 a, f32x4 b) { const u32x2 x = pk4(a), y = pk4(b); return (u32x4){x.x, x.y, y.x, y.y}; }
; #define UNPK(w) (f32x4){__uint_as_float((w).x << 16), __uint_as_float((w).x & 0xffff0000u), __uint_as_float((w).y << 16), __uint_as_float((w).y & 0xffff0000u)}
; #define UNPK(w) (f32x4){__uint_as_float((w).x << 16), __uint_as_float((w).x & 0xffff0000u), __uint_as_float((w).y << 16), __uint_as_float((w).y & 0xffff0000u)}
; __device__ __forceinline__ float wave_sum(float v, int lane) {
; #pragma unroll
;     for (int o = 1; o < 64; o <<= 1) v += shx(v, o, lane);
;     return v;
; __global__ void __launch_bounds__(NTHR, 2) fwd(Args args) {
;     ...
;                     for (int hh = 0; hh < 8; ++hh) { const size_t o = (size_t)row * 4096 + hh * 512 + lane * 8; const u32x4 ow = __builtin_nontemporal_load((const u32x4*)(O2 + o)), gw4 = __builtin_nontemporal_load((const u32x4*)(SG + o));
;                         const f32x4 v0 = UNPK(((u32x2){ow.x, ow.y})), v1 = UNPK(((u32x2){ow.z, ow.w}));
;                         const float ss = wave_sum((v0[0] * v0[0] + v0[1] * v0[1]) + (v0[2] * v0[2] + v0[3] * v0[3]) + (v1[0] * v1[0] + v1[1] * v1[1]) + (v1[2] * v1[2] + v1[3] * v1[3]), lane);
;                         const float rs = 1.f / sqrtf(ss * (1.f / 512.f) + LN_EPS);
;                         const f32x4 ga = UNPK(((u32x2){gw4.x, gw4.y})), gb2 = UNPK(((u32x2){gw4.z, gw4.w}));
;                         *(u32x4*)(RO + o) = pk8(v0 * rs * ga, v1 * rs * gb2); }
;                 }
	v_lshlrev_b32_e32 v2, 16, v88
	v_and_b32_e32 v3, 0xffff0000, v88
	v_lshlrev_b32_e32 v88, 16, v89
	v_and_b32_e32 v89, 0xffff0000, v89
	v_mul_f32_e32 v0, v3, v3
	v_mul_f32_e32 v22, v89, v89
	v_fmac_f32_e32 v0, v2, v2
	v_fmac_f32_e32 v22, v88, v88
	v_add_f32_e32 v0, v0, v22
	v_lshlrev_b32_e32 v23, 16, v91
	v_lshlrev_b32_e32 v22, 16, v90
	v_and_b32_e32 v91, 0xffff0000, v91
	v_and_b32_e32 v90, 0xffff0000, v90
	v_pk_mul_f32 v[24:25], v[90:91], v[90:91]
	s_nop 0
	v_pk_fma_f32 v[24:25], v[22:23], v[22:23], v[24:25]
	s_nop 0
	v_add_f32_e32 v0, v24, v0
	v_add_f32_e32 v0, v25, v0
	ds_bpermute_b32 v24, v12, v0
	s_waitcnt lgkmcnt(0)
	v_add_f32_e32 v0, v0, v24
	ds_bpermute_b32 v24, v13, v0
	s_waitcnt lgkmcnt(0)
	v_add_f32_e32 v0, v0, v24
	ds_bpermute_b32 v24, v14, v0
	s_waitcnt lgkmcnt(0)
	v_add_f32_e32 v0, v0, v24
	ds_bpermute_b32 v24, v15, v0
	s_waitcnt lgkmcnt(0)
	v_add_f32_e32 v0, v0, v24
	v_mov_b32_e32 v24, v0
	s_nop 1
	v_permlane16_swap_b32_e32 v24, v0
	v_add_f32_e32 v0, v0, v24
	v_mov_b32_e32 v24, v0
	s_nop 1
	v_permlane32_swap_b32_e32 v24, v0
	v_add_f32_e32 v0, v0, v24
	v_fmamk_f32 v0, v0, 0x3b000000, v244
	v_cmp_gt_f32_e32 vcc, s83, v0
	v_mul_f32_e32 v24, 0x4f800000, v0
	s_nop 0
	v_cndmask_b32_e32 v0, v0, v24, vcc
	v_sqrt_f32_e32 v24, v0
	s_nop 0
	v_add_u32_e32 v25, -1, v24
	v_fma_f32 v26, -v25, v24, v0
	v_cmp_ge_f32_e64 s[2:3], 0, v26
	v_add_u32_e32 v26, 1, v24
	s_nop 0
	v_cndmask_b32_e64 v25, v24, v25, s[2:3]
	v_fma_f32 v24, -v26, v24, v0
	v_cmp_lt_f32_e64 s[2:3], 0, v24
	s_nop 1
	v_cndmask_b32_e64 v24, v25, v26, s[2:3]
	v_mul_f32_e32 v25, 0x37800000, v24
	v_cndmask_b32_e32 v24, v24, v25, vcc
	v_cmp_class_f32_e32 vcc, v0, v245
	s_nop 1
	v_cndmask_b32_e32 v0, v24, v0, vcc
	v_div_scale_f32 v24, s[2:3], v0, v0, 1.0
	v_rcp_f32_e32 v25, v24
	s_nop 0
	v_fma_f32 v26, -v24, v25, 1.0
	v_fmac_f32_e32 v25, v26, v25
	v_div_scale_f32 v26, vcc, 1.0, v0, 1.0
	v_mul_f32_e32 v27, v26, v25
	v_fma_f32 v28, -v24, v27, v26
	v_fmac_f32_e32 v27, v28, v25
	v_fma_f32 v24, -v24, v27, v26
	v_div_fmas_f32 v24, v24, v25, v27
	v_div_fixup_f32 v0, v24, v0, 1.0
	v_lshlrev_b32_e32 v24, 16, v92
	v_and_b32_e32 v25, 0xffff0000, v92
	v_lshlrev_b32_e32 v92, 16, v93
	v_and_b32_e32 v93, 0xffff0000, v93
	v_pk_mul_f32 v[88:89], v[88:89], v[0:1] op_sel_hi:[1,0]
	v_lshlrev_b32_e32 v26, 16, v94
	v_pk_mul_f32 v[92:93], v[88:89], v[92:93]
	v_mov_b32_e32 v88, v22
	v_mov_b32_e32 v89, v90
	v_mov_b32_e32 v90, v23
	v_and_b32_e32 v27, 0xffff0000, v94
	v_lshlrev_b32_e32 v94, 16, v95
	v_and_b32_e32 v95, 0xffff0000, v95
	v_pk_mul_f32 v[88:89], v[0:1], v[88:89] op_sel_hi:[0,1]
	v_pk_mul_f32 v[90:91], v[0:1], v[90:91] op_sel_hi:[0,1]
	v_pk_mul_f32 v[2:3], v[2:3], v[0:1] op_sel_hi:[1,0]
	v_pk_mul_f32 v[94:95], v[90:91], v[94:95]
	v_pk_mul_f32 v[90:91], v[88:89], v[26:27]
	v_pk_mul_f32 v[2:3], v[2:3], v[24:25]
	s_nop 0
	v_cvt_pk_bf16_f32 v88, v2, v3
	v_cvt_pk_bf16_f32 v89, v92, v93
	v_cvt_pk_bf16_f32 v90, v90, v91
	v_cvt_pk_bf16_f32 v91, v94, v95
	global_store_dwordx4 v[6:7], v[32:35], off
	global_store_dwordx4 v[6:7], v[40:43], off offset:1024
	global_store_dwordx4 v[6:7], v[48:51], off offset:2048
	global_store_dwordx4 v[6:7], v[56:59], off offset:3072
	global_store_dwordx4 v[164:165], v[64:67], off
	global_store_dwordx4 v[164:165], v[72:75], off offset:1024
	global_store_dwordx4 v[164:165], v[80:83], off offset:2048
	global_store_dwordx4 v[164:165], v[88:91], off offset:3072
	v_lshl_add_u64 v[6:7], v[6:7], 0, s[6:7]
	s_add_i32 s10, s10, s4
	s_cmpk_lt_i32 s10, 0x2400
	s_cbranch_scc1 .LBB0_769

; __device__ __forceinline__ float shx(float v, int mask, int lane) { return __int_as_float(__builtin_amdgcn_ds_bpermute((lane ^ mask) << 2, __float_as_int(v))); }
; __device__ __forceinline__ void attn_dif_unit(LAS unsigned char* lds, const int tid, const int wave_s, const bf16_t* q, const bf16_t* k0, const bf16_t* k1, const bf16_t* vt0, const bf16_t* vt1, ...
;     ...
;     const float inv0 = 1.f / (l_run[0] + shx(l_run[0], 32, lane)), inv1 = lamf / (l_run[1] + shx(l_run[1], 32, lane));
;     float ss = 0.f;
; #pragma unroll
;     for (int i = 0; i < 4; ++i)
; #pragma unroll
;         for (int r = 0; r < 16; ++r) { const float v = oacc[0][i][r] * inv0 - oacc[1][i][r] * inv1; oacc[0][i][r] = v; ss += v * v; }
.LBB0_980:
	ds_bpermute_b32 v0, v203, v219
	s_lshl_b64 s[2:3], s[2:3], 1
	s_add_u32 s2, s33, s2
	s_addc_u32 s3, s36, s3
	s_lshl_b32 s6, s42, 1
	s_add_u32 s6, s2, s6
	s_waitcnt lgkmcnt(0)
	v_add_f32_e32 v0, v219, v0
	s_addc_u32 s7, s3, 0
	v_div_scale_f32 v2, s[2:3], v0, v0, 1.0
	v_rcp_f32_e32 v3, v2
	s_mov_b32 s10, 0x3f24fd5c
	s_add_i32 s17, s17, s16
	s_cmpk_lt_i32 s17, 0x240
	v_fma_f32 v4, -v2, v3, 1.0
	v_fmac_f32_e32 v3, v4, v3
	v_div_scale_f32 v4, vcc, 1.0, v0, 1.0
	v_mul_f32_e32 v5, v4, v3
	v_fma_f32 v6, -v2, v5, v4
	v_fmac_f32_e32 v5, v6, v3
	v_fma_f32 v2, -v2, v5, v4
	v_div_fmas_f32 v2, v2, v3, v5
	v_div_fixup_f32 v0, v2, v0, 1.0
	ds_bpermute_b32 v2, v203, v216
	s_waitcnt lgkmcnt(0)
	v_add_f32_e32 v2, v216, v2
	v_div_scale_f32 v3, s[2:3], v2, v2, v253
	v_rcp_f32_e32 v4, v3
	s_nop 0
	v_fma_f32 v5, -v3, v4, 1.0
	v_fmac_f32_e32 v4, v5, v4
	v_div_scale_f32 v5, vcc, v253, v2, v253
	v_mul_f32_e32 v6, v5, v4
	v_fma_f32 v7, -v3, v6, v5
	v_fmac_f32_e32 v6, v7, v4
	v_fma_f32 v3, -v3, v6, v5
	v_div_fmas_f32 v3, v3, v4, v6
	v_div_fixup_f32 v2, v3, v2, v253
	v_pk_mul_f32 v[6:7], v[114:115], v[2:3] op_sel_hi:[1,0]
	v_pk_mul_f32 v[4:5], v[112:113], v[2:3] op_sel_hi:[1,0]
	v_pk_fma_f32 v[146:147], v[130:131], v[0:1], v[6:7] op_sel_hi:[1,0,1] neg_lo:[0,0,1] neg_hi:[0,0,1]
	v_pk_mul_f32 v[6:7], v[116:117], v[2:3] op_sel_hi:[1,0]
	v_pk_fma_f32 v[144:145], v[128:129], v[0:1], v[4:5] op_sel_hi:[1,0,1] neg_lo:[0,0,1] neg_hi:[0,0,1]
	v_pk_fma_f32 v[128:129], v[132:133], v[0:1], v[6:7] op_sel_hi:[1,0,1] neg_lo:[0,0,1] neg_hi:[0,0,1]
	v_pk_mul_f32 v[6:7], v[118:119], v[2:3] op_sel_hi:[1,0]
	v_pk_mul_f32 v[4:5], v[144:145], v[144:145]
	v_pk_fma_f32 v[130:131], v[134:135], v[0:1], v[6:7] op_sel_hi:[1,0,1] neg_lo:[0,0,1] neg_hi:[0,0,1]
	v_pk_mul_f32 v[6:7], v[120:121], v[2:3] op_sel_hi:[1,0]
	v_pk_mul_f32 v[148:149], v[146:147], v[146:147]
	v_pk_fma_f32 v[118:119], v[136:137], v[0:1], v[6:7] op_sel_hi:[1,0,1] neg_lo:[0,0,1] neg_hi:[0,0,1]
	v_pk_mul_f32 v[6:7], v[122:123], v[2:3] op_sel_hi:[1,0]
	v_pk_mul_f32 v[132:133], v[128:129], v[128:129]
	v_pk_fma_f32 v[122:123], v[138:139], v[0:1], v[6:7] op_sel_hi:[1,0,1] neg_lo:[0,0,1] neg_hi:[0,0,1]
	v_pk_mul_f32 v[6:7], v[124:125], v[2:3] op_sel_hi:[1,0]
	v_pk_mul_f32 v[134:135], v[130:131], v[130:131]
	v_pk_fma_f32 v[114:115], v[140:141], v[0:1], v[6:7] op_sel_hi:[1,0,1] neg_lo:[0,0,1] neg_hi:[0,0,1]
	v_pk_mul_f32 v[6:7], v[126:127], v[2:3] op_sel_hi:[1,0]
	v_pk_mul_f32 v[136:137], v[118:119], v[118:119]
	v_pk_fma_f32 v[120:121], v[142:143], v[0:1], v[6:7] op_sel_hi:[1,0,1] neg_lo:[0,0,1] neg_hi:[0,0,1]
	v_pk_mul_f32 v[6:7], v[80:81], v[2:3] op_sel_hi:[1,0]
	v_pk_mul_f32 v[138:139], v[122:123], v[122:123]
	v_pk_fma_f32 v[112:113], v[96:97], v[0:1], v[6:7] op_sel_hi:[1,0,1] neg_lo:[0,0,1] neg_hi:[0,0,1]
	v_pk_mul_f32 v[6:7], v[82:83], v[2:3] op_sel_hi:[1,0]
	v_pk_mul_f32 v[124:125], v[114:115], v[114:115]
	v_pk_fma_f32 v[116:117], v[98:99], v[0:1], v[6:7] op_sel_hi:[1,0,1] neg_lo:[0,0,1] neg_hi:[0,0,1]
	v_pk_mul_f32 v[6:7], v[84:85], v[2:3] op_sel_hi:[1,0]
	v_pk_mul_f32 v[126:127], v[120:121], v[120:121]
	v_pk_fma_f32 v[96:97], v[100:101], v[0:1], v[6:7] op_sel_hi:[1,0,1] neg_lo:[0,0,1] neg_hi:[0,0,1]
	v_pk_mul_f32 v[6:7], v[86:87], v[2:3] op_sel_hi:[1,0]
	v_pk_mul_f32 v[140:141], v[112:113], v[112:113]
	v_pk_fma_f32 v[98:99], v[102:103], v[0:1], v[6:7] op_sel_hi:[1,0,1] neg_lo:[0,0,1] neg_hi:[0,0,1]
	v_pk_mul_f32 v[6:7], v[88:89], v[2:3] op_sel_hi:[1,0]
	v_pk_mul_f32 v[142:143], v[116:117], v[116:117]
	v_pk_fma_f32 v[84:85], v[104:105], v[0:1], v[6:7] op_sel_hi:[1,0,1] neg_lo:[0,0,1] neg_hi:[0,0,1]
	v_pk_mul_f32 v[6:7], v[90:91], v[2:3] op_sel_hi:[1,0]
	v_pk_mul_f32 v[100:101], v[96:97], v[96:97]
	v_pk_fma_f32 v[88:89], v[106:107], v[0:1], v[6:7] op_sel_hi:[1,0,1] neg_lo:[0,0,1] neg_hi:[0,0,1]
	v_pk_mul_f32 v[6:7], v[92:93], v[2:3] op_sel_hi:[1,0]
	v_pk_mul_f32 v[102:103], v[98:99], v[98:99]
	v_pk_fma_f32 v[80:81], v[108:109], v[0:1], v[6:7] op_sel_hi:[1,0,1] neg_lo:[0,0,1] neg_hi:[0,0,1]
	v_pk_mul_f32 v[6:7], v[94:95], v[2:3] op_sel_hi:[1,0]
	v_pk_mul_f32 v[104:105], v[84:85], v[84:85]
	v_pk_fma_f32 v[86:87], v[110:111], v[0:1], v[6:7] op_sel_hi:[1,0,1] neg_lo:[0,0,1] neg_hi:[0,0,1]
	v_pk_mul_f32 v[6:7], v[48:49], v[2:3] op_sel_hi:[1,0]
	v_pk_mul_f32 v[90:91], v[88:89], v[88:89]
	v_pk_fma_f32 v[64:65], v[64:65], v[0:1], v[6:7] op_sel_hi:[1,0,1] neg_lo:[0,0,1] neg_hi:[0,0,1]
	v_pk_mul_f32 v[6:7], v[50:51], v[2:3] op_sel_hi:[1,0]
	v_pk_mul_f32 v[92:93], v[80:81], v[80:81]
	v_pk_fma_f32 v[82:83], v[66:67], v[0:1], v[6:7] op_sel_hi:[1,0,1] neg_lo:[0,0,1] neg_hi:[0,0,1]
	v_pk_mul_f32 v[6:7], v[52:53], v[2:3] op_sel_hi:[1,0]
	v_pk_mul_f32 v[94:95], v[86:87], v[86:87]
	v_pk_fma_f32 v[52:53], v[68:69], v[0:1], v[6:7] op_sel_hi:[1,0,1] neg_lo:[0,0,1] neg_hi:[0,0,1]
	v_pk_mul_f32 v[6:7], v[54:55], v[2:3] op_sel_hi:[1,0]
	v_pk_mul_f32 v[106:107], v[64:65], v[64:65]
	v_pk_fma_f32 v[66:67], v[70:71], v[0:1], v[6:7] op_sel_hi:[1,0,1] neg_lo:[0,0,1] neg_hi:[0,0,1]
	v_pk_mul_f32 v[6:7], v[56:57], v[2:3] op_sel_hi:[1,0]
	v_pk_mul_f32 v[108:109], v[82:83], v[82:83]
	v_pk_fma_f32 v[50:51], v[72:73], v[0:1], v[6:7] op_sel_hi:[1,0,1] neg_lo:[0,0,1] neg_hi:[0,0,1]
	v_pk_mul_f32 v[6:7], v[58:59], v[2:3] op_sel_hi:[1,0]
	v_pk_mul_f32 v[68:69], v[52:53], v[52:53]
	v_pk_fma_f32 v[56:57], v[74:75], v[0:1], v[6:7] op_sel_hi:[1,0,1] neg_lo:[0,0,1] neg_hi:[0,0,1]
	v_pk_mul_f32 v[6:7], v[60:61], v[2:3] op_sel_hi:[1,0]
	v_pk_mul_f32 v[70:71], v[66:67], v[66:67]
	v_pk_fma_f32 v[48:49], v[76:77], v[0:1], v[6:7] op_sel_hi:[1,0,1] neg_lo:[0,0,1] neg_hi:[0,0,1]
	v_pk_mul_f32 v[6:7], v[62:63], v[2:3] op_sel_hi:[1,0]
	v_pk_mul_f32 v[72:73], v[50:51], v[50:51]
; __device__ __forceinline__ u32x2 pk4(f32x4 v) { u32x2 w; w.x = cvt_pk_bf16(v[0], v[1]); w.y = cvt_pk_bf16(v[2], v[3]); return w; }
; __device__ __forceinline__ float shx(float v, int mask, int lane) { return __int_as_float(__builtin_amdgcn_ds_bpermute((lane ^ mask) << 2, __float_as_int(v))); }
; __device__ __forceinline__ void attn_dif_unit(LAS unsigned char* lds, const int tid, const int wave_s, const bf16_t* q, const bf16_t* k0, const bf16_t* k1, const bf16_t* vt0, const bf16_t* vt1, ...
;     ...
;         for (int r = 0; r < 16; ++r) { const float v = oacc[0][i][r] * inv0 - oacc[1][i][r] * inv1; oacc[0][i][r] = v; ss += v * v; }
;     ss += shx(ss, 32, lane);
;     const float rs = subscale / sqrtf(ss * (1.f / 128.f) + LN_EPS);
;     int c32b = c32, hib = hi, wb = w; asm volatile("" : "+v"(c32b), "+v"(hib), "+v"(wb));
;     const unsigned ob = (unsigned)((32 * wb + c32b) * D + 4 * hib) * 2u; const float* subp = sub + 4 * hib;
; #pragma unroll
;     for (int i = 0; i < 4; ++i)
; #pragma unroll
;         for (int g = 0; g < 4; ++g) { const int col = 32 * i + 8 * g; const f32x4 sb = *(const f32x4*)(subp + col);
;             const f32x4 v = (f32x4){oacc[0][i][4 * g], oacc[0][i][4 * g + 1], oacc[0][i][4 * g + 2], oacc[0][i][4 * g + 3]} * rs * sb; *(u32x2*)((char*)o + ob + col * 2) = pk4(v); }
	v_pk_fma_f32 v[54:55], v[78:79], v[0:1], v[6:7] op_sel_hi:[1,0,1] neg_lo:[0,0,1] neg_hi:[0,0,1]
	v_pk_mul_f32 v[6:7], v[16:17], v[2:3] op_sel_hi:[1,0]
	v_pk_mul_f32 v[58:59], v[56:57], v[56:57]
	v_pk_fma_f32 v[12:13], v[32:33], v[0:1], v[6:7] op_sel_hi:[1,0,1] neg_lo:[0,0,1] neg_hi:[0,0,1]
	v_pk_mul_f32 v[6:7], v[18:19], v[2:3] op_sel_hi:[1,0]
	v_pk_mul_f32 v[60:61], v[48:49], v[48:49]
	v_pk_fma_f32 v[32:33], v[34:35], v[0:1], v[6:7] op_sel_hi:[1,0,1] neg_lo:[0,0,1] neg_hi:[0,0,1]
	v_pk_mul_f32 v[6:7], v[20:21], v[2:3] op_sel_hi:[1,0]
	v_pk_mul_f32 v[62:63], v[54:55], v[54:55]
	v_pk_fma_f32 v[10:11], v[36:37], v[0:1], v[6:7] op_sel_hi:[1,0,1] neg_lo:[0,0,1] neg_hi:[0,0,1]
	v_pk_mul_f32 v[6:7], v[22:23], v[2:3] op_sel_hi:[1,0]
	v_pk_mul_f32 v[74:75], v[12:13], v[12:13]
	v_pk_fma_f32 v[18:19], v[38:39], v[0:1], v[6:7] op_sel_hi:[1,0,1] neg_lo:[0,0,1] neg_hi:[0,0,1]
	v_pk_mul_f32 v[6:7], v[24:25], v[2:3] op_sel_hi:[1,0]
	v_pk_mul_f32 v[34:35], v[32:33], v[32:33]
	v_pk_fma_f32 v[8:9], v[40:41], v[0:1], v[6:7] op_sel_hi:[1,0,1] neg_lo:[0,0,1] neg_hi:[0,0,1]
	v_pk_mul_f32 v[6:7], v[26:27], v[2:3] op_sel_hi:[1,0]
	v_pk_mul_f32 v[20:21], v[10:11], v[10:11]
	v_pk_fma_f32 v[16:17], v[42:43], v[0:1], v[6:7] op_sel_hi:[1,0,1] neg_lo:[0,0,1] neg_hi:[0,0,1]
	v_pk_mul_f32 v[6:7], v[28:29], v[2:3] op_sel_hi:[1,0]
	v_pk_mul_f32 v[2:3], v[30:31], v[2:3] op_sel_hi:[1,0]
	v_pk_fma_f32 v[6:7], v[44:45], v[0:1], v[6:7] op_sel_hi:[1,0,1] neg_lo:[0,0,1] neg_hi:[0,0,1]
	v_pk_fma_f32 v[14:15], v[46:47], v[0:1], v[2:3] op_sel_hi:[1,0,1] neg_lo:[0,0,1] neg_hi:[0,0,1]
	v_add_f32_e32 v0, v4, v5
	v_add_f32_e32 v0, v148, v0
	v_add_f32_e32 v0, v149, v0
	v_add_f32_e32 v0, v132, v0
	v_add_f32_e32 v0, v133, v0
	v_add_f32_e32 v0, v134, v0
	v_add_f32_e32 v0, v135, v0
	v_add_f32_e32 v0, v136, v0
	v_add_f32_e32 v0, v137, v0
	v_add_f32_e32 v0, v138, v0
	v_add_f32_e32 v0, v139, v0
	v_add_f32_e32 v0, v124, v0
	v_add_f32_e32 v0, v125, v0
	v_add_f32_e32 v0, v126, v0
	v_add_f32_e32 v0, v127, v0
	v_add_f32_e32 v0, v140, v0
	v_add_f32_e32 v0, v141, v0
	v_add_f32_e32 v0, v142, v0
	v_add_f32_e32 v0, v143, v0
	v_add_f32_e32 v0, v100, v0
	v_add_f32_e32 v0, v101, v0
	v_add_f32_e32 v0, v102, v0
	v_add_f32_e32 v0, v103, v0
	v_add_f32_e32 v0, v104, v0
	v_add_f32_e32 v0, v105, v0
	v_add_f32_e32 v0, v90, v0
	v_add_f32_e32 v0, v91, v0
	v_add_f32_e32 v0, v92, v0
	v_add_f32_e32 v0, v93, v0
	v_add_f32_e32 v0, v94, v0
	v_add_f32_e32 v0, v95, v0
	v_add_f32_e32 v0, v106, v0
	v_add_f32_e32 v0, v107, v0
	v_add_f32_e32 v0, v108, v0
	v_add_f32_e32 v0, v109, v0
	v_add_f32_e32 v0, v68, v0
	v_add_f32_e32 v0, v69, v0
	v_add_f32_e32 v0, v70, v0
	v_add_f32_e32 v0, v71, v0
	v_add_f32_e32 v0, v72, v0
	v_add_f32_e32 v0, v73, v0
	v_add_f32_e32 v0, v58, v0
	v_add_f32_e32 v0, v59, v0
	v_add_f32_e32 v0, v60, v0
	v_add_f32_e32 v0, v61, v0
	v_add_f32_e32 v0, v62, v0
	v_add_f32_e32 v0, v63, v0
	v_add_f32_e32 v0, v74, v0
	v_add_f32_e32 v0, v75, v0
	v_add_f32_e32 v0, v34, v0
	v_add_f32_e32 v0, v35, v0
	v_add_f32_e32 v0, v20, v0
	v_pk_mul_f32 v[22:23], v[18:19], v[18:19]
	v_add_f32_e32 v0, v21, v0
	v_add_f32_e32 v0, v22, v0
	v_pk_mul_f32 v[24:25], v[8:9], v[8:9]
	v_add_f32_e32 v0, v23, v0
	v_add_f32_e32 v0, v24, v0
	v_pk_mul_f32 v[26:27], v[16:17], v[16:17]
	v_add_f32_e32 v0, v25, v0
	v_add_f32_e32 v0, v26, v0
	v_pk_mul_f32 v[28:29], v[6:7], v[6:7]
	v_add_f32_e32 v0, v27, v0
	v_add_f32_e32 v0, v28, v0
	v_pk_mul_f32 v[2:3], v[14:15], v[14:15]
	v_add_f32_e32 v0, v29, v0
	v_add_f32_e32 v0, v2, v0
	v_add_f32_e32 v0, v3, v0
	v_mov_b32_e32 v2, v0
	s_nop 1
	v_permlane32_swap_b32_e32 v2, v0
	v_add_f32_e32 v0, v0, v2
	v_fmamk_f32 v0, v0, 0x3c000000, v244
	v_cmp_gt_f32_e32 vcc, s83, v0
	v_mul_f32_e32 v2, 0x4f800000, v0
	s_nop 0
	v_cndmask_b32_e32 v0, v0, v2, vcc
	v_sqrt_f32_e32 v2, v0
	s_nop 0
	v_add_u32_e32 v3, -1, v2
	v_fma_f32 v4, -v3, v2, v0
	v_cmp_ge_f32_e64 s[2:3], 0, v4
	v_add_u32_e32 v4, 1, v2
	s_nop 0
	v_cndmask_b32_e64 v3, v2, v3, s[2:3]
	v_fma_f32 v2, -v4, v2, v0
	v_cmp_lt_f32_e64 s[2:3], 0, v2
	s_nop 1
	v_cndmask_b32_e64 v2, v3, v4, s[2:3]
	v_mul_f32_e32 v3, 0x37800000, v2
	v_cndmask_b32_e32 v2, v2, v3, vcc
	v_cmp_class_f32_e32 vcc, v0, v245
	s_nop 1
	v_cndmask_b32_e32 v0, v2, v0, vcc
	v_div_scale_f32 v2, s[2:3], v0, v0, s10
	v_rcp_f32_e32 v3, v2
	s_nop 0
	v_fma_f32 v4, -v2, v3, 1.0
	v_fmac_f32_e32 v3, v4, v3
	v_div_scale_f32 v4, vcc, s10, v0, s10
	v_mul_f32_e32 v5, v4, v3
	v_fma_f32 v20, -v2, v5, v4
	v_fmac_f32_e32 v5, v20, v3
	v_fma_f32 v2, -v2, v5, v4
	v_div_fmas_f32 v2, v2, v3, v5
	v_div_fixup_f32 v0, v2, v0, s10
	v_mov_b32_e32 v2, v254
	v_lshrrev_b32_e32 v3, 5, v202
	v_mov_b32_e32 v4, v208
	v_pk_mul_f32 v[24:25], v[144:145], v[0:1] op_sel_hi:[1,0]
	v_lshlrev_b32_e32 v4, 11, v4
	v_lshl_add_u32 v4, v2, 16, v4
	v_lshlrev_b32_e32 v2, 2, v3
	v_ashrrev_i32_e32 v3, 31, v2
	v_lshl_add_u64 v[20:21], v[2:3], 2, s[4:5]
	v_add_lshl_u32 v22, v4, v2, 1
	global_load_dwordx4 v[28:31], v[20:21], off
	global_load_dwordx4 v[36:39], v[20:21], off offset:32
	global_load_dwordx4 v[40:43], v[20:21], off offset:64
	global_load_dwordx4 v[44:47], v[20:21], off offset:96
	global_load_dwordx4 v[60:63], v[20:21], off offset:128
	global_load_dwordx4 v[68:71], v[20:21], off offset:160
	global_load_dwordx4 v[72:75], v[20:21], off offset:192
	global_load_dwordx4 v[76:79], v[20:21], off offset:224
	global_load_dwordx4 v[92:95], v[20:21], off offset:256
	global_load_dwordx4 v[100:103], v[20:21], off offset:288
	global_load_dwordx4 v[104:107], v[20:21], off offset:320
	global_load_dwordx4 v[108:111], v[20:21], off offset:352
	global_load_dwordx4 v[124:127], v[20:21], off offset:384
	global_load_dwordx4 v[132:135], v[20:21], off offset:416
	global_load_dwordx4 v[136:139], v[20:21], off offset:448
	global_load_dwordx4 v[140:143], v[20:21], off offset:480
	v_pk_mul_f32 v[26:27], v[146:147], v[0:1] op_sel_hi:[1,0]
	v_pk_mul_f32 v[12:13], v[12:13], v[0:1] op_sel_hi:[1,0]
	v_pk_mul_f32 v[10:11], v[10:11], v[0:1] op_sel_hi:[1,0]
	v_pk_mul_f32 v[8:9], v[8:9], v[0:1] op_sel_hi:[1,0]
	v_pk_mul_f32 v[6:7], v[6:7], v[0:1] op_sel_hi:[1,0]
	s_waitcnt vmcnt(0)
; __device__ __forceinline__ u32x2 pk4(f32x4 v) { u32x2 w; w.x = cvt_pk_bf16(v[0], v[1]); w.y = cvt_pk_bf16(v[2], v[3]); return w; }
; __device__ __forceinline__ void attn_dif_unit(LAS unsigned char* lds, const int tid, const int wave_s, const bf16_t* q, const bf16_t* k0, const bf16_t* k1, const bf16_t* vt0, const bf16_t* vt1, ...
;     ...
; #pragma unroll
;     for (int i = 0; i < 4; ++i)
; #pragma unroll
;         for (int g = 0; g < 4; ++g) { const int col = 32 * i + 8 * g; const f32x4 sb = *(const f32x4*)(subp + col);
;             const f32x4 v = (f32x4){oacc[0][i][4 * g], oacc[0][i][4 * g + 1], oacc[0][i][4 * g + 2], oacc[0][i][4 * g + 3]} * rs * sb; *(u32x2*)((char*)o + ob + col * 2) = pk4(v); }
;     asm volatile("s_waitcnt lgkmcnt(0)" ::: "memory"); __builtin_amdgcn_s_barrier(); asm volatile("" ::: "memory");
	v_pk_mul_f32 v[2:3], v[28:29], v[24:25]
	v_pk_mul_f32 v[4:5], v[30:31], v[26:27]
	v_cvt_pk_bf16_f32 v2, v2, v3
	v_pk_mul_f32 v[24:25], v[128:129], v[0:1] op_sel_hi:[1,0]
	v_cvt_pk_bf16_f32 v3, v4, v5
	global_store_dwordx2 v22, v[2:3], s[6:7]
	v_pk_mul_f32 v[26:27], v[130:131], v[0:1] op_sel_hi:[1,0]
	v_pk_mul_f32 v[2:3], v[36:37], v[24:25]
	v_pk_mul_f32 v[4:5], v[38:39], v[26:27]
	v_cvt_pk_bf16_f32 v2, v2, v3
	v_pk_mul_f32 v[24:25], v[118:119], v[0:1] op_sel_hi:[1,0]
	v_cvt_pk_bf16_f32 v3, v4, v5
	global_store_dwordx2 v22, v[2:3], s[6:7] offset:16
	v_pk_mul_f32 v[26:27], v[122:123], v[0:1] op_sel_hi:[1,0]
	v_pk_mul_f32 v[2:3], v[40:41], v[24:25]
	v_pk_mul_f32 v[4:5], v[42:43], v[26:27]
	v_cvt_pk_bf16_f32 v2, v2, v3
	v_pk_mul_f32 v[24:25], v[114:115], v[0:1] op_sel_hi:[1,0]
	v_cvt_pk_bf16_f32 v3, v4, v5
	global_store_dwordx2 v22, v[2:3], s[6:7] offset:32
	v_pk_mul_f32 v[26:27], v[120:121], v[0:1] op_sel_hi:[1,0]
	v_pk_mul_f32 v[2:3], v[44:45], v[24:25]
	v_pk_mul_f32 v[4:5], v[46:47], v[26:27]
	v_cvt_pk_bf16_f32 v2, v2, v3
	v_pk_mul_f32 v[24:25], v[112:113], v[0:1] op_sel_hi:[1,0]
	v_cvt_pk_bf16_f32 v3, v4, v5
	global_store_dwordx2 v22, v[2:3], s[6:7] offset:48
	v_pk_mul_f32 v[26:27], v[116:117], v[0:1] op_sel_hi:[1,0]
	v_pk_mul_f32 v[2:3], v[60:61], v[24:25]
	v_pk_mul_f32 v[4:5], v[62:63], v[26:27]
	v_cvt_pk_bf16_f32 v2, v2, v3
	v_pk_mul_f32 v[24:25], v[96:97], v[0:1] op_sel_hi:[1,0]
	v_cvt_pk_bf16_f32 v3, v4, v5
	global_store_dwordx2 v22, v[2:3], s[6:7] offset:64
	v_pk_mul_f32 v[26:27], v[98:99], v[0:1] op_sel_hi:[1,0]
	v_pk_mul_f32 v[2:3], v[68:69], v[24:25]
	v_pk_mul_f32 v[4:5], v[70:71], v[26:27]
	v_cvt_pk_bf16_f32 v2, v2, v3
	v_pk_mul_f32 v[24:25], v[84:85], v[0:1] op_sel_hi:[1,0]
	v_cvt_pk_bf16_f32 v3, v4, v5
	global_store_dwordx2 v22, v[2:3], s[6:7] offset:80
	v_pk_mul_f32 v[26:27], v[88:89], v[0:1] op_sel_hi:[1,0]
	v_pk_mul_f32 v[2:3], v[72:73], v[24:25]
	v_pk_mul_f32 v[4:5], v[74:75], v[26:27]
	v_cvt_pk_bf16_f32 v2, v2, v3
	v_pk_mul_f32 v[24:25], v[80:81], v[0:1] op_sel_hi:[1,0]
	v_cvt_pk_bf16_f32 v3, v4, v5
	global_store_dwordx2 v22, v[2:3], s[6:7] offset:96
	v_pk_mul_f32 v[26:27], v[86:87], v[0:1] op_sel_hi:[1,0]
	v_pk_mul_f32 v[2:3], v[76:77], v[24:25]
	v_pk_mul_f32 v[4:5], v[78:79], v[26:27]
	v_cvt_pk_bf16_f32 v2, v2, v3
	v_pk_mul_f32 v[24:25], v[64:65], v[0:1] op_sel_hi:[1,0]
	v_cvt_pk_bf16_f32 v3, v4, v5
	global_store_dwordx2 v22, v[2:3], s[6:7] offset:112
	v_pk_mul_f32 v[26:27], v[82:83], v[0:1] op_sel_hi:[1,0]
	v_pk_mul_f32 v[2:3], v[92:93], v[24:25]
	v_pk_mul_f32 v[4:5], v[94:95], v[26:27]
	v_cvt_pk_bf16_f32 v2, v2, v3
	v_pk_mul_f32 v[24:25], v[52:53], v[0:1] op_sel_hi:[1,0]
	v_cvt_pk_bf16_f32 v3, v4, v5
	global_store_dwordx2 v22, v[2:3], s[6:7] offset:128
	v_pk_mul_f32 v[26:27], v[66:67], v[0:1] op_sel_hi:[1,0]
	v_pk_mul_f32 v[2:3], v[100:101], v[24:25]
	v_pk_mul_f32 v[4:5], v[102:103], v[26:27]
	v_cvt_pk_bf16_f32 v2, v2, v3
	v_pk_mul_f32 v[24:25], v[50:51], v[0:1] op_sel_hi:[1,0]
	v_cvt_pk_bf16_f32 v3, v4, v5
	global_store_dwordx2 v22, v[2:3], s[6:7] offset:144
	v_pk_mul_f32 v[26:27], v[56:57], v[0:1] op_sel_hi:[1,0]
	v_pk_mul_f32 v[2:3], v[104:105], v[24:25]
	v_pk_mul_f32 v[4:5], v[106:107], v[26:27]
	v_cvt_pk_bf16_f32 v2, v2, v3
	v_pk_mul_f32 v[24:25], v[48:49], v[0:1] op_sel_hi:[1,0]
	v_cvt_pk_bf16_f32 v3, v4, v5
	global_store_dwordx2 v22, v[2:3], s[6:7] offset:160
	v_pk_mul_f32 v[26:27], v[54:55], v[0:1] op_sel_hi:[1,0]
	v_pk_mul_f32 v[2:3], v[108:109], v[24:25]
	v_pk_mul_f32 v[4:5], v[110:111], v[26:27]
	v_cvt_pk_bf16_f32 v2, v2, v3
	v_pk_mul_f32 v[24:25], v[32:33], v[0:1] op_sel_hi:[1,0]
	v_cvt_pk_bf16_f32 v3, v4, v5
	global_store_dwordx2 v22, v[2:3], s[6:7] offset:176
	v_pk_mul_f32 v[2:3], v[124:125], v[12:13]
	v_pk_mul_f32 v[4:5], v[126:127], v[24:25]
	v_cvt_pk_bf16_f32 v2, v2, v3
	v_pk_mul_f32 v[12:13], v[18:19], v[0:1] op_sel_hi:[1,0]
	v_cvt_pk_bf16_f32 v3, v4, v5
	global_store_dwordx2 v22, v[2:3], s[6:7] offset:192
	v_pk_mul_f32 v[2:3], v[132:133], v[10:11]
	v_pk_mul_f32 v[4:5], v[134:135], v[12:13]
	v_cvt_pk_bf16_f32 v2, v2, v3
	v_pk_mul_f32 v[10:11], v[16:17], v[0:1] op_sel_hi:[1,0]
	v_cvt_pk_bf16_f32 v3, v4, v5
	global_store_dwordx2 v22, v[2:3], s[6:7] offset:208
	v_pk_mul_f32 v[2:3], v[136:137], v[8:9]
	v_pk_mul_f32 v[4:5], v[138:139], v[10:11]
	v_cvt_pk_bf16_f32 v2, v2, v3
	v_pk_mul_f32 v[8:9], v[14:15], v[0:1] op_sel_hi:[1,0]
	v_cvt_pk_bf16_f32 v3, v4, v5
	global_store_dwordx2 v22, v[2:3], s[6:7] offset:224
	v_pk_mul_f32 v[2:3], v[140:141], v[6:7]
	v_pk_mul_f32 v[4:5], v[142:143], v[8:9]
	v_cvt_pk_bf16_f32 v2, v2, v3
	s_nop 0
	v_cvt_pk_bf16_f32 v3, v4, v5
	global_store_dwordx2 v22, v[2:3], s[6:7] offset:240
	s_waitcnt lgkmcnt(0)
	s_barrier
	s_cbranch_scc0 .LBB0_1007

; #define LAS __attribute__((address_space(3)))
; __device__ __forceinline__ float ex2(float x) { return __builtin_amdgcn_exp2f(x); }
; __device__ __forceinline__ float shx(float v, int mask, int lane) { return __int_as_float(__builtin_amdgcn_ds_bpermute((lane ^ mask) << 2, __float_as_int(v))); }
; __device__ __forceinline__ void attn_dif_unit(LAS unsigned char* lds, const int tid, const int wave_s, const bf16_t* q, const bf16_t* k0, const bf16_t* k1, const bf16_t* vt0, const bf16_t* vt1, ...
;     ...
;             f32x16 sacc[2]; const float nm = -m_used[m];
;             {
;                 bf16x8 qf[4], kfa[4], kfb[4];
; #pragma unroll
;                 for (int ks = 0; ks < 4; ++ks) qf[ks] = *(const LAS bf16x8*)(qb + c32 * DA_KP + m * 128 + ks * 32 + hi * 16);
; #pragma unroll
;                 for (int ks = 0; ks < 4; ++ks) kfa[ks] = *(const LAS bf16x8*)(kb + c32 * DA_KP + m * 128 + ks * 32 + hi * 16);
; #pragma unroll
;                 for (int ks = 0; ks < 4; ++ks) kfb[ks] = *(const LAS bf16x8*)(kb + (32 + c32) * DA_KP + m * 128 + ks * 32 + hi * 16);
; #pragma unroll
;                 for (int r = 0; r < 16; ++r) { sacc[0][r] = nm; sacc[1][r] = nm; }
; #pragma unroll
;                 for (int ks = 0; ks < 4; ++ks) sacc[0] = __builtin_amdgcn_mfma_f32_32x32x16_bf16(kfa[ks], qf[ks], sacc[0], 0, 0, 0);
; #pragma unroll
;                 for (int ks = 0; ks < 4; ++ks) sacc[1] = __builtin_amdgcn_mfma_f32_32x32x16_bf16(kfb[ks], qf[ks], sacc[1], 0, 0, 0);
;             }
;             float mx = fmaxf(sacc[0][0], sacc[1][0]);
; #pragma unroll
;             for (int a = 0; a < 2; ++a)
; #pragma unroll
;                 for (int r = 1; r < 16; r += 2) mx = fmaxf(fmaxf(mx, sacc[a][r]), sacc[a][r + 1 < 16 ? r + 1 : r]);
;             mx = fmaxf(mx, shx(mx, 32, lane));
;             if (t == 0 || __any(mx > DA_THR)) {
;                 const float delta = t == 0 ? mx : fmaxf(mx, 0.f), alpha = t == 0 ? 1.f : ex2(-delta);
.Ldif_noload:
.LBB0_989:
	v_mul_u32_u24_e32 v0, 0x110, v208
	v_add_u32_e32 v0, s22, v0
	v_add_u32_e32 v252, v0, v213
	ds_read_b128 v[2:5], v215
	ds_read_b128 v[6:9], v252
	v_xor_b32_e32 v144, 0x80000000, v218
	v_mov_b32_e32 v145, v144
	v_mov_b32_e32 v146, v144
	v_mov_b32_e32 v147, v144
	v_mov_b32_e32 v148, v144
	v_mov_b32_e32 v149, v144
	v_mov_b32_e32 v150, v144
	v_mov_b32_e32 v151, v144
	v_mov_b32_e32 v152, v144
	v_mov_b32_e32 v153, v144
	v_mov_b32_e32 v154, v144
	v_mov_b32_e32 v155, v144
	v_mov_b32_e32 v156, v144
	v_mov_b32_e32 v157, v144
	v_mov_b32_e32 v158, v144
	v_mov_b32_e32 v159, v144
	s_cmp_eq_u32 s55, 1
	s_cselect_b64 s[6:7], -1, 0
	s_waitcnt lgkmcnt(0)
	v_mfma_f32_32x32x16_bf16 v[160:175], v[6:9], v[2:5], v[144:159]
	ds_read_b128 v[6:9], v252 offset:32
	ds_read_b128 v[10:13], v215 offset:32
	s_cmp_lg_u32 s55, 1
	s_cselect_b64 s[10:11], -1, 0
	s_and_b64 vcc, exec, s[10:11]
	s_waitcnt lgkmcnt(0)
	v_mfma_f32_32x32x16_bf16 v[160:175], v[6:9], v[10:13], v[160:175]
	ds_read_b128 v[6:9], v252 offset:64
	ds_read_b128 v[192:195], v215 offset:64
	s_waitcnt lgkmcnt(0)
	v_mfma_f32_32x32x16_bf16 v[160:175], v[6:9], v[192:195], v[160:175]
	ds_read_b128 v[6:9], v252 offset:8704
	s_waitcnt lgkmcnt(0)
	v_mfma_f32_32x32x16_bf16 v[144:159], v[6:9], v[2:5], v[144:159]
	ds_read_b128 v[2:5], v252 offset:8736
	s_waitcnt lgkmcnt(0)
	v_mfma_f32_32x32x16_bf16 v[144:159], v[2:5], v[10:13], v[144:159]
	ds_read_b128 v[2:5], v252 offset:8768
	s_waitcnt lgkmcnt(0)
	v_mfma_f32_32x32x16_bf16 v[144:159], v[2:5], v[192:195], v[144:159]
	ds_read_b128 v[2:5], v252 offset:8800
	ds_read_b128 v[6:9], v215 offset:96
	s_waitcnt lgkmcnt(0)
	v_mfma_f32_32x32x16_bf16 v[144:159], v[2:5], v[6:9], v[144:159]
	ds_read_b128 v[2:5], v252 offset:96
	s_waitcnt lgkmcnt(0)
	v_mfma_f32_32x32x16_bf16 v[160:175], v[2:5], v[6:9], v[160:175]
	s_nop 8
	v_max_f32_e32 v0, v144, v144
	s_nop 1
	v_max_f32_e32 v2, v160, v160
	v_max_f32_e32 v0, v2, v0
	v_max3_f32 v0, v0, v161, v162
	v_max3_f32 v0, v0, v163, v164
	v_max3_f32 v0, v0, v165, v166
	v_max3_f32 v0, v0, v167, v168
	v_max3_f32 v0, v0, v169, v170
	v_max3_f32 v0, v0, v171, v172
	v_max3_f32 v0, v0, v173, v174
	v_max3_f32 v0, v0, v175, v145
	v_max3_f32 v0, v0, v146, v147
	v_max3_f32 v0, v0, v148, v149
	v_max3_f32 v0, v0, v150, v151
	v_max3_f32 v0, v0, v152, v153
	v_max3_f32 v0, v0, v154, v155
	v_max3_f32 v0, v0, v156, v157
	v_max3_f32 v0, v0, v158, v159
	v_mov_b32_e32 v2, v0
	s_nop 1
	v_permlane32_swap_b32_e32 v2, v0
	v_max_f32_e32 v192, v0, v2
	s_cbranch_vccz .LBB0_993
	v_cmp_lt_f32_e32 vcc, s64, v192
	s_mov_b64 s[14:15], 0
	s_mov_b64 s[12:13], 0
	s_cbranch_vccz .LBB0_992
	v_max_f32_e32 v0, v192, v192
	v_max_f32_e32 v0, 0, v0
	s_mov_b64 s[12:13], -1

; __device__ __forceinline__ void attn_dif_unit(LAS unsigned char* lds, const int tid, const int wave_s, const bf16_t* q, const bf16_t* k0, const bf16_t* k1, const bf16_t* vt0, const bf16_t* vt1, ...
;     ...
;             f32x16 sacc[2]; const float nm = -m_used[m];
;             {
;                 bf16x8 qf[4], kfa[4], kfb[4];
; #pragma unroll
;                 for (int ks = 0; ks < 4; ++ks) qf[ks] = *(const LAS bf16x8*)(qb + c32 * DA_KP + m * 128 + ks * 32 + hi * 16);
; #pragma unroll
;                 for (int ks = 0; ks < 4; ++ks) kfa[ks] = *(const LAS bf16x8*)(kb + c32 * DA_KP + m * 128 + ks * 32 + hi * 16);
; #pragma unroll
;                 for (int ks = 0; ks < 4; ++ks) kfb[ks] = *(const LAS bf16x8*)(kb + (32 + c32) * DA_KP + m * 128 + ks * 32 + hi * 16);
; #pragma unroll
;                 for (int r = 0; r < 16; ++r) { sacc[0][r] = nm; sacc[1][r] = nm; }
; #pragma unroll
;                 for (int ks = 0; ks < 4; ++ks) sacc[0] = __builtin_amdgcn_mfma_f32_32x32x16_bf16(kfa[ks], qf[ks], sacc[0], 0, 0, 0);
; #pragma unroll
;                 for (int ks = 0; ks < 4; ++ks) sacc[1] = __builtin_amdgcn_mfma_f32_32x32x16_bf16(kfb[ks], qf[ks], sacc[1], 0, 0, 0);
;             }
;             float mx = fmaxf(sacc[0][0], sacc[1][0]);
; #pragma unroll
;             for (int a = 0; a < 2; ++a)
; #pragma unroll
;     ...
;             float ls = 0.f;
; #pragma unroll
;             for (int a = 0; a < 2; ++a)
; #pragma unroll
;                 for (int r = 0; r < 16; ++r) { const float p = ex2(sacc[a][r]); sacc[a][r] = p; ls += p; }
;             l_run[m] += ls;
;             bf16x8 pf[4];
; #pragma unroll
;             for (int a = 0; a < 2; ++a)
; #pragma unroll
;                 for (int jj = 0; jj < 2; ++jj) { u32x4 wv; wv.x = cvt_pk_bf16(sacc[a][8 * jj + 0], sacc[a][8 * jj + 1]); wv.y = cvt_pk_bf16(sacc[a][8 * jj + 2], sacc[a][8 * jj + 3]);
;                     wv.z = cvt_pk_bf16(sacc[a][8 * jj + 4], sacc[a][8 * jj + 5]); wv.w = cvt_pk_bf16(sacc[a][8 * jj + 6], sacc[a][8 * jj + 7]); pf[2 * a + jj] = __builtin_bit_cast(bf16x8, wv); }
;             if (m == 1 && t + 1 < ntile) DA_LOAD(t + 1);
;             {
;                 const LAS unsigned char* vp0 = vb + c32 * DA_VP + hi * 16;
;     ...
;                 bf16x8 va[4], vc[4];
;                 DA_VF(va, 0); DA_VF(vc, 1); DA_PV(va, 0); DA_VF(va, 2); DA_PV(vc, 1); DA_VF(vc, 3); DA_PV(va, 2); DA_PV(vc, 3);
.LBB0_997:
	v_mul_u32_u24_e32 v0, 0x90, v208
	v_add_u32_e32 v0, s22, v0
	v_add_u32_e32 v220, v0, v213
	v_exp_f32_e32 v221, v160
	v_exp_f32_e32 v222, v161
	v_exp_f32_e32 v223, v162
	v_exp_f32_e32 v224, v163
	v_exp_f32_e32 v225, v164
	v_exp_f32_e32 v226, v165
	v_exp_f32_e32 v227, v166
	v_exp_f32_e32 v228, v167
	v_exp_f32_e32 v229, v168
	v_exp_f32_e32 v230, v169
	v_exp_f32_e32 v231, v170
	v_exp_f32_e32 v232, v171
	v_exp_f32_e32 v233, v172
	v_exp_f32_e32 v234, v173
	v_exp_f32_e32 v235, v174
	v_exp_f32_e32 v236, v175
	v_exp_f32_e32 v237, v144
	v_exp_f32_e32 v238, v145
	v_exp_f32_e32 v239, v146
	v_exp_f32_e32 v247, v147
	v_exp_f32_e32 v241, v148
	v_exp_f32_e32 v243, v149
	v_exp_f32_e32 v240, v150
	v_exp_f32_e32 v192, v151
	v_exp_f32_e32 v193, v152
	v_exp_f32_e32 v194, v153
	v_exp_f32_e32 v195, v154
	v_exp_f32_e32 v196, v155
	v_exp_f32_e32 v197, v156
	v_exp_f32_e32 v242, v157
	v_exp_f32_e32 v250, v158
	v_exp_f32_e32 v251, v159
	ds_read_b128 v[148:151], v220 offset:17408
	ds_read_b128 v[152:155], v220 offset:17440
	ds_read_b128 v[156:159], v220 offset:17472
	ds_read_b128 v[160:163], v220 offset:17504
	ds_read_b128 v[164:167], v220 offset:22016
	ds_read_b128 v[168:171], v220 offset:22048
	v_cvt_pk_bf16_f32 v2, v221, v222
	v_cvt_pk_bf16_f32 v3, v223, v224
	v_cvt_pk_bf16_f32 v4, v225, v226
	v_cvt_pk_bf16_f32 v5, v227, v228
	v_cvt_pk_bf16_f32 v6, v229, v230
	v_cvt_pk_bf16_f32 v7, v231, v232
	v_cvt_pk_bf16_f32 v8, v233, v234
	v_cvt_pk_bf16_f32 v9, v235, v236
	v_cvt_pk_bf16_f32 v10, v237, v238
	v_cvt_pk_bf16_f32 v11, v239, v247
	v_cvt_pk_bf16_f32 v12, v241, v243
	v_cvt_pk_bf16_f32 v13, v240, v192
	v_cvt_pk_bf16_f32 v144, v193, v194
	v_cvt_pk_bf16_f32 v145, v195, v196
	v_cvt_pk_bf16_f32 v146, v197, v242
	v_cvt_pk_bf16_f32 v147, v250, v251
	s_waitcnt lgkmcnt(5)
	v_mfma_f32_32x32x16_bf16 v[128:143], v[148:151], v[2:5], v[128:143]
	ds_read_b128 v[172:175], v220 offset:22080
	s_waitcnt lgkmcnt(5)
	v_mfma_f32_32x32x16_bf16 v[128:143], v[152:155], v[6:9], v[128:143]
	ds_read_b128 v[148:151], v220 offset:22112
	s_waitcnt lgkmcnt(5)
	v_mfma_f32_32x32x16_bf16 v[128:143], v[156:159], v[10:13], v[128:143]
	ds_read_b128 v[152:155], v220 offset:26624
	s_waitcnt lgkmcnt(5)
	v_mfma_f32_32x32x16_bf16 v[128:143], v[160:163], v[144:147], v[128:143]
	ds_read_b128 v[156:159], v220 offset:26656
	s_waitcnt lgkmcnt(5)
	v_mfma_f32_32x32x16_bf16 v[96:111], v[164:167], v[2:5], v[96:111]
	ds_read_b128 v[160:163], v220 offset:26688
	s_waitcnt lgkmcnt(5)
	v_mfma_f32_32x32x16_bf16 v[96:111], v[168:171], v[6:9], v[96:111]
	ds_read_b128 v[164:167], v220 offset:26720
	s_waitcnt lgkmcnt(5)
	v_mfma_f32_32x32x16_bf16 v[96:111], v[172:175], v[10:13], v[96:111]
	ds_read_b128 v[168:171], v220 offset:31232
	s_waitcnt lgkmcnt(5)
	v_mfma_f32_32x32x16_bf16 v[96:111], v[148:151], v[144:147], v[96:111]
	ds_read_b128 v[172:175], v220 offset:31264
	s_waitcnt lgkmcnt(5)
	v_mfma_f32_32x32x16_bf16 v[64:79], v[152:155], v[2:5], v[64:79]
	ds_read_b128 v[148:151], v220 offset:31296
	s_waitcnt lgkmcnt(5)
	v_mfma_f32_32x32x16_bf16 v[64:79], v[156:159], v[6:9], v[64:79]
	ds_read_b128 v[152:155], v220 offset:31328
	s_waitcnt lgkmcnt(5)
	v_mfma_f32_32x32x16_bf16 v[64:79], v[160:163], v[10:13], v[64:79]
	s_waitcnt lgkmcnt(4)
	v_mfma_f32_32x32x16_bf16 v[64:79], v[164:167], v[144:147], v[64:79]
	s_waitcnt lgkmcnt(3)
	v_mfma_f32_32x32x16_bf16 v[32:47], v[168:171], v[2:5], v[32:47]
	s_waitcnt lgkmcnt(2)
	v_mfma_f32_32x32x16_bf16 v[32:47], v[172:175], v[6:9], v[32:47]
	s_waitcnt lgkmcnt(1)
	v_mfma_f32_32x32x16_bf16 v[32:47], v[148:151], v[10:13], v[32:47]
	s_waitcnt lgkmcnt(0)
	v_mfma_f32_32x32x16_bf16 v[32:47], v[152:155], v[144:147], v[32:47]
	ds_read_b128 v[2:5], v215 offset:128
	ds_read_b128 v[6:9], v252 offset:128
	v_xor_b32_e32 v144, 0x80000000, v217
	v_mov_b32_e32 v145, v144
	v_mov_b32_e32 v146, v144
	v_mov_b32_e32 v147, v144
	v_mov_b32_e32 v148, v144
	v_mov_b32_e32 v149, v144
	v_mov_b32_e32 v150, v144
	v_mov_b32_e32 v151, v144
	v_mov_b32_e32 v152, v144
	v_mov_b32_e32 v153, v144
	v_mov_b32_e32 v154, v144
	v_mov_b32_e32 v155, v144
	v_mov_b32_e32 v156, v144
	v_mov_b32_e32 v157, v144
	v_mov_b32_e32 v158, v144
	v_mov_b32_e32 v159, v144
	s_and_b64 vcc, exec, s[10:11]
	s_waitcnt lgkmcnt(0)
	v_mfma_f32_32x32x16_bf16 v[160:175], v[6:9], v[2:5], v[144:159]
	ds_read_b128 v[6:9], v252 offset:160
	ds_read_b128 v[10:13], v215 offset:160
	s_waitcnt lgkmcnt(0)
	v_mfma_f32_32x32x16_bf16 v[160:175], v[6:9], v[10:13], v[160:175]
	ds_read_b128 v[6:9], v252 offset:192
	ds_read_b128 v[204:207], v215 offset:192
	s_waitcnt lgkmcnt(0)
	v_mfma_f32_32x32x16_bf16 v[160:175], v[6:9], v[204:207], v[160:175]
	ds_read_b128 v[6:9], v252 offset:8832
	s_waitcnt lgkmcnt(0)
	v_mfma_f32_32x32x16_bf16 v[144:159], v[6:9], v[2:5], v[144:159]
	ds_read_b128 v[2:5], v252 offset:8864
	s_waitcnt lgkmcnt(0)
	v_mfma_f32_32x32x16_bf16 v[144:159], v[2:5], v[10:13], v[144:159]
	ds_read_b128 v[2:5], v252 offset:8896
	s_waitcnt lgkmcnt(0)
	v_mfma_f32_32x32x16_bf16 v[144:159], v[2:5], v[204:207], v[144:159]
	ds_read_b128 v[2:5], v252 offset:8928
	ds_read_b128 v[6:9], v215 offset:224
	s_waitcnt lgkmcnt(0)
	v_mfma_f32_32x32x16_bf16 v[144:159], v[2:5], v[6:9], v[144:159]
	ds_read_b128 v[2:5], v252 offset:224
	s_waitcnt lgkmcnt(0)
	v_mfma_f32_32x32x16_bf16 v[160:175], v[2:5], v[6:9], v[160:175]
	s_nop 8
	v_max_f32_e32 v0, v144, v144
	s_nop 1
	v_max_f32_e32 v2, v160, v160
	v_max_f32_e32 v0, v2, v0
	v_max3_f32 v0, v0, v161, v162
	v_max3_f32 v0, v0, v163, v164
	v_max3_f32 v0, v0, v165, v166
	v_max3_f32 v0, v0, v167, v168
	v_max3_f32 v0, v0, v169, v170
	v_max3_f32 v0, v0, v171, v172
	v_max3_f32 v0, v0, v173, v174
	v_max3_f32 v0, v0, v175, v145
	v_max3_f32 v0, v0, v146, v147
	v_max3_f32 v0, v0, v148, v149
	v_max3_f32 v0, v0, v150, v151
	v_max3_f32 v0, v0, v152, v153
	v_max3_f32 v0, v0, v154, v155
	v_max3_f32 v0, v0, v156, v157
	v_max3_f32 v0, v0, v158, v159
	v_mov_b32_e32 v2, v0
	s_nop 1
	v_permlane32_swap_b32_e32 v2, v0
	v_max_f32_e32 v252, v0, v2
	s_cbranch_vccz .LBB0_1001
	v_cmp_lt_f32_e32 vcc, s64, v252
	s_mov_b64 s[12:13], 0
	s_mov_b64 s[10:11], 0
	s_cbranch_vccz .LBB0_1000
	v_max_f32_e32 v0, v252, v252
	v_max_f32_e32 v0, 0, v0
	s_mov_b64 s[10:11], -1

; #define PG8_WAIT_V(n) asm volatile("s_waitcnt vmcnt(" #n ")" ::: "memory")
; #define PG8_BAR __builtin_amdgcn_s_barrier()
; #define EPI_ROWS(ai, m) _Pragma("unroll") for (int ai = 0; ai < 2; ++ai) _Pragma("unroll") for (int m = 0; m < 4; ++m)
; #define EPI_COLS(bj, n) _Pragma("unroll") for (int bj = 0; bj < 2; ++bj) _Pragma("unroll") for (int n = 0; n < 2; ++n)
; template <class Epi, class Sched, bool ALIGN_EPI, bool LAST_FUSED = false, bool PERM = false, bool CARRY = false>
; __device__ __forceinline__ void gemm_phase(LAS unsigned char* lds, const int tid, const int K, const int lda, const int ldb, const Sched& S, const Epi& E) {
;     ...
;     PG8_WAIT_V(0);
;     if constexpr (!ALIGN_EPI) { if (wr == 0) PG8_BAR; }
;     PG8_BAR;
;     __device__ __forceinline__ void fused(Acc& acc, const Unit& u, int wr, int wc, int fr, int fq) const {
;         const int colb = u.pn * 256 + wc * 32 + fq * 4;
;         f32x4 gv[2][2];
;         { const float* gp = gate + (size_t)((u.pm * 256) >> 11) * MODW + colb;
;           EPI_COLS(bj, n) gv[bj][n] = *(const f32x4*)(gp + bj * 128 + n * 16); }
;         EPI_ROWS(ai, m) { const int row = u.pm * 256 + ai * 128 + wr * 64 + m * 16 + fr; const float* hp = H + (size_t)row * D + colb;
;             EPI_COLS(bj, n) { const int co = bj * 128 + n * 16; acc[ai][bj][m][n] = *(const f32x4*)(hp + co) * ALPHA + gv[bj][n] * acc[ai][bj][m][n]; }
;             asm volatile("" : "+v"(acc[ai][0][m][0]), "+v"(acc[ai][0][m][1]), "+v"(acc[ai][1][m][0]), "+v"(acc[ai][1][m][1]));
;             if (m == 3) asm volatile("" ::: "memory"); }
.LBB0_1592:
	s_waitcnt vmcnt(0)
	s_barrier
	s_lshl_b32 s2, s38, 8
	s_lshl_b32 s3, s39, 5
	s_add_i32 s3, s3, s2
	s_ashr_i32 s2, s30, 3
	s_mul_i32 s46, s2, 0xc000
	s_mul_hi_i32 s24, s2, 0xc000
	s_add_u32 s2, s60, s46
	v_lshl_add_u32 v190, v155, 2, s3
	s_addc_u32 s3, s61, s24
	s_lshl_b32 s40, s30, 8
	v_lshl_add_u32 v0, s31, 6, v154
	v_ashrrev_i32_e32 v191, 31, v190
	v_add_u32_e32 v200, s40, v0
	v_lshlrev_b64 v[178:179], 2, v[190:191]
	v_ashrrev_i32_e32 v201, 31, v200
	v_lshl_add_u64 v[122:123], s[2:3], 0, v[178:179]
	v_lshlrev_b64 v[206:207], 13, v[200:201]
	global_load_dwordx4 v[150:153], v[122:123], off
	global_load_dwordx4 v[146:149], v[122:123], off offset:64
	global_load_dwordx4 v[142:145], v[122:123], off offset:512
	global_load_dwordx4 v[138:141], v[122:123], off offset:576
	v_add_u32_e32 v180, 16, v200
	v_ashrrev_i32_e32 v181, 31, v180
	v_lshlrev_b64 v[182:183], 13, v[180:181]
	v_add_u32_e32 v184, 32, v200
	v_ashrrev_i32_e32 v185, 31, v184
	v_lshlrev_b64 v[186:187], 13, v[184:185]
	v_add_u32_e32 v188, 48, v200
	v_ashrrev_i32_e32 v189, 31, v188
	v_lshlrev_b64 v[198:199], 13, v[188:189]
	v_add_u32_e32 v202, 0x80, v200
	v_ashrrev_i32_e32 v203, 31, v202
	v_lshlrev_b64 v[204:205], 13, v[202:203]
	v_add_u32_e32 v208, 0x90, v200
	v_ashrrev_i32_e32 v209, 31, v208
	v_lshlrev_b64 v[210:211], 13, v[208:209]
	v_add_u32_e32 v212, 0xa0, v200
	v_ashrrev_i32_e32 v213, 31, v212
	v_lshlrev_b64 v[214:215], 13, v[212:213]
	v_add_u32_e32 v216, 0xb0, v200
	v_ashrrev_i32_e32 v217, 31, v216
	v_lshlrev_b64 v[218:219], 13, v[216:217]
	s_lshl_b32 s2, s39, 3
	s_add_i32 s14, s2, 0
	v_cmp_eq_u32_e32 vcc, 0, v155
	s_add_i32 s14, s14, 0x20000
	v_lshl_add_u64 v[196:197], s[70:71], 0, v[206:207]
	v_lshl_add_u64 v[196:197], v[196:197], 0, v[178:179]
	global_load_dwordx4 v[158:161], v[196:197], off
	global_load_dwordx4 v[162:165], v[196:197], off offset:64
	global_load_dwordx4 v[166:169], v[196:197], off offset:512
	global_load_dwordx4 v[170:173], v[196:197], off offset:576
	v_lshl_add_u64 v[196:197], s[70:71], 0, v[182:183]
	v_lshl_add_u64 v[196:197], v[196:197], 0, v[178:179]
	global_load_dwordx4 v[174:177], v[196:197], off
	global_load_dwordx4 v[192:195], v[196:197], off offset:64
	global_load_dwordx4 v[220:223], v[196:197], off offset:512
	global_load_dwordx4 v[224:227], v[196:197], off offset:576
	s_waitcnt vmcnt(4)
	v_pk_mul_f32 v[124:125], v[160:161], s[84:85] op_sel_hi:[1,0]
	v_pk_mul_f32 v[122:123], v[158:159], s[84:85] op_sel_hi:[1,0]
	v_pk_fma_f32 v[64:65], v[64:65], v[152:153], v[124:125]
	v_pk_fma_f32 v[62:63], v[62:63], v[150:151], v[122:123]
	v_pk_mul_f32 v[124:125], v[164:165], s[84:85] op_sel_hi:[1,0]
	v_pk_mul_f32 v[122:123], v[162:163], s[84:85] op_sel_hi:[1,0]
	v_pk_fma_f32 v[44:45], v[44:45], v[148:149], v[124:125]
	v_pk_fma_f32 v[42:43], v[42:43], v[146:147], v[122:123]
	v_pk_mul_f32 v[124:125], v[168:169], s[84:85] op_sel_hi:[1,0]
	v_pk_mul_f32 v[122:123], v[166:167], s[84:85] op_sel_hi:[1,0]
	v_pk_fma_f32 v[36:37], v[36:37], v[144:145], v[124:125]
	v_pk_fma_f32 v[34:35], v[34:35], v[142:143], v[122:123]
	v_pk_mul_f32 v[122:123], v[170:171], s[84:85] op_sel_hi:[1,0]
	v_pk_mul_f32 v[124:125], v[172:173], s[84:85] op_sel_hi:[1,0]
	v_lshl_add_u64 v[196:197], s[70:71], 0, v[186:187]
	v_lshl_add_u64 v[196:197], v[196:197], 0, v[178:179]
	global_load_dwordx4 v[158:161], v[196:197], off
	global_load_dwordx4 v[162:165], v[196:197], off offset:64
	global_load_dwordx4 v[166:169], v[196:197], off offset:512
	global_load_dwordx4 v[170:173], v[196:197], off offset:576
	v_pk_fma_f32 v[2:3], v[2:3], v[138:139], v[122:123]
	v_pk_fma_f32 v[4:5], v[4:5], v[140:141], v[124:125]
	s_waitcnt vmcnt(4)
	v_pk_mul_f32 v[124:125], v[176:177], s[84:85] op_sel_hi:[1,0]
	v_pk_mul_f32 v[122:123], v[174:175], s[84:85] op_sel_hi:[1,0]
	v_pk_fma_f32 v[20:21], v[20:21], v[152:153], v[124:125]
	v_pk_fma_f32 v[18:19], v[18:19], v[150:151], v[122:123]
	v_pk_mul_f32 v[124:125], v[194:195], s[84:85] op_sel_hi:[1,0]
	v_pk_mul_f32 v[122:123], v[192:193], s[84:85] op_sel_hi:[1,0]
	v_pk_fma_f32 v[16:17], v[16:17], v[148:149], v[124:125]
	v_pk_fma_f32 v[14:15], v[14:15], v[146:147], v[122:123]
	v_pk_mul_f32 v[124:125], v[222:223], s[84:85] op_sel_hi:[1,0]
	v_pk_mul_f32 v[122:123], v[220:221], s[84:85] op_sel_hi:[1,0]
	v_pk_fma_f32 v[12:13], v[12:13], v[144:145], v[124:125]
	v_pk_fma_f32 v[10:11], v[10:11], v[142:143], v[122:123]
	v_pk_mul_f32 v[122:123], v[224:225], s[84:85] op_sel_hi:[1,0]
	v_pk_mul_f32 v[124:125], v[226:227], s[84:85] op_sel_hi:[1,0]
	v_lshl_add_u64 v[196:197], s[70:71], 0, v[198:199]
	v_lshl_add_u64 v[196:197], v[196:197], 0, v[178:179]
	global_load_dwordx4 v[174:177], v[196:197], off
	global_load_dwordx4 v[192:195], v[196:197], off offset:64
	global_load_dwordx4 v[220:223], v[196:197], off offset:512
	global_load_dwordx4 v[224:227], v[196:197], off offset:576
	v_pk_fma_f32 v[6:7], v[6:7], v[138:139], v[122:123]
	v_pk_fma_f32 v[8:9], v[8:9], v[140:141], v[124:125]
	s_waitcnt vmcnt(4)
	v_pk_mul_f32 v[124:125], v[160:161], s[84:85] op_sel_hi:[1,0]
	v_pk_mul_f32 v[122:123], v[158:159], s[84:85] op_sel_hi:[1,0]
	v_pk_fma_f32 v[40:41], v[40:41], v[152:153], v[124:125]
	v_pk_fma_f32 v[38:39], v[38:39], v[150:151], v[122:123]
	v_pk_mul_f32 v[124:125], v[164:165], s[84:85] op_sel_hi:[1,0]
	v_pk_mul_f32 v[122:123], v[162:163], s[84:85] op_sel_hi:[1,0]
	v_pk_fma_f32 v[32:33], v[32:33], v[148:149], v[124:125]
	v_pk_fma_f32 v[30:31], v[30:31], v[146:147], v[122:123]
	v_pk_mul_f32 v[124:125], v[168:169], s[84:85] op_sel_hi:[1,0]
	v_pk_mul_f32 v[122:123], v[166:167], s[84:85] op_sel_hi:[1,0]
	v_pk_fma_f32 v[28:29], v[28:29], v[144:145], v[124:125]
	v_pk_fma_f32 v[26:27], v[26:27], v[142:143], v[122:123]
	v_pk_mul_f32 v[122:123], v[170:171], s[84:85] op_sel_hi:[1,0]
	v_pk_mul_f32 v[124:125], v[172:173], s[84:85] op_sel_hi:[1,0]
	v_lshl_add_u64 v[196:197], s[70:71], 0, v[204:205]
	v_lshl_add_u64 v[196:197], v[196:197], 0, v[178:179]
	global_load_dwordx4 v[158:161], v[196:197], off
	global_load_dwordx4 v[162:165], v[196:197], off offset:64
	global_load_dwordx4 v[166:169], v[196:197], off offset:512
	global_load_dwordx4 v[170:173], v[196:197], off offset:576
	v_pk_fma_f32 v[22:23], v[22:23], v[138:139], v[122:123]
	v_pk_fma_f32 v[24:25], v[24:25], v[140:141], v[124:125]
	s_waitcnt vmcnt(4)
; #define EPI_ROWS(ai, m) _Pragma("unroll") for (int ai = 0; ai < 2; ++ai) _Pragma("unroll") for (int m = 0; m < 4; ++m)
; #define EPI_COLS(bj, n) _Pragma("unroll") for (int bj = 0; bj < 2; ++bj) _Pragma("unroll") for (int n = 0; n < 2; ++n)
;     __device__ __forceinline__ void fused(Acc& acc, const Unit& u, int wr, int wc, int fr, int fq) const {
;     ...
;         EPI_ROWS(ai, m) { const int row = u.pm * 256 + ai * 128 + wr * 64 + m * 16 + fr; const float* hp = H + (size_t)row * D + colb;
;             EPI_COLS(bj, n) { const int co = bj * 128 + n * 16; acc[ai][bj][m][n] = *(const f32x4*)(hp + co) * ALPHA + gv[bj][n] * acc[ai][bj][m][n]; }
;             asm volatile("" : "+v"(acc[ai][0][m][0]), "+v"(acc[ai][0][m][1]), "+v"(acc[ai][1][m][0]), "+v"(acc[ai][1][m][1]));
;             if (m == 3) asm volatile("" ::: "memory"); }
	v_pk_mul_f32 v[124:125], v[176:177], s[84:85] op_sel_hi:[1,0]
	v_pk_mul_f32 v[122:123], v[174:175], s[84:85] op_sel_hi:[1,0]
	v_pk_fma_f32 v[60:61], v[60:61], v[152:153], v[124:125]
	v_pk_fma_f32 v[58:59], v[58:59], v[150:151], v[122:123]
	v_pk_mul_f32 v[124:125], v[194:195], s[84:85] op_sel_hi:[1,0]
	v_pk_mul_f32 v[122:123], v[192:193], s[84:85] op_sel_hi:[1,0]
	v_pk_fma_f32 v[56:57], v[56:57], v[148:149], v[124:125]
	v_pk_fma_f32 v[54:55], v[54:55], v[146:147], v[122:123]
	v_pk_mul_f32 v[124:125], v[222:223], s[84:85] op_sel_hi:[1,0]
	v_pk_mul_f32 v[122:123], v[220:221], s[84:85] op_sel_hi:[1,0]
	v_pk_fma_f32 v[52:53], v[52:53], v[144:145], v[124:125]
	v_pk_fma_f32 v[50:51], v[50:51], v[142:143], v[122:123]
	v_pk_mul_f32 v[124:125], v[226:227], s[84:85] op_sel_hi:[1,0]
	v_pk_mul_f32 v[122:123], v[224:225], s[84:85] op_sel_hi:[1,0]
	v_lshl_add_u64 v[196:197], s[70:71], 0, v[210:211]
	v_lshl_add_u64 v[196:197], v[196:197], 0, v[178:179]
	global_load_dwordx4 v[174:177], v[196:197], off
	global_load_dwordx4 v[192:195], v[196:197], off offset:64
	global_load_dwordx4 v[220:223], v[196:197], off offset:512
	global_load_dwordx4 v[224:227], v[196:197], off offset:576
	v_pk_fma_f32 v[48:49], v[48:49], v[140:141], v[124:125]
	v_pk_fma_f32 v[46:47], v[46:47], v[138:139], v[122:123]
	s_waitcnt vmcnt(4)
	v_pk_mul_f32 v[124:125], v[160:161], s[84:85] op_sel_hi:[1,0]
	v_pk_mul_f32 v[122:123], v[158:159], s[84:85] op_sel_hi:[1,0]
	v_pk_fma_f32 v[80:81], v[80:81], v[152:153], v[124:125]
	v_pk_fma_f32 v[78:79], v[78:79], v[150:151], v[122:123]
	v_pk_mul_f32 v[124:125], v[164:165], s[84:85] op_sel_hi:[1,0]
	v_pk_mul_f32 v[122:123], v[162:163], s[84:85] op_sel_hi:[1,0]
	v_pk_fma_f32 v[76:77], v[76:77], v[148:149], v[124:125]
	v_pk_fma_f32 v[74:75], v[74:75], v[146:147], v[122:123]
	v_pk_mul_f32 v[124:125], v[168:169], s[84:85] op_sel_hi:[1,0]
	v_pk_mul_f32 v[122:123], v[166:167], s[84:85] op_sel_hi:[1,0]
	v_pk_fma_f32 v[72:73], v[72:73], v[144:145], v[124:125]
	v_pk_fma_f32 v[70:71], v[70:71], v[142:143], v[122:123]
	v_pk_mul_f32 v[122:123], v[170:171], s[84:85] op_sel_hi:[1,0]
	v_pk_mul_f32 v[124:125], v[172:173], s[84:85] op_sel_hi:[1,0]
	v_lshl_add_u64 v[196:197], s[70:71], 0, v[214:215]
	v_lshl_add_u64 v[196:197], v[196:197], 0, v[178:179]
	global_load_dwordx4 v[158:161], v[196:197], off
	global_load_dwordx4 v[162:165], v[196:197], off offset:64
	global_load_dwordx4 v[166:169], v[196:197], off offset:512
	global_load_dwordx4 v[170:173], v[196:197], off offset:576
	v_pk_fma_f32 v[66:67], v[66:67], v[138:139], v[122:123]
	v_pk_fma_f32 v[68:69], v[68:69], v[140:141], v[124:125]
	s_waitcnt vmcnt(4)
	v_pk_mul_f32 v[124:125], v[176:177], s[84:85] op_sel_hi:[1,0]
	v_pk_mul_f32 v[122:123], v[174:175], s[84:85] op_sel_hi:[1,0]
	v_pk_fma_f32 v[100:101], v[100:101], v[152:153], v[124:125]
	v_pk_fma_f32 v[98:99], v[98:99], v[150:151], v[122:123]
	v_pk_mul_f32 v[124:125], v[194:195], s[84:85] op_sel_hi:[1,0]
	v_pk_mul_f32 v[122:123], v[192:193], s[84:85] op_sel_hi:[1,0]
	v_pk_fma_f32 v[96:97], v[96:97], v[148:149], v[124:125]
	v_pk_fma_f32 v[94:95], v[94:95], v[146:147], v[122:123]
	v_pk_mul_f32 v[124:125], v[222:223], s[84:85] op_sel_hi:[1,0]
	v_pk_mul_f32 v[122:123], v[220:221], s[84:85] op_sel_hi:[1,0]
	v_pk_fma_f32 v[92:93], v[92:93], v[144:145], v[124:125]
	v_pk_fma_f32 v[90:91], v[90:91], v[142:143], v[122:123]
	v_pk_mul_f32 v[122:123], v[224:225], s[84:85] op_sel_hi:[1,0]
	v_pk_mul_f32 v[124:125], v[226:227], s[84:85] op_sel_hi:[1,0]
	v_lshl_add_u64 v[196:197], s[70:71], 0, v[218:219]
	v_lshl_add_u64 v[196:197], v[196:197], 0, v[178:179]
	global_load_dwordx4 v[174:177], v[196:197], off
	global_load_dwordx4 v[192:195], v[196:197], off offset:64
	global_load_dwordx4 v[220:223], v[196:197], off offset:512
	global_load_dwordx4 v[224:227], v[196:197], off offset:576
	v_pk_fma_f32 v[86:87], v[86:87], v[138:139], v[122:123]
	v_pk_fma_f32 v[88:89], v[88:89], v[140:141], v[124:125]
	s_waitcnt vmcnt(4)
	v_pk_mul_f32 v[124:125], v[160:161], s[84:85] op_sel_hi:[1,0]
	v_pk_mul_f32 v[122:123], v[158:159], s[84:85] op_sel_hi:[1,0]
	v_pk_fma_f32 v[128:129], v[120:121], v[152:153], v[124:125]
	v_pk_fma_f32 v[126:127], v[118:119], v[150:151], v[122:123]
	v_pk_mul_f32 v[120:121], v[164:165], s[84:85] op_sel_hi:[1,0]
	v_pk_mul_f32 v[118:119], v[162:163], s[84:85] op_sel_hi:[1,0]
	v_pk_fma_f32 v[124:125], v[116:117], v[148:149], v[120:121]
	v_pk_fma_f32 v[122:123], v[114:115], v[146:147], v[118:119]
	v_pk_mul_f32 v[116:117], v[168:169], s[84:85] op_sel_hi:[1,0]
	v_pk_mul_f32 v[114:115], v[166:167], s[84:85] op_sel_hi:[1,0]
	v_pk_fma_f32 v[120:121], v[112:113], v[144:145], v[116:117]
	v_pk_fma_f32 v[118:119], v[110:111], v[142:143], v[114:115]
	v_pk_mul_f32 v[110:111], v[170:171], s[84:85] op_sel_hi:[1,0]
	v_pk_mul_f32 v[112:113], v[172:173], s[84:85] op_sel_hi:[1,0]
	v_pk_fma_f32 v[114:115], v[106:107], v[138:139], v[110:111]
	v_pk_fma_f32 v[116:117], v[108:109], v[140:141], v[112:113]
	s_waitcnt vmcnt(0)
; __device__ __forceinline__ float shx(float v, int mask, int lane) { return __int_as_float(__builtin_amdgcn_ds_bpermute((lane ^ mask) << 2, __float_as_int(v))); }
;     __device__ __forceinline__ void run(const Acc& v, const Unit& u, int wr, int wc, int fr, int fq, LAS unsigned char* sl, int wid, int lane) const {
;     ...
;                 float sm = 0.f;
; #pragma unroll
;                 for (int bj = 0; bj < 2; ++bj)
; #pragma unroll
;                     for (int n = 0; n < 2; ++n) { const f32x4 x = v[ai][bj][m][n]; sm += (x[0] + x[1]) + (x[2] + x[3]); }
;                 sm += shx(sm, 16, lane); sm += shx(sm, 32, lane);
;                 const float mw = sm * (1.0f / 64.0f); float q = 0.f;
; #pragma unroll
;                 for (int bj = 0; bj < 2; ++bj)
; #pragma unroll
;                     for (int n = 0; n < 2; ++n) { const f32x4 d = v[ai][bj][m][n] - mw; q += (d[0] * d[0] + d[1] * d[1]) + (d[2] * d[2] + d[3] * d[3]); }
;                 q += shx(q, 16, lane); q += shx(q, 32, lane);
;                 if (fq == 0) P[(ai * 128 + wr * 64 + m * 16 + fr) * 4 + wc] = (f32x2){mw, q};
	v_pk_mul_f32 v[108:109], v[176:177], s[84:85] op_sel_hi:[1,0]
	v_pk_mul_f32 v[106:107], v[174:175], s[84:85] op_sel_hi:[1,0]
	v_pk_fma_f32 v[112:113], v[136:137], v[152:153], v[108:109]
	v_pk_fma_f32 v[110:111], v[134:135], v[150:151], v[106:107]
	v_mov_b32_e32 v134, v63
	v_mov_b32_e32 v135, v64
	v_mov_b32_e32 v136, v62
	v_mov_b32_e32 v137, v65
	v_pk_add_f32 v[134:135], v[134:135], v[136:137]
	v_mov_b32_e32 v136, v43
	v_mov_b32_e32 v137, v44
	v_pk_mul_f32 v[108:109], v[194:195], s[84:85] op_sel_hi:[1,0]
	v_pk_mul_f32 v[106:107], v[192:193], s[84:85] op_sel_hi:[1,0]
	v_pk_fma_f32 v[108:109], v[132:133], v[148:149], v[108:109]
	v_pk_fma_f32 v[106:107], v[130:131], v[146:147], v[106:107]
	v_pk_mul_f32 v[132:133], v[222:223], s[84:85] op_sel_hi:[1,0]
	v_pk_mul_f32 v[130:131], v[220:221], s[84:85] op_sel_hi:[1,0]
	v_pk_fma_f32 v[104:105], v[104:105], v[144:145], v[132:133]
	v_pk_fma_f32 v[102:103], v[102:103], v[142:143], v[130:131]
	v_pk_mul_f32 v[130:131], v[224:225], s[84:85] op_sel_hi:[1,0]
	s_nop 0
	v_pk_fma_f32 v[82:83], v[82:83], v[138:139], v[130:131]
	v_mov_b32_e32 v138, v42
	v_mov_b32_e32 v139, v45
	v_pk_mul_f32 v[132:133], v[226:227], s[84:85] op_sel_hi:[1,0]
	v_pk_add_f32 v[136:137], v[136:137], v[138:139]
	v_pk_fma_f32 v[84:85], v[84:85], v[140:141], v[132:133]
	v_add_f32_e32 v133, v134, v135
	v_pk_add_f32 v[136:137], v[136:137], v[136:137] op_sel_hi:[0,1]
	v_add_f32_e32 v135, 0, v133
	v_add_f32_e32 v139, v34, v35
	v_add_f32_e32 v141, v36, v37
	v_mov_b32_e32 v138, v2
	v_mov_b32_e32 v140, v3
	v_mov_b32_e32 v136, v4
	v_mov_b32_e32 v134, v5
	v_lshl_add_u32 v132, v155, 4, v154
	v_pk_add_f32 v[138:139], v[138:139], v[140:141]
	v_pk_add_f32 v[134:135], v[136:137], v[134:135]
	v_lshlrev_b32_e32 v130, 2, v132
	v_pk_add_f32 v[134:135], v[138:139], v[134:135]
	v_xor_b32_e32 v131, 64, v130
	v_add_f32_e32 v133, v134, v135
	v_mov_b32_e32 v134, v133
	s_nop 1
	v_permlane16_swap_b32_e32 v134, v133
	v_xor_b32_e32 v130, 0x80, v130
	v_add_f32_e32 v133, v133, v134
	v_mov_b32_e32 v134, v133
	s_nop 1
	v_permlane32_swap_b32_e32 v134, v133
	v_add_f32_e32 v133, v133, v134
	v_fmamk_f32 v135, v133, 0xbc800000, v65
	v_fmamk_f32 v137, v133, 0xbc800000, v63
	v_fmamk_f32 v134, v133, 0xbc800000, v64
	v_fmamk_f32 v136, v133, 0xbc800000, v62
	v_mul_f32_e32 v137, v137, v137
	v_mul_f32_e32 v135, v135, v135
	v_fmac_f32_e32 v137, v136, v136
	v_fmac_f32_e32 v135, v134, v134
	v_fmamk_f32 v136, v133, 0xbc800000, v45
	v_fmamk_f32 v138, v133, 0xbc800000, v43
	v_add_f32_e32 v134, v137, v135
	v_fmamk_f32 v135, v133, 0xbc800000, v44
	v_fmamk_f32 v137, v133, 0xbc800000, v42
	v_mul_f32_e32 v138, v138, v138
	v_mul_f32_e32 v136, v136, v136
	v_fmac_f32_e32 v138, v137, v137
	v_fmac_f32_e32 v136, v135, v135
	v_add_f32_e32 v135, v138, v136
	v_fmamk_f32 v136, v133, 0xbc800000, v37
	v_fmamk_f32 v138, v133, 0xbc800000, v35
	v_add_f32_e32 v134, v134, v135
	v_fmamk_f32 v135, v133, 0xbc800000, v36
	v_fmamk_f32 v137, v133, 0xbc800000, v34
	v_mul_f32_e32 v138, v138, v138
	v_mul_f32_e32 v136, v136, v136
	v_fmac_f32_e32 v138, v137, v137
	v_fmac_f32_e32 v136, v135, v135
	v_add_f32_e32 v135, v138, v136
	v_fmamk_f32 v136, v133, 0xbc800000, v5
	v_fmamk_f32 v138, v133, 0xbc800000, v3
	v_add_f32_e32 v134, v135, v134
	v_fmamk_f32 v135, v133, 0xbc800000, v4
	v_fmamk_f32 v137, v133, 0xbc800000, v2
	v_mul_f32_e32 v138, v138, v138
	v_mul_f32_e32 v136, v136, v136
	v_fmac_f32_e32 v138, v137, v137
	v_fmac_f32_e32 v136, v135, v135
	v_add_f32_e32 v135, v138, v136
	v_add_f32_e32 v134, v135, v134
	v_mov_b32_e32 v135, v134
	s_nop 1
	v_permlane16_swap_b32_e32 v135, v134
	v_add_f32_e32 v134, v134, v135
	ds_bpermute_b32 v135, v130, v134
	s_and_saveexec_b64 s[2:3], vcc
	s_cbranch_execz .LBB0_1594
	s_lshl_b32 s22, s31, 11
	s_add_i32 s22, s14, s22
	v_mul_f32_e32 v136, 0x3c800000, v133
	s_waitcnt lgkmcnt(0)
	v_add_f32_e32 v137, v134, v135
	v_lshl_add_u32 v133, v154, 5, s22
	ds_write_b64 v133, v[136:137]
.LBB0_1594:
	s_or_b64 exec, exec, s[2:3]
	v_mov_b32_e32 v134, v19
	s_waitcnt lgkmcnt(0)
	v_mov_b32_e32 v135, v20
	v_mov_b32_e32 v136, v18
	v_mov_b32_e32 v137, v21
	v_pk_add_f32 v[134:135], v[134:135], v[136:137]
	v_mov_b32_e32 v136, v15
	v_mov_b32_e32 v137, v16
	v_mov_b32_e32 v138, v14
	v_mov_b32_e32 v139, v17
	v_pk_add_f32 v[136:137], v[136:137], v[138:139]
	v_add_f32_e32 v133, v134, v135
	v_pk_add_f32 v[136:137], v[136:137], v[136:137] op_sel_hi:[0,1]
	v_add_f32_e32 v135, 0, v133
	v_add_f32_e32 v139, v10, v11
	v_add_f32_e32 v141, v12, v13
	v_mov_b32_e32 v138, v6
	v_mov_b32_e32 v140, v7
	v_mov_b32_e32 v136, v8
	v_mov_b32_e32 v134, v9
	v_pk_add_f32 v[138:139], v[138:139], v[140:141]
	v_pk_add_f32 v[134:135], v[136:137], v[134:135]
	s_nop 0
	v_pk_add_f32 v[134:135], v[138:139], v[134:135]
	s_nop 0
	v_add_f32_e32 v133, v134, v135
	v_mov_b32_e32 v134, v133
	s_nop 1
	v_permlane16_swap_b32_e32 v134, v133
	v_add_f32_e32 v133, v133, v134
	v_mov_b32_e32 v134, v133
	s_nop 1
	v_permlane32_swap_b32_e32 v134, v133
	v_add_f32_e32 v133, v133, v134
	v_fmamk_f32 v135, v133, 0xbc800000, v21
	v_fmamk_f32 v137, v133, 0xbc800000, v19
	v_fmamk_f32 v134, v133, 0xbc800000, v20
	v_fmamk_f32 v136, v133, 0xbc800000, v18
	v_mul_f32_e32 v137, v137, v137
	v_mul_f32_e32 v135, v135, v135
	v_fmac_f32_e32 v137, v136, v136
	v_fmac_f32_e32 v135, v134, v134
	v_fmamk_f32 v136, v133, 0xbc800000, v17
	v_fmamk_f32 v138, v133, 0xbc800000, v15
	v_add_f32_e32 v134, v137, v135
	v_fmamk_f32 v135, v133, 0xbc800000, v16
	v_fmamk_f32 v137, v133, 0xbc800000, v14
	v_mul_f32_e32 v138, v138, v138
	v_mul_f32_e32 v136, v136, v136
	v_fmac_f32_e32 v138, v137, v137
	v_fmac_f32_e32 v136, v135, v135
	v_add_f32_e32 v135, v138, v136
	v_fmamk_f32 v136, v133, 0xbc800000, v13
	v_fmamk_f32 v138, v133, 0xbc800000, v11
	v_add_f32_e32 v134, v134, v135
	v_fmamk_f32 v135, v133, 0xbc800000, v12
	v_fmamk_f32 v137, v133, 0xbc800000, v10
	v_mul_f32_e32 v138, v138, v138
	v_mul_f32_e32 v136, v136, v136
	v_fmac_f32_e32 v138, v137, v137
	v_fmac_f32_e32 v136, v135, v135
	v_add_f32_e32 v135, v138, v136
	v_fmamk_f32 v136, v133, 0xbc800000, v9
	v_fmamk_f32 v138, v133, 0xbc800000, v7
	v_add_f32_e32 v134, v135, v134
	v_fmamk_f32 v135, v133, 0xbc800000, v8
	v_fmamk_f32 v137, v133, 0xbc800000, v6
	v_mul_f32_e32 v138, v138, v138
	v_mul_f32_e32 v136, v136, v136
	v_fmac_f32_e32 v138, v137, v137
	v_fmac_f32_e32 v136, v135, v135
	v_add_f32_e32 v135, v138, v136
	v_add_f32_e32 v134, v135, v134
	v_mov_b32_e32 v135, v134
	s_nop 1
	v_permlane16_swap_b32_e32 v135, v134
	v_add_f32_e32 v134, v134, v135
	ds_bpermute_b32 v135, v130, v134
	s_and_saveexec_b64 s[2:3], vcc
	s_load_dwordx2 s[90:91], s[0:1], 0xe0
	v_readlane_b32 s85, v255, 37
	s_movk_i32 s35, 0x2000
	s_cbranch_execz .LBB0_1596
	s_lshl_b32 s22, s31, 11
	s_add_i32 s22, s14, s22
	v_mul_f32_e32 v136, 0x3c800000, v133
	s_waitcnt lgkmcnt(0)
	v_add_f32_e32 v137, v134, v135
	v_lshl_add_u32 v133, v154, 5, s22
	ds_write_b64 v133, v[136:137] offset:512
; __device__ __forceinline__ float shx(float v, int mask, int lane) { return __int_as_float(__builtin_amdgcn_ds_bpermute((lane ^ mask) << 2, __float_as_int(v))); }
;     __device__ __forceinline__ void run(const Acc& v, const Unit& u, int wr, int wc, int fr, int fq, LAS unsigned char* sl, int wid, int lane) const {
;     ...
;                 float sm = 0.f;
; #pragma unroll
;                 for (int bj = 0; bj < 2; ++bj)
; #pragma unroll
;                     for (int n = 0; n < 2; ++n) { const f32x4 x = v[ai][bj][m][n]; sm += (x[0] + x[1]) + (x[2] + x[3]); }
;                 sm += shx(sm, 16, lane); sm += shx(sm, 32, lane);
;                 const float mw = sm * (1.0f / 64.0f); float q = 0.f;
; #pragma unroll
;                 for (int bj = 0; bj < 2; ++bj)
; #pragma unroll
;                     for (int n = 0; n < 2; ++n) { const f32x4 d = v[ai][bj][m][n] - mw; q += (d[0] * d[0] + d[1] * d[1]) + (d[2] * d[2] + d[3] * d[3]); }
;                 q += shx(q, 16, lane); q += shx(q, 32, lane);
;                 if (fq == 0) P[(ai * 128 + wr * 64 + m * 16 + fr) * 4 + wc] = (f32x2){mw, q};
.LBB0_1596:
	s_or_b64 exec, exec, s[2:3]
	v_mov_b32_e32 v134, v39
	s_waitcnt lgkmcnt(0)
	v_mov_b32_e32 v135, v40
	v_mov_b32_e32 v136, v38
	v_mov_b32_e32 v137, v41
	v_pk_add_f32 v[134:135], v[134:135], v[136:137]
	v_mov_b32_e32 v136, v31
	v_mov_b32_e32 v137, v32
	v_mov_b32_e32 v138, v30
	v_mov_b32_e32 v139, v33
	v_pk_add_f32 v[136:137], v[136:137], v[138:139]
	v_add_f32_e32 v133, v134, v135
	v_pk_add_f32 v[136:137], v[136:137], v[136:137] op_sel_hi:[0,1]
	v_add_f32_e32 v135, 0, v133
	v_add_f32_e32 v139, v26, v27
	v_add_f32_e32 v141, v28, v29
	v_mov_b32_e32 v138, v22
	v_mov_b32_e32 v140, v23
	v_mov_b32_e32 v136, v24
	v_mov_b32_e32 v134, v25
	v_pk_add_f32 v[138:139], v[138:139], v[140:141]
	v_pk_add_f32 v[134:135], v[136:137], v[134:135]
	s_nop 0
	v_pk_add_f32 v[134:135], v[138:139], v[134:135]
	s_nop 0
	v_add_f32_e32 v133, v134, v135
	v_mov_b32_e32 v134, v133
	s_nop 1
	v_permlane16_swap_b32_e32 v134, v133
	v_add_f32_e32 v133, v133, v134
	v_mov_b32_e32 v134, v133
	s_nop 1
	v_permlane32_swap_b32_e32 v134, v133
	v_add_f32_e32 v133, v133, v134
	v_fmamk_f32 v135, v133, 0xbc800000, v41
	v_fmamk_f32 v137, v133, 0xbc800000, v39
	v_fmamk_f32 v134, v133, 0xbc800000, v40
	v_fmamk_f32 v136, v133, 0xbc800000, v38
	v_mul_f32_e32 v137, v137, v137
	v_mul_f32_e32 v135, v135, v135
	v_fmac_f32_e32 v137, v136, v136
	v_fmac_f32_e32 v135, v134, v134
	v_fmamk_f32 v136, v133, 0xbc800000, v33
	v_fmamk_f32 v138, v133, 0xbc800000, v31
	v_add_f32_e32 v134, v137, v135
	v_fmamk_f32 v135, v133, 0xbc800000, v32
	v_fmamk_f32 v137, v133, 0xbc800000, v30
	v_mul_f32_e32 v138, v138, v138
	v_mul_f32_e32 v136, v136, v136
	v_fmac_f32_e32 v138, v137, v137
	v_fmac_f32_e32 v136, v135, v135
	v_add_f32_e32 v135, v138, v136
	v_fmamk_f32 v136, v133, 0xbc800000, v29
	v_fmamk_f32 v138, v133, 0xbc800000, v27
	v_add_f32_e32 v134, v134, v135
	v_fmamk_f32 v135, v133, 0xbc800000, v28
	v_fmamk_f32 v137, v133, 0xbc800000, v26
	v_mul_f32_e32 v138, v138, v138
	v_mul_f32_e32 v136, v136, v136
	v_fmac_f32_e32 v138, v137, v137
	v_fmac_f32_e32 v136, v135, v135
	v_add_f32_e32 v135, v138, v136
	v_fmamk_f32 v136, v133, 0xbc800000, v25
	v_fmamk_f32 v138, v133, 0xbc800000, v23
	v_add_f32_e32 v134, v135, v134
	v_fmamk_f32 v135, v133, 0xbc800000, v24
	v_fmamk_f32 v137, v133, 0xbc800000, v22
	v_mul_f32_e32 v138, v138, v138
	v_mul_f32_e32 v136, v136, v136
	v_fmac_f32_e32 v138, v137, v137
	v_fmac_f32_e32 v136, v135, v135
	v_add_f32_e32 v135, v138, v136
	v_add_f32_e32 v134, v135, v134
	v_mov_b32_e32 v135, v134
	s_nop 1
	v_permlane16_swap_b32_e32 v135, v134
	v_add_f32_e32 v134, v134, v135
	ds_bpermute_b32 v135, v130, v134
	s_and_saveexec_b64 s[2:3], vcc
	s_cbranch_execz .LBB0_1598
	s_lshl_b32 s22, s31, 11
	s_add_i32 s22, s14, s22
	v_mul_f32_e32 v136, 0x3c800000, v133
	s_waitcnt lgkmcnt(0)
	v_add_f32_e32 v137, v134, v135
	v_lshl_add_u32 v133, v154, 5, s22
	ds_write_b64 v133, v[136:137] offset:1024
.LBB0_1598:
	s_or_b64 exec, exec, s[2:3]
	v_mov_b32_e32 v134, v59
	s_waitcnt lgkmcnt(0)
	v_mov_b32_e32 v135, v60
	v_mov_b32_e32 v136, v58
	v_mov_b32_e32 v137, v61
	v_pk_add_f32 v[134:135], v[134:135], v[136:137]
	v_mov_b32_e32 v136, v55
	v_mov_b32_e32 v137, v56
	v_mov_b32_e32 v138, v54
	v_mov_b32_e32 v139, v57
	v_pk_add_f32 v[136:137], v[136:137], v[138:139]
	v_add_f32_e32 v133, v134, v135
	v_pk_add_f32 v[136:137], v[136:137], v[136:137] op_sel_hi:[0,1]
	v_add_f32_e32 v135, 0, v133
	v_add_f32_e32 v139, v50, v51
	v_add_f32_e32 v141, v52, v53
	v_mov_b32_e32 v138, v46
	v_mov_b32_e32 v140, v47
	v_mov_b32_e32 v136, v48
	v_mov_b32_e32 v134, v49
	v_pk_add_f32 v[138:139], v[138:139], v[140:141]
	v_pk_add_f32 v[134:135], v[136:137], v[134:135]
	s_nop 0
	v_pk_add_f32 v[134:135], v[138:139], v[134:135]
	s_nop 0
	v_add_f32_e32 v133, v134, v135
	v_mov_b32_e32 v134, v133
	s_nop 1
	v_permlane16_swap_b32_e32 v134, v133
	v_add_f32_e32 v133, v133, v134
	v_mov_b32_e32 v134, v133
	s_nop 1
	v_permlane32_swap_b32_e32 v134, v133
	v_add_f32_e32 v133, v133, v134
	v_fmamk_f32 v135, v133, 0xbc800000, v61
	v_fmamk_f32 v137, v133, 0xbc800000, v59
	v_fmamk_f32 v134, v133, 0xbc800000, v60
	v_fmamk_f32 v136, v133, 0xbc800000, v58
	v_mul_f32_e32 v137, v137, v137
	v_mul_f32_e32 v135, v135, v135
	v_fmac_f32_e32 v137, v136, v136
	v_fmac_f32_e32 v135, v134, v134
	v_fmamk_f32 v136, v133, 0xbc800000, v57
	v_fmamk_f32 v138, v133, 0xbc800000, v55
	v_add_f32_e32 v134, v137, v135
	v_fmamk_f32 v135, v133, 0xbc800000, v56
	v_fmamk_f32 v137, v133, 0xbc800000, v54
	v_mul_f32_e32 v138, v138, v138
	v_mul_f32_e32 v136, v136, v136
	v_fmac_f32_e32 v138, v137, v137
	v_fmac_f32_e32 v136, v135, v135
	v_add_f32_e32 v135, v138, v136
	v_fmamk_f32 v136, v133, 0xbc800000, v53
	v_fmamk_f32 v138, v133, 0xbc800000, v51
	v_add_f32_e32 v134, v134, v135
	v_fmamk_f32 v135, v133, 0xbc800000, v52
	v_fmamk_f32 v137, v133, 0xbc800000, v50
	v_mul_f32_e32 v138, v138, v138
	v_mul_f32_e32 v136, v136, v136
	v_fmac_f32_e32 v138, v137, v137
	v_fmac_f32_e32 v136, v135, v135
	v_add_f32_e32 v135, v138, v136
	v_fmamk_f32 v136, v133, 0xbc800000, v49
	v_fmamk_f32 v138, v133, 0xbc800000, v47
	v_add_f32_e32 v134, v135, v134
	v_fmamk_f32 v135, v133, 0xbc800000, v48
	v_fmamk_f32 v137, v133, 0xbc800000, v46
	v_mul_f32_e32 v138, v138, v138
	v_mul_f32_e32 v136, v136, v136
	v_fmac_f32_e32 v138, v137, v137
	v_fmac_f32_e32 v136, v135, v135
	v_add_f32_e32 v135, v138, v136
	v_add_f32_e32 v134, v135, v134
	v_mov_b32_e32 v135, v134
	s_nop 1
	v_permlane16_swap_b32_e32 v135, v134
	v_add_f32_e32 v134, v134, v135
	ds_bpermute_b32 v135, v130, v134
	s_and_saveexec_b64 s[2:3], vcc
	s_cbranch_execz .LBB0_1600
	s_lshl_b32 s22, s31, 11
	s_add_i32 s22, s14, s22
	v_mul_f32_e32 v136, 0x3c800000, v133
	s_waitcnt lgkmcnt(0)
	v_add_f32_e32 v137, v134, v135
	v_lshl_add_u32 v133, v154, 5, s22
	ds_write_b64 v133, v[136:137] offset:1536
; __device__ __forceinline__ float shx(float v, int mask, int lane) { return __int_as_float(__builtin_amdgcn_ds_bpermute((lane ^ mask) << 2, __float_as_int(v))); }
;     __device__ __forceinline__ void run(const Acc& v, const Unit& u, int wr, int wc, int fr, int fq, LAS unsigned char* sl, int wid, int lane) const {
;     ...
;                 float sm = 0.f;
; #pragma unroll
;                 for (int bj = 0; bj < 2; ++bj)
; #pragma unroll
;                     for (int n = 0; n < 2; ++n) { const f32x4 x = v[ai][bj][m][n]; sm += (x[0] + x[1]) + (x[2] + x[3]); }
;                 sm += shx(sm, 16, lane); sm += shx(sm, 32, lane);
;                 const float mw = sm * (1.0f / 64.0f); float q = 0.f;
; #pragma unroll
;                 for (int bj = 0; bj < 2; ++bj)
; #pragma unroll
;                     for (int n = 0; n < 2; ++n) { const f32x4 d = v[ai][bj][m][n] - mw; q += (d[0] * d[0] + d[1] * d[1]) + (d[2] * d[2] + d[3] * d[3]); }
;                 q += shx(q, 16, lane); q += shx(q, 32, lane);
;                 if (fq == 0) P[(ai * 128 + wr * 64 + m * 16 + fr) * 4 + wc] = (f32x2){mw, q};
.LBB0_1600:
	s_or_b64 exec, exec, s[2:3]
	v_mov_b32_e32 v134, v79
	s_waitcnt lgkmcnt(0)
	v_mov_b32_e32 v135, v80
	v_mov_b32_e32 v136, v78
	v_mov_b32_e32 v137, v81
	v_pk_add_f32 v[134:135], v[134:135], v[136:137]
	v_mov_b32_e32 v136, v75
	v_mov_b32_e32 v137, v76
	v_mov_b32_e32 v138, v74
	v_mov_b32_e32 v139, v77
	v_pk_add_f32 v[136:137], v[136:137], v[138:139]
	v_add_f32_e32 v133, v134, v135
	v_pk_add_f32 v[136:137], v[136:137], v[136:137] op_sel_hi:[0,1]
	v_add_f32_e32 v135, 0, v133
	v_add_f32_e32 v139, v70, v71
	v_add_f32_e32 v141, v72, v73
	v_mov_b32_e32 v138, v66
	v_mov_b32_e32 v140, v67
	v_mov_b32_e32 v136, v68
	v_mov_b32_e32 v134, v69
	v_pk_add_f32 v[138:139], v[138:139], v[140:141]
	v_pk_add_f32 v[134:135], v[136:137], v[134:135]
	s_nop 0
	v_pk_add_f32 v[134:135], v[138:139], v[134:135]
	s_nop 0
	v_add_f32_e32 v133, v134, v135
	v_mov_b32_e32 v134, v133
	s_nop 1
	v_permlane16_swap_b32_e32 v134, v133
	v_add_f32_e32 v133, v133, v134
	v_mov_b32_e32 v134, v133
	s_nop 1
	v_permlane32_swap_b32_e32 v134, v133
	v_add_f32_e32 v133, v133, v134
	v_fmamk_f32 v135, v133, 0xbc800000, v81
	v_fmamk_f32 v137, v133, 0xbc800000, v79
	v_fmamk_f32 v134, v133, 0xbc800000, v80
	v_fmamk_f32 v136, v133, 0xbc800000, v78
	v_mul_f32_e32 v137, v137, v137
	v_mul_f32_e32 v135, v135, v135
	v_fmac_f32_e32 v137, v136, v136
	v_fmac_f32_e32 v135, v134, v134
	v_fmamk_f32 v136, v133, 0xbc800000, v77
	v_fmamk_f32 v138, v133, 0xbc800000, v75
	v_add_f32_e32 v134, v137, v135
	v_fmamk_f32 v135, v133, 0xbc800000, v76
	v_fmamk_f32 v137, v133, 0xbc800000, v74
	v_mul_f32_e32 v138, v138, v138
	v_mul_f32_e32 v136, v136, v136
	v_fmac_f32_e32 v138, v137, v137
	v_fmac_f32_e32 v136, v135, v135
	v_add_f32_e32 v135, v138, v136
	v_fmamk_f32 v136, v133, 0xbc800000, v73
	v_fmamk_f32 v138, v133, 0xbc800000, v71
	v_add_f32_e32 v134, v134, v135
	v_fmamk_f32 v135, v133, 0xbc800000, v72
	v_fmamk_f32 v137, v133, 0xbc800000, v70
	v_mul_f32_e32 v138, v138, v138
	v_mul_f32_e32 v136, v136, v136
	v_fmac_f32_e32 v138, v137, v137
	v_fmac_f32_e32 v136, v135, v135
	v_add_f32_e32 v135, v138, v136
	v_fmamk_f32 v136, v133, 0xbc800000, v69
	v_fmamk_f32 v138, v133, 0xbc800000, v67
	v_add_f32_e32 v134, v135, v134
	v_fmamk_f32 v135, v133, 0xbc800000, v68
	v_fmamk_f32 v137, v133, 0xbc800000, v66
	v_mul_f32_e32 v138, v138, v138
	v_mul_f32_e32 v136, v136, v136
	v_fmac_f32_e32 v138, v137, v137
	v_fmac_f32_e32 v136, v135, v135
	v_add_f32_e32 v135, v138, v136
	v_add_f32_e32 v134, v135, v134
	v_mov_b32_e32 v135, v134
	s_nop 1
	v_permlane16_swap_b32_e32 v135, v134
	v_add_f32_e32 v134, v134, v135
	ds_bpermute_b32 v135, v130, v134
	s_and_saveexec_b64 s[2:3], vcc
	s_cbranch_execz .LBB0_1602
	s_lshl_b32 s22, s31, 11
	s_add_i32 s22, s14, s22
	v_mul_f32_e32 v136, 0x3c800000, v133
	s_waitcnt lgkmcnt(0)
	v_add_f32_e32 v137, v134, v135
	v_lshl_add_u32 v133, v154, 5, s22
	ds_write_b64 v133, v[136:137] offset:4096
.LBB0_1602:
	s_or_b64 exec, exec, s[2:3]
	v_mov_b32_e32 v134, v99
	s_waitcnt lgkmcnt(0)
	v_mov_b32_e32 v135, v100
	v_mov_b32_e32 v136, v98
	v_mov_b32_e32 v137, v101
	v_pk_add_f32 v[134:135], v[134:135], v[136:137]
	v_mov_b32_e32 v136, v95
	v_mov_b32_e32 v137, v96
	v_mov_b32_e32 v138, v94
	v_mov_b32_e32 v139, v97
	v_pk_add_f32 v[136:137], v[136:137], v[138:139]
	v_add_f32_e32 v133, v134, v135
	v_pk_add_f32 v[136:137], v[136:137], v[136:137] op_sel_hi:[0,1]
	v_add_f32_e32 v135, 0, v133
	v_add_f32_e32 v139, v90, v91
	v_add_f32_e32 v141, v92, v93
	v_mov_b32_e32 v138, v86
	v_mov_b32_e32 v140, v87
	v_mov_b32_e32 v136, v88
	v_mov_b32_e32 v134, v89
	v_pk_add_f32 v[138:139], v[138:139], v[140:141]
	v_pk_add_f32 v[134:135], v[136:137], v[134:135]
	s_nop 0
	v_pk_add_f32 v[134:135], v[138:139], v[134:135]
	s_nop 0
	v_add_f32_e32 v133, v134, v135
	v_mov_b32_e32 v134, v133
	s_nop 1
	v_permlane16_swap_b32_e32 v134, v133
	v_add_f32_e32 v133, v133, v134
	v_mov_b32_e32 v134, v133
	s_nop 1
	v_permlane32_swap_b32_e32 v134, v133
	v_add_f32_e32 v133, v133, v134
	v_fmamk_f32 v135, v133, 0xbc800000, v101
	v_fmamk_f32 v137, v133, 0xbc800000, v99
	v_fmamk_f32 v134, v133, 0xbc800000, v100
	v_fmamk_f32 v136, v133, 0xbc800000, v98
	v_mul_f32_e32 v137, v137, v137
	v_mul_f32_e32 v135, v135, v135
	v_fmac_f32_e32 v137, v136, v136
	v_fmac_f32_e32 v135, v134, v134
	v_fmamk_f32 v136, v133, 0xbc800000, v97
	v_fmamk_f32 v138, v133, 0xbc800000, v95
	v_add_f32_e32 v134, v137, v135
	v_fmamk_f32 v135, v133, 0xbc800000, v96
	v_fmamk_f32 v137, v133, 0xbc800000, v94
	v_mul_f32_e32 v138, v138, v138
	v_mul_f32_e32 v136, v136, v136
	v_fmac_f32_e32 v138, v137, v137
	v_fmac_f32_e32 v136, v135, v135
	v_add_f32_e32 v135, v138, v136
	v_fmamk_f32 v136, v133, 0xbc800000, v93
	v_fmamk_f32 v138, v133, 0xbc800000, v91
	v_add_f32_e32 v134, v134, v135
	v_fmamk_f32 v135, v133, 0xbc800000, v92
	v_fmamk_f32 v137, v133, 0xbc800000, v90
	v_mul_f32_e32 v138, v138, v138
	v_mul_f32_e32 v136, v136, v136
	v_fmac_f32_e32 v138, v137, v137
	v_fmac_f32_e32 v136, v135, v135
	v_add_f32_e32 v135, v138, v136
	v_fmamk_f32 v136, v133, 0xbc800000, v89
	v_fmamk_f32 v138, v133, 0xbc800000, v87
	v_add_f32_e32 v134, v135, v134
	v_fmamk_f32 v135, v133, 0xbc800000, v88
	v_fmamk_f32 v137, v133, 0xbc800000, v86
	v_mul_f32_e32 v138, v138, v138
	v_mul_f32_e32 v136, v136, v136
	v_fmac_f32_e32 v138, v137, v137
	v_fmac_f32_e32 v136, v135, v135
	v_add_f32_e32 v135, v138, v136
	v_add_f32_e32 v134, v135, v134
	v_mov_b32_e32 v135, v134
	s_nop 1
	v_permlane16_swap_b32_e32 v135, v134
	v_add_f32_e32 v134, v134, v135
	ds_bpermute_b32 v135, v130, v134
	s_and_saveexec_b64 s[2:3], vcc
	s_cbranch_execz .LBB0_1604
	s_lshl_b32 s22, s31, 11
	s_add_i32 s22, s14, s22
	v_mul_f32_e32 v136, 0x3c800000, v133
	s_waitcnt lgkmcnt(0)
	v_add_f32_e32 v137, v134, v135
	v_lshl_add_u32 v133, v154, 5, s22
	ds_write_b64 v133, v[136:137] offset:4608
; __device__ __forceinline__ float shx(float v, int mask, int lane) { return __int_as_float(__builtin_amdgcn_ds_bpermute((lane ^ mask) << 2, __float_as_int(v))); }
;     __device__ __forceinline__ void run(const Acc& v, const Unit& u, int wr, int wc, int fr, int fq, LAS unsigned char* sl, int wid, int lane) const {
;     ...
;                 float sm = 0.f;
; #pragma unroll
;                 for (int bj = 0; bj < 2; ++bj)
; #pragma unroll
;                     for (int n = 0; n < 2; ++n) { const f32x4 x = v[ai][bj][m][n]; sm += (x[0] + x[1]) + (x[2] + x[3]); }
;                 sm += shx(sm, 16, lane); sm += shx(sm, 32, lane);
;                 const float mw = sm * (1.0f / 64.0f); float q = 0.f;
; #pragma unroll
;                 for (int bj = 0; bj < 2; ++bj)
; #pragma unroll
;                     for (int n = 0; n < 2; ++n) { const f32x4 d = v[ai][bj][m][n] - mw; q += (d[0] * d[0] + d[1] * d[1]) + (d[2] * d[2] + d[3] * d[3]); }
;                 q += shx(q, 16, lane); q += shx(q, 32, lane);
;                 if (fq == 0) P[(ai * 128 + wr * 64 + m * 16 + fr) * 4 + wc] = (f32x2){mw, q};
.LBB0_1604:
	s_or_b64 exec, exec, s[2:3]
	v_mov_b32_e32 v134, v127
	s_waitcnt lgkmcnt(0)
	v_mov_b32_e32 v135, v128
	v_mov_b32_e32 v136, v126
	v_mov_b32_e32 v137, v129
	v_pk_add_f32 v[134:135], v[134:135], v[136:137]
	v_mov_b32_e32 v136, v123
	v_mov_b32_e32 v137, v124
	v_mov_b32_e32 v138, v122
	v_mov_b32_e32 v139, v125
	v_pk_add_f32 v[136:137], v[136:137], v[138:139]
	v_add_f32_e32 v133, v134, v135
	v_pk_add_f32 v[136:137], v[136:137], v[136:137] op_sel_hi:[0,1]
	v_add_f32_e32 v135, 0, v133
	v_add_f32_e32 v139, v118, v119
	v_add_f32_e32 v141, v120, v121
	v_mov_b32_e32 v138, v114
	v_mov_b32_e32 v140, v115
	v_mov_b32_e32 v136, v116
	v_mov_b32_e32 v134, v117
	v_pk_add_f32 v[138:139], v[138:139], v[140:141]
	v_pk_add_f32 v[134:135], v[136:137], v[134:135]
	s_nop 0
	v_pk_add_f32 v[134:135], v[138:139], v[134:135]
	s_nop 0
	v_add_f32_e32 v133, v134, v135
	v_mov_b32_e32 v134, v133
	s_nop 1
	v_permlane16_swap_b32_e32 v134, v133
	v_add_f32_e32 v133, v133, v134
	v_mov_b32_e32 v134, v133
	s_nop 1
	v_permlane32_swap_b32_e32 v134, v133
	v_add_f32_e32 v133, v133, v134
	v_fmamk_f32 v135, v133, 0xbc800000, v129
	v_fmamk_f32 v137, v133, 0xbc800000, v127
	v_fmamk_f32 v134, v133, 0xbc800000, v128
	v_fmamk_f32 v136, v133, 0xbc800000, v126
	v_mul_f32_e32 v137, v137, v137
	v_mul_f32_e32 v135, v135, v135
	v_fmac_f32_e32 v137, v136, v136
	v_fmac_f32_e32 v135, v134, v134
	v_fmamk_f32 v136, v133, 0xbc800000, v125
	v_fmamk_f32 v138, v133, 0xbc800000, v123
	v_add_f32_e32 v134, v137, v135
	v_fmamk_f32 v135, v133, 0xbc800000, v124
	v_fmamk_f32 v137, v133, 0xbc800000, v122
	v_mul_f32_e32 v138, v138, v138
	v_mul_f32_e32 v136, v136, v136
	v_fmac_f32_e32 v138, v137, v137
	v_fmac_f32_e32 v136, v135, v135
	v_add_f32_e32 v135, v138, v136
	v_fmamk_f32 v136, v133, 0xbc800000, v121
	v_fmamk_f32 v138, v133, 0xbc800000, v119
	v_add_f32_e32 v134, v134, v135
	v_fmamk_f32 v135, v133, 0xbc800000, v120
	v_fmamk_f32 v137, v133, 0xbc800000, v118
	v_mul_f32_e32 v138, v138, v138
	v_mul_f32_e32 v136, v136, v136
	v_fmac_f32_e32 v138, v137, v137
	v_fmac_f32_e32 v136, v135, v135
	v_add_f32_e32 v135, v138, v136
	v_fmamk_f32 v136, v133, 0xbc800000, v117
	v_fmamk_f32 v138, v133, 0xbc800000, v115
	v_add_f32_e32 v134, v135, v134
	v_fmamk_f32 v135, v133, 0xbc800000, v116
	v_fmamk_f32 v137, v133, 0xbc800000, v114
	v_mul_f32_e32 v138, v138, v138
	v_mul_f32_e32 v136, v136, v136
	v_fmac_f32_e32 v138, v137, v137
	v_fmac_f32_e32 v136, v135, v135
	v_add_f32_e32 v135, v138, v136
	v_add_f32_e32 v134, v135, v134
	v_mov_b32_e32 v135, v134
	s_nop 1
	v_permlane16_swap_b32_e32 v135, v134
	v_add_f32_e32 v134, v134, v135
	ds_bpermute_b32 v135, v130, v134
	s_and_saveexec_b64 s[2:3], vcc
	s_cbranch_execz .LBB0_1606
	s_lshl_b32 s22, s31, 11
	s_add_i32 s22, s14, s22
	v_mul_f32_e32 v136, 0x3c800000, v133
	s_waitcnt lgkmcnt(0)
	v_add_f32_e32 v137, v134, v135
	v_lshl_add_u32 v133, v154, 5, s22
	ds_write_b64 v133, v[136:137] offset:5120
.LBB0_1606:
	s_or_b64 exec, exec, s[2:3]
	v_mov_b32_e32 v134, v111
	s_waitcnt lgkmcnt(0)
	v_mov_b32_e32 v135, v112
	v_mov_b32_e32 v136, v110
	v_mov_b32_e32 v137, v113
	v_pk_add_f32 v[134:135], v[134:135], v[136:137]
	v_mov_b32_e32 v136, v107
	v_mov_b32_e32 v137, v108
	v_mov_b32_e32 v138, v106
	v_mov_b32_e32 v139, v109
	v_pk_add_f32 v[136:137], v[136:137], v[138:139]
	v_add_f32_e32 v133, v134, v135
	v_pk_add_f32 v[136:137], v[136:137], v[136:137] op_sel_hi:[0,1]
	v_add_f32_e32 v135, 0, v133
	v_add_f32_e32 v139, v102, v103
	v_add_f32_e32 v141, v104, v105
	v_mov_b32_e32 v138, v82
	v_mov_b32_e32 v140, v83
	v_mov_b32_e32 v136, v84
	v_mov_b32_e32 v134, v85
	v_pk_add_f32 v[138:139], v[138:139], v[140:141]
	v_pk_add_f32 v[134:135], v[136:137], v[134:135]
	s_nop 0
	v_pk_add_f32 v[134:135], v[138:139], v[134:135]
	s_nop 0
	v_add_f32_e32 v133, v134, v135
	v_mov_b32_e32 v134, v133
	s_nop 1
	v_permlane16_swap_b32_e32 v134, v133
	v_add_f32_e32 v133, v133, v134
	v_mov_b32_e32 v134, v133
	s_nop 1
	v_permlane32_swap_b32_e32 v134, v133
	v_add_f32_e32 v133, v133, v134
	v_fmamk_f32 v135, v133, 0xbc800000, v113
	v_fmamk_f32 v137, v133, 0xbc800000, v111
	v_fmamk_f32 v134, v133, 0xbc800000, v112
	v_fmamk_f32 v136, v133, 0xbc800000, v110
	v_mul_f32_e32 v137, v137, v137
	v_mul_f32_e32 v135, v135, v135
	v_fmac_f32_e32 v137, v136, v136
	v_fmac_f32_e32 v135, v134, v134
	v_fmamk_f32 v136, v133, 0xbc800000, v109
	v_fmamk_f32 v138, v133, 0xbc800000, v107
	v_add_f32_e32 v134, v137, v135
	v_fmamk_f32 v135, v133, 0xbc800000, v108
	v_fmamk_f32 v137, v133, 0xbc800000, v106
	v_mul_f32_e32 v138, v138, v138
	v_mul_f32_e32 v136, v136, v136
	v_fmac_f32_e32 v138, v137, v137
	v_fmac_f32_e32 v136, v135, v135
	v_add_f32_e32 v135, v138, v136
	v_fmamk_f32 v136, v133, 0xbc800000, v105
	v_fmamk_f32 v138, v133, 0xbc800000, v103
	v_add_f32_e32 v134, v134, v135
	v_fmamk_f32 v135, v133, 0xbc800000, v104
	v_fmamk_f32 v137, v133, 0xbc800000, v102
	v_mul_f32_e32 v138, v138, v138
	v_mul_f32_e32 v136, v136, v136
	v_fmac_f32_e32 v138, v137, v137
	v_fmac_f32_e32 v136, v135, v135
	v_add_f32_e32 v135, v138, v136
	v_fmamk_f32 v136, v133, 0xbc800000, v85
	v_fmamk_f32 v138, v133, 0xbc800000, v83
	v_add_f32_e32 v134, v135, v134
	v_fmamk_f32 v135, v133, 0xbc800000, v84
	v_fmamk_f32 v137, v133, 0xbc800000, v82
	v_mul_f32_e32 v138, v138, v138
	v_mul_f32_e32 v136, v136, v136
	v_fmac_f32_e32 v138, v137, v137
	v_fmac_f32_e32 v136, v135, v135
	v_add_f32_e32 v135, v138, v136
	v_add_f32_e32 v134, v135, v134
	ds_bpermute_b32 v131, v131, v134
	s_waitcnt lgkmcnt(0)
	v_add_f32_e32 v131, v134, v131
	ds_bpermute_b32 v130, v130, v131
	s_and_saveexec_b64 s[2:3], vcc
	s_cbranch_execz .LBB0_1608
	s_lshl_b32 s22, s31, 11
	s_add_i32 s14, s14, s22
	v_mul_f32_e32 v134, 0x3c800000, v133
	s_waitcnt lgkmcnt(0)
	v_add_f32_e32 v135, v131, v130
	v_lshl_add_u32 v130, v154, 5, s14
	ds_write_b64 v130, v[134:135] offset:5632

; #define EPI_ROWS(ai, m) _Pragma("unroll") for (int ai = 0; ai < 2; ++ai) _Pragma("unroll") for (int m = 0; m < 4; ++m)
; #define EPI_COLS(bj, n) _Pragma("unroll") for (int bj = 0; bj < 2; ++bj) _Pragma("unroll") for (int n = 0; n < 2; ++n)
;     __device__ __forceinline__ void fused(Acc& acc, const Unit& u, int wr, int wc, int fr, int fq) const {
;         const int colb = u.pn * 256 + wc * 32 + fq * 4;
;         f32x4 gv[2][2];
;         { const float* gp = gate + (size_t)((u.pm * 256) >> 11) * MODW + colb;
;           EPI_COLS(bj, n) gv[bj][n] = *(const f32x4*)(gp + bj * 128 + n * 16); }
;         EPI_ROWS(ai, m) { const int row = u.pm * 256 + ai * 128 + wr * 64 + m * 16 + fr; const float* hp = H + (size_t)row * D + colb;
;             EPI_COLS(bj, n) { const int co = bj * 128 + n * 16; acc[ai][bj][m][n] = *(const f32x4*)(hp + co) * ALPHA + gv[bj][n] * acc[ai][bj][m][n]; }
;             asm volatile("" : "+v"(acc[ai][0][m][0]), "+v"(acc[ai][0][m][1]), "+v"(acc[ai][1][m][0]), "+v"(acc[ai][1][m][1]));
;             if (m == 3) asm volatile("" ::: "memory"); }
.LBB0_1669:
	s_waitcnt vmcnt(0)
	s_barrier
	s_lshl_b32 s2, s4, 8
	s_lshl_b32 s3, s31, 5
	s_add_i32 s3, s3, s2
	s_ashr_i32 s2, s30, 3
	s_mul_i32 s46, s2, 0xc000
	s_mul_hi_i32 s24, s2, 0xc000
	s_add_u32 s2, s60, s46
	v_lshl_add_u32 v190, v155, 2, s3
	s_addc_u32 s3, s61, s24
	s_lshl_b32 s38, s30, 8
	v_lshl_add_u32 v0, s5, 6, v154
	v_ashrrev_i32_e32 v191, 31, v190
	v_add_u32_e32 v200, s38, v0
	v_lshlrev_b64 v[178:179], 2, v[190:191]
	v_ashrrev_i32_e32 v201, 31, v200
	v_lshl_add_u64 v[122:123], s[2:3], 0, v[178:179]
	v_lshlrev_b64 v[206:207], 13, v[200:201]
	global_load_dwordx4 v[150:153], v[122:123], off
	global_load_dwordx4 v[146:149], v[122:123], off offset:64
	global_load_dwordx4 v[142:145], v[122:123], off offset:512
	global_load_dwordx4 v[138:141], v[122:123], off offset:576
	v_add_u32_e32 v180, 16, v200
	v_ashrrev_i32_e32 v181, 31, v180
	v_lshlrev_b64 v[182:183], 13, v[180:181]
	v_add_u32_e32 v184, 32, v200
	v_ashrrev_i32_e32 v185, 31, v184
	v_lshlrev_b64 v[186:187], 13, v[184:185]
	v_add_u32_e32 v188, 48, v200
	v_ashrrev_i32_e32 v189, 31, v188
	v_lshlrev_b64 v[198:199], 13, v[188:189]
	v_add_u32_e32 v202, 0x80, v200
	v_ashrrev_i32_e32 v203, 31, v202
	v_lshlrev_b64 v[204:205], 13, v[202:203]
	v_add_u32_e32 v208, 0x90, v200
	v_ashrrev_i32_e32 v209, 31, v208
	v_lshlrev_b64 v[210:211], 13, v[208:209]
	v_add_u32_e32 v212, 0xa0, v200
	v_ashrrev_i32_e32 v213, 31, v212
	v_lshlrev_b64 v[214:215], 13, v[212:213]
	v_add_u32_e32 v216, 0xb0, v200
	v_ashrrev_i32_e32 v217, 31, v216
	v_lshlrev_b64 v[218:219], 13, v[216:217]
	s_lshl_b32 s2, s31, 3
	s_add_i32 s14, s2, 0
	v_cmp_eq_u32_e32 vcc, 0, v155
	s_add_i32 s14, s14, 0x20000
	v_lshl_add_u64 v[196:197], s[70:71], 0, v[206:207]
	v_lshl_add_u64 v[196:197], v[196:197], 0, v[178:179]
	global_load_dwordx4 v[158:161], v[196:197], off
	global_load_dwordx4 v[162:165], v[196:197], off offset:64
	global_load_dwordx4 v[166:169], v[196:197], off offset:512
	global_load_dwordx4 v[170:173], v[196:197], off offset:576
	v_lshl_add_u64 v[196:197], s[70:71], 0, v[182:183]
	v_lshl_add_u64 v[196:197], v[196:197], 0, v[178:179]
	global_load_dwordx4 v[174:177], v[196:197], off
	global_load_dwordx4 v[192:195], v[196:197], off offset:64
	global_load_dwordx4 v[220:223], v[196:197], off offset:512
	global_load_dwordx4 v[224:227], v[196:197], off offset:576
	v_lshl_add_u64 v[196:197], s[70:71], 0, v[186:187]
	v_lshl_add_u64 v[196:197], v[196:197], 0, v[178:179]
	global_load_dwordx4 v[228:231], v[196:197], off
	global_load_dwordx4 v[232:235], v[196:197], off offset:64
	global_load_dwordx4 v[236:239], v[196:197], off offset:512
	global_load_dwordx4 v[240:243], v[196:197], off offset:576
	s_waitcnt vmcnt(8)
	v_pk_mul_f32 v[124:125], v[160:161], s[84:85] op_sel_hi:[1,0]
	v_pk_mul_f32 v[122:123], v[158:159], s[84:85] op_sel_hi:[1,0]
	v_pk_fma_f32 v[64:65], v[64:65], v[152:153], v[124:125]
	v_pk_fma_f32 v[62:63], v[62:63], v[150:151], v[122:123]
	v_pk_mul_f32 v[124:125], v[164:165], s[84:85] op_sel_hi:[1,0]
	v_pk_mul_f32 v[122:123], v[162:163], s[84:85] op_sel_hi:[1,0]
	v_pk_fma_f32 v[44:45], v[44:45], v[148:149], v[124:125]
	v_pk_fma_f32 v[42:43], v[42:43], v[146:147], v[122:123]
	v_pk_mul_f32 v[124:125], v[168:169], s[84:85] op_sel_hi:[1,0]
	v_pk_mul_f32 v[122:123], v[166:167], s[84:85] op_sel_hi:[1,0]
	v_pk_fma_f32 v[36:37], v[36:37], v[144:145], v[124:125]
	v_pk_fma_f32 v[34:35], v[34:35], v[142:143], v[122:123]
	v_pk_mul_f32 v[122:123], v[170:171], s[84:85] op_sel_hi:[1,0]
	v_pk_mul_f32 v[124:125], v[172:173], s[84:85] op_sel_hi:[1,0]
	v_lshl_add_u64 v[196:197], s[70:71], 0, v[198:199]
	v_lshl_add_u64 v[196:197], v[196:197], 0, v[178:179]
	global_load_dwordx4 v[158:161], v[196:197], off
	global_load_dwordx4 v[162:165], v[196:197], off offset:64
	global_load_dwordx4 v[166:169], v[196:197], off offset:512
	global_load_dwordx4 v[170:173], v[196:197], off offset:576
	v_pk_fma_f32 v[2:3], v[2:3], v[138:139], v[122:123]
	v_pk_fma_f32 v[4:5], v[4:5], v[140:141], v[124:125]
	s_waitcnt vmcnt(8)
	v_pk_mul_f32 v[124:125], v[176:177], s[84:85] op_sel_hi:[1,0]
	v_pk_mul_f32 v[122:123], v[174:175], s[84:85] op_sel_hi:[1,0]
	v_pk_fma_f32 v[20:21], v[20:21], v[152:153], v[124:125]
	v_pk_fma_f32 v[18:19], v[18:19], v[150:151], v[122:123]
	v_pk_mul_f32 v[124:125], v[194:195], s[84:85] op_sel_hi:[1,0]
	v_pk_mul_f32 v[122:123], v[192:193], s[84:85] op_sel_hi:[1,0]
	v_pk_fma_f32 v[16:17], v[16:17], v[148:149], v[124:125]
	v_pk_fma_f32 v[14:15], v[14:15], v[146:147], v[122:123]
	v_pk_mul_f32 v[124:125], v[222:223], s[84:85] op_sel_hi:[1,0]
	v_pk_mul_f32 v[122:123], v[220:221], s[84:85] op_sel_hi:[1,0]
	v_pk_fma_f32 v[12:13], v[12:13], v[144:145], v[124:125]
	v_pk_fma_f32 v[10:11], v[10:11], v[142:143], v[122:123]
	v_pk_mul_f32 v[122:123], v[224:225], s[84:85] op_sel_hi:[1,0]
	v_pk_mul_f32 v[124:125], v[226:227], s[84:85] op_sel_hi:[1,0]
	v_lshl_add_u64 v[196:197], s[70:71], 0, v[204:205]
	v_lshl_add_u64 v[196:197], v[196:197], 0, v[178:179]
	global_load_dwordx4 v[174:177], v[196:197], off
	global_load_dwordx4 v[192:195], v[196:197], off offset:64
	global_load_dwordx4 v[220:223], v[196:197], off offset:512
	global_load_dwordx4 v[224:227], v[196:197], off offset:576
	v_pk_fma_f32 v[6:7], v[6:7], v[138:139], v[122:123]
	v_pk_fma_f32 v[8:9], v[8:9], v[140:141], v[124:125]
	s_waitcnt vmcnt(8)
; #define EPI_ROWS(ai, m) _Pragma("unroll") for (int ai = 0; ai < 2; ++ai) _Pragma("unroll") for (int m = 0; m < 4; ++m)
; #define EPI_COLS(bj, n) _Pragma("unroll") for (int bj = 0; bj < 2; ++bj) _Pragma("unroll") for (int n = 0; n < 2; ++n)
;     __device__ __forceinline__ void fused(Acc& acc, const Unit& u, int wr, int wc, int fr, int fq) const {
;     ...
;         EPI_ROWS(ai, m) { const int row = u.pm * 256 + ai * 128 + wr * 64 + m * 16 + fr; const float* hp = H + (size_t)row * D + colb;
;             EPI_COLS(bj, n) { const int co = bj * 128 + n * 16; acc[ai][bj][m][n] = *(const f32x4*)(hp + co) * ALPHA + gv[bj][n] * acc[ai][bj][m][n]; }
;             asm volatile("" : "+v"(acc[ai][0][m][0]), "+v"(acc[ai][0][m][1]), "+v"(acc[ai][1][m][0]), "+v"(acc[ai][1][m][1]));
;             if (m == 3) asm volatile("" ::: "memory"); }
	v_pk_mul_f32 v[124:125], v[230:231], s[84:85] op_sel_hi:[1,0]
	v_pk_mul_f32 v[122:123], v[228:229], s[84:85] op_sel_hi:[1,0]
	v_pk_fma_f32 v[40:41], v[40:41], v[152:153], v[124:125]
	v_pk_fma_f32 v[38:39], v[38:39], v[150:151], v[122:123]
	v_pk_mul_f32 v[124:125], v[234:235], s[84:85] op_sel_hi:[1,0]
	v_pk_mul_f32 v[122:123], v[232:233], s[84:85] op_sel_hi:[1,0]
	v_pk_fma_f32 v[32:33], v[32:33], v[148:149], v[124:125]
	v_pk_fma_f32 v[30:31], v[30:31], v[146:147], v[122:123]
	v_pk_mul_f32 v[124:125], v[238:239], s[84:85] op_sel_hi:[1,0]
	v_pk_mul_f32 v[122:123], v[236:237], s[84:85] op_sel_hi:[1,0]
	v_pk_fma_f32 v[28:29], v[28:29], v[144:145], v[124:125]
	v_pk_fma_f32 v[26:27], v[26:27], v[142:143], v[122:123]
	v_pk_mul_f32 v[122:123], v[240:241], s[84:85] op_sel_hi:[1,0]
	v_pk_mul_f32 v[124:125], v[242:243], s[84:85] op_sel_hi:[1,0]
	v_lshl_add_u64 v[196:197], s[70:71], 0, v[210:211]
	v_lshl_add_u64 v[196:197], v[196:197], 0, v[178:179]
	global_load_dwordx4 v[228:231], v[196:197], off
	global_load_dwordx4 v[232:235], v[196:197], off offset:64
	global_load_dwordx4 v[236:239], v[196:197], off offset:512
	global_load_dwordx4 v[240:243], v[196:197], off offset:576
	v_pk_fma_f32 v[22:23], v[22:23], v[138:139], v[122:123]
	v_pk_fma_f32 v[24:25], v[24:25], v[140:141], v[124:125]
	s_waitcnt vmcnt(8)
	v_pk_mul_f32 v[124:125], v[160:161], s[84:85] op_sel_hi:[1,0]
	v_pk_mul_f32 v[122:123], v[158:159], s[84:85] op_sel_hi:[1,0]
	v_pk_fma_f32 v[60:61], v[60:61], v[152:153], v[124:125]
	v_pk_fma_f32 v[58:59], v[58:59], v[150:151], v[122:123]
	v_pk_mul_f32 v[124:125], v[164:165], s[84:85] op_sel_hi:[1,0]
	v_pk_mul_f32 v[122:123], v[162:163], s[84:85] op_sel_hi:[1,0]
	v_pk_fma_f32 v[56:57], v[56:57], v[148:149], v[124:125]
	v_pk_fma_f32 v[54:55], v[54:55], v[146:147], v[122:123]
	v_pk_mul_f32 v[124:125], v[168:169], s[84:85] op_sel_hi:[1,0]
	v_pk_mul_f32 v[122:123], v[166:167], s[84:85] op_sel_hi:[1,0]
	v_pk_fma_f32 v[52:53], v[52:53], v[144:145], v[124:125]
	v_pk_fma_f32 v[50:51], v[50:51], v[142:143], v[122:123]
	v_pk_mul_f32 v[124:125], v[172:173], s[84:85] op_sel_hi:[1,0]
	v_pk_mul_f32 v[122:123], v[170:171], s[84:85] op_sel_hi:[1,0]
	v_lshl_add_u64 v[196:197], s[70:71], 0, v[214:215]
	v_lshl_add_u64 v[196:197], v[196:197], 0, v[178:179]
	global_load_dwordx4 v[158:161], v[196:197], off
	global_load_dwordx4 v[162:165], v[196:197], off offset:64
	global_load_dwordx4 v[166:169], v[196:197], off offset:512
	global_load_dwordx4 v[170:173], v[196:197], off offset:576
	v_pk_fma_f32 v[48:49], v[48:49], v[140:141], v[124:125]
	v_pk_fma_f32 v[46:47], v[46:47], v[138:139], v[122:123]
	s_waitcnt vmcnt(8)
	v_pk_mul_f32 v[124:125], v[176:177], s[84:85] op_sel_hi:[1,0]
	v_pk_mul_f32 v[122:123], v[174:175], s[84:85] op_sel_hi:[1,0]
	v_pk_fma_f32 v[80:81], v[80:81], v[152:153], v[124:125]
	v_pk_fma_f32 v[78:79], v[78:79], v[150:151], v[122:123]
	v_pk_mul_f32 v[124:125], v[194:195], s[84:85] op_sel_hi:[1,0]
	v_pk_mul_f32 v[122:123], v[192:193], s[84:85] op_sel_hi:[1,0]
	v_pk_fma_f32 v[76:77], v[76:77], v[148:149], v[124:125]
	v_pk_fma_f32 v[74:75], v[74:75], v[146:147], v[122:123]
	v_pk_mul_f32 v[124:125], v[222:223], s[84:85] op_sel_hi:[1,0]
	v_pk_mul_f32 v[122:123], v[220:221], s[84:85] op_sel_hi:[1,0]
	v_pk_fma_f32 v[72:73], v[72:73], v[144:145], v[124:125]
	v_pk_fma_f32 v[70:71], v[70:71], v[142:143], v[122:123]
	v_pk_mul_f32 v[122:123], v[224:225], s[84:85] op_sel_hi:[1,0]
	v_pk_mul_f32 v[124:125], v[226:227], s[84:85] op_sel_hi:[1,0]
	v_lshl_add_u64 v[196:197], s[70:71], 0, v[218:219]
	v_lshl_add_u64 v[196:197], v[196:197], 0, v[178:179]
	global_load_dwordx4 v[174:177], v[196:197], off
	global_load_dwordx4 v[192:195], v[196:197], off offset:64
	global_load_dwordx4 v[220:223], v[196:197], off offset:512
	global_load_dwordx4 v[224:227], v[196:197], off offset:576
	v_pk_fma_f32 v[66:67], v[66:67], v[138:139], v[122:123]
	v_pk_fma_f32 v[68:69], v[68:69], v[140:141], v[124:125]
	s_waitcnt vmcnt(8)
	v_pk_mul_f32 v[124:125], v[230:231], s[84:85] op_sel_hi:[1,0]
	v_pk_mul_f32 v[122:123], v[228:229], s[84:85] op_sel_hi:[1,0]
	v_pk_fma_f32 v[100:101], v[100:101], v[152:153], v[124:125]
	v_pk_fma_f32 v[98:99], v[98:99], v[150:151], v[122:123]
	v_pk_mul_f32 v[124:125], v[234:235], s[84:85] op_sel_hi:[1,0]
	v_pk_mul_f32 v[122:123], v[232:233], s[84:85] op_sel_hi:[1,0]
	v_pk_fma_f32 v[96:97], v[96:97], v[148:149], v[124:125]
	v_pk_fma_f32 v[94:95], v[94:95], v[146:147], v[122:123]
	v_pk_mul_f32 v[124:125], v[238:239], s[84:85] op_sel_hi:[1,0]
	v_pk_mul_f32 v[122:123], v[236:237], s[84:85] op_sel_hi:[1,0]
	v_pk_fma_f32 v[92:93], v[92:93], v[144:145], v[124:125]
	v_pk_fma_f32 v[90:91], v[90:91], v[142:143], v[122:123]
	v_pk_mul_f32 v[122:123], v[240:241], s[84:85] op_sel_hi:[1,0]
	v_pk_mul_f32 v[124:125], v[242:243], s[84:85] op_sel_hi:[1,0]
	v_pk_fma_f32 v[86:87], v[86:87], v[138:139], v[122:123]
	v_pk_fma_f32 v[88:89], v[88:89], v[140:141], v[124:125]
	s_waitcnt vmcnt(4)
	v_pk_mul_f32 v[124:125], v[160:161], s[84:85] op_sel_hi:[1,0]
	v_pk_mul_f32 v[122:123], v[158:159], s[84:85] op_sel_hi:[1,0]
	v_pk_fma_f32 v[128:129], v[120:121], v[152:153], v[124:125]
	v_pk_fma_f32 v[126:127], v[118:119], v[150:151], v[122:123]
	v_pk_mul_f32 v[120:121], v[164:165], s[84:85] op_sel_hi:[1,0]
	v_pk_mul_f32 v[118:119], v[162:163], s[84:85] op_sel_hi:[1,0]
	v_pk_fma_f32 v[124:125], v[116:117], v[148:149], v[120:121]
	v_pk_fma_f32 v[122:123], v[114:115], v[146:147], v[118:119]
	v_pk_mul_f32 v[116:117], v[168:169], s[84:85] op_sel_hi:[1,0]
	v_pk_mul_f32 v[114:115], v[166:167], s[84:85] op_sel_hi:[1,0]
	v_pk_fma_f32 v[120:121], v[112:113], v[144:145], v[116:117]
	v_pk_fma_f32 v[118:119], v[110:111], v[142:143], v[114:115]
	v_pk_mul_f32 v[110:111], v[170:171], s[84:85] op_sel_hi:[1,0]
	v_pk_mul_f32 v[112:113], v[172:173], s[84:85] op_sel_hi:[1,0]
	v_pk_fma_f32 v[114:115], v[106:107], v[138:139], v[110:111]
	v_pk_fma_f32 v[116:117], v[108:109], v[140:141], v[112:113]
	s_waitcnt vmcnt(0)
; __device__ __forceinline__ float shx(float v, int mask, int lane) { return __int_as_float(__builtin_amdgcn_ds_bpermute((lane ^ mask) << 2, __float_as_int(v))); }
;     __device__ __forceinline__ void run(const Acc& v, const Unit& u, int wr, int wc, int fr, int fq, LAS unsigned char* sl, int wid, int lane) const {
;     ...
;                 float sm = 0.f;
; #pragma unroll
;                 for (int bj = 0; bj < 2; ++bj)
; #pragma unroll
;                     for (int n = 0; n < 2; ++n) { const f32x4 x = v[ai][bj][m][n]; sm += (x[0] + x[1]) + (x[2] + x[3]); }
;                 sm += shx(sm, 16, lane); sm += shx(sm, 32, lane);
;                 const float mw = sm * (1.0f / 64.0f); float q = 0.f;
; #pragma unroll
;                 for (int bj = 0; bj < 2; ++bj)
; #pragma unroll
;                     for (int n = 0; n < 2; ++n) { const f32x4 d = v[ai][bj][m][n] - mw; q += (d[0] * d[0] + d[1] * d[1]) + (d[2] * d[2] + d[3] * d[3]); }
;                 q += shx(q, 16, lane); q += shx(q, 32, lane);
;                 if (fq == 0) P[(ai * 128 + wr * 64 + m * 16 + fr) * 4 + wc] = (f32x2){mw, q};
	v_pk_mul_f32 v[108:109], v[176:177], s[84:85] op_sel_hi:[1,0]
	v_pk_mul_f32 v[106:107], v[174:175], s[84:85] op_sel_hi:[1,0]
	v_pk_fma_f32 v[112:113], v[136:137], v[152:153], v[108:109]
	v_pk_fma_f32 v[110:111], v[134:135], v[150:151], v[106:107]
	v_mov_b32_e32 v134, v63
	v_mov_b32_e32 v135, v64
	v_mov_b32_e32 v136, v62
	v_mov_b32_e32 v137, v65
	v_pk_add_f32 v[134:135], v[134:135], v[136:137]
	v_mov_b32_e32 v136, v43
	v_mov_b32_e32 v137, v44
	v_pk_mul_f32 v[108:109], v[194:195], s[84:85] op_sel_hi:[1,0]
	v_pk_mul_f32 v[106:107], v[192:193], s[84:85] op_sel_hi:[1,0]
	v_pk_fma_f32 v[108:109], v[132:133], v[148:149], v[108:109]
	v_pk_fma_f32 v[106:107], v[130:131], v[146:147], v[106:107]
	v_pk_mul_f32 v[132:133], v[222:223], s[84:85] op_sel_hi:[1,0]
	v_pk_mul_f32 v[130:131], v[220:221], s[84:85] op_sel_hi:[1,0]
	v_pk_fma_f32 v[104:105], v[104:105], v[144:145], v[132:133]
	v_pk_fma_f32 v[102:103], v[102:103], v[142:143], v[130:131]
	v_pk_mul_f32 v[130:131], v[224:225], s[84:85] op_sel_hi:[1,0]
	s_nop 0
	v_pk_fma_f32 v[82:83], v[82:83], v[138:139], v[130:131]
	v_mov_b32_e32 v138, v42
	v_mov_b32_e32 v139, v45
	v_pk_mul_f32 v[132:133], v[226:227], s[84:85] op_sel_hi:[1,0]
	v_pk_add_f32 v[136:137], v[136:137], v[138:139]
	v_pk_fma_f32 v[84:85], v[84:85], v[140:141], v[132:133]
	v_add_f32_e32 v133, v134, v135
	v_pk_add_f32 v[136:137], v[136:137], v[136:137] op_sel_hi:[0,1]
	v_add_f32_e32 v135, 0, v133
	v_add_f32_e32 v139, v34, v35
	v_add_f32_e32 v141, v36, v37
	v_mov_b32_e32 v138, v2
	v_mov_b32_e32 v140, v3
	v_mov_b32_e32 v136, v4
	v_mov_b32_e32 v134, v5
	v_lshl_add_u32 v132, v155, 4, v154
	v_pk_add_f32 v[138:139], v[138:139], v[140:141]
	v_pk_add_f32 v[134:135], v[136:137], v[134:135]
	v_lshlrev_b32_e32 v130, 2, v132
	v_pk_add_f32 v[134:135], v[138:139], v[134:135]
	v_xor_b32_e32 v131, 64, v130
	v_add_f32_e32 v133, v134, v135
	v_mov_b32_e32 v134, v133
	s_nop 1
	v_permlane16_swap_b32_e32 v134, v133
	v_xor_b32_e32 v130, 0x80, v130
	v_add_f32_e32 v133, v133, v134
	v_mov_b32_e32 v134, v133
	s_nop 1
	v_permlane32_swap_b32_e32 v134, v133
	v_add_f32_e32 v133, v133, v134
	v_fmamk_f32 v135, v133, 0xbc800000, v65
	v_fmamk_f32 v137, v133, 0xbc800000, v63
	v_fmamk_f32 v134, v133, 0xbc800000, v64
	v_fmamk_f32 v136, v133, 0xbc800000, v62
	v_mul_f32_e32 v137, v137, v137
	v_mul_f32_e32 v135, v135, v135
	v_fmac_f32_e32 v137, v136, v136
	v_fmac_f32_e32 v135, v134, v134
	v_fmamk_f32 v136, v133, 0xbc800000, v45
	v_fmamk_f32 v138, v133, 0xbc800000, v43
	v_add_f32_e32 v134, v137, v135
	v_fmamk_f32 v135, v133, 0xbc800000, v44
	v_fmamk_f32 v137, v133, 0xbc800000, v42
	v_mul_f32_e32 v138, v138, v138
	v_mul_f32_e32 v136, v136, v136
	v_fmac_f32_e32 v138, v137, v137
	v_fmac_f32_e32 v136, v135, v135
	v_add_f32_e32 v135, v138, v136
	v_fmamk_f32 v136, v133, 0xbc800000, v37
	v_fmamk_f32 v138, v133, 0xbc800000, v35
	v_add_f32_e32 v134, v134, v135
	v_fmamk_f32 v135, v133, 0xbc800000, v36
	v_fmamk_f32 v137, v133, 0xbc800000, v34
	v_mul_f32_e32 v138, v138, v138
	v_mul_f32_e32 v136, v136, v136
	v_fmac_f32_e32 v138, v137, v137
	v_fmac_f32_e32 v136, v135, v135
	v_add_f32_e32 v135, v138, v136
	v_fmamk_f32 v136, v133, 0xbc800000, v5
	v_fmamk_f32 v138, v133, 0xbc800000, v3
	v_add_f32_e32 v134, v135, v134
	v_fmamk_f32 v135, v133, 0xbc800000, v4
	v_fmamk_f32 v137, v133, 0xbc800000, v2
	v_mul_f32_e32 v138, v138, v138
	v_mul_f32_e32 v136, v136, v136
	v_fmac_f32_e32 v138, v137, v137
	v_fmac_f32_e32 v136, v135, v135
	v_add_f32_e32 v135, v138, v136
	v_add_f32_e32 v134, v135, v134
	v_mov_b32_e32 v135, v134
	s_nop 1
	v_permlane16_swap_b32_e32 v135, v134
	v_add_f32_e32 v134, v134, v135
	ds_bpermute_b32 v135, v130, v134
	s_and_saveexec_b64 s[2:3], vcc
	s_cbranch_execz .LBB0_1671
	s_lshl_b32 s22, s5, 11
	s_add_i32 s22, s14, s22
	v_mul_f32_e32 v136, 0x3c800000, v133
	s_waitcnt lgkmcnt(0)
	v_add_f32_e32 v137, v134, v135
	v_lshl_add_u32 v133, v154, 5, s22
	ds_write_b64 v133, v[136:137]
.LBB0_1671:
	s_or_b64 exec, exec, s[2:3]
	v_mov_b32_e32 v134, v19
	s_waitcnt lgkmcnt(0)
	v_mov_b32_e32 v135, v20
	v_mov_b32_e32 v136, v18
	v_mov_b32_e32 v137, v21
	v_pk_add_f32 v[134:135], v[134:135], v[136:137]
	v_mov_b32_e32 v136, v15
	v_mov_b32_e32 v137, v16
	v_mov_b32_e32 v138, v14
	v_mov_b32_e32 v139, v17
	v_pk_add_f32 v[136:137], v[136:137], v[138:139]
	v_add_f32_e32 v133, v134, v135
	v_pk_add_f32 v[136:137], v[136:137], v[136:137] op_sel_hi:[0,1]
	v_add_f32_e32 v135, 0, v133
	v_add_f32_e32 v139, v10, v11
	v_add_f32_e32 v141, v12, v13
	v_mov_b32_e32 v138, v6
	v_mov_b32_e32 v140, v7
	v_mov_b32_e32 v136, v8
	v_mov_b32_e32 v134, v9
	v_pk_add_f32 v[138:139], v[138:139], v[140:141]
	v_pk_add_f32 v[134:135], v[136:137], v[134:135]
	s_nop 0
	v_pk_add_f32 v[134:135], v[138:139], v[134:135]
	s_nop 0
	v_add_f32_e32 v133, v134, v135
	v_mov_b32_e32 v134, v133
	s_nop 1
	v_permlane16_swap_b32_e32 v134, v133
	v_add_f32_e32 v133, v133, v134
	v_mov_b32_e32 v134, v133
	s_nop 1
	v_permlane32_swap_b32_e32 v134, v133
	v_add_f32_e32 v133, v133, v134
	v_fmamk_f32 v135, v133, 0xbc800000, v21
	v_fmamk_f32 v137, v133, 0xbc800000, v19
	v_fmamk_f32 v134, v133, 0xbc800000, v20
	v_fmamk_f32 v136, v133, 0xbc800000, v18
	v_mul_f32_e32 v137, v137, v137
	v_mul_f32_e32 v135, v135, v135
	v_fmac_f32_e32 v137, v136, v136
	v_fmac_f32_e32 v135, v134, v134
	v_fmamk_f32 v136, v133, 0xbc800000, v17
	v_fmamk_f32 v138, v133, 0xbc800000, v15
	v_add_f32_e32 v134, v137, v135
	v_fmamk_f32 v135, v133, 0xbc800000, v16
	v_fmamk_f32 v137, v133, 0xbc800000, v14
	v_mul_f32_e32 v138, v138, v138
	v_mul_f32_e32 v136, v136, v136
	v_fmac_f32_e32 v138, v137, v137
	v_fmac_f32_e32 v136, v135, v135
	v_add_f32_e32 v135, v138, v136
	v_fmamk_f32 v136, v133, 0xbc800000, v13
	v_fmamk_f32 v138, v133, 0xbc800000, v11
	v_add_f32_e32 v134, v134, v135
	v_fmamk_f32 v135, v133, 0xbc800000, v12
	v_fmamk_f32 v137, v133, 0xbc800000, v10
	v_mul_f32_e32 v138, v138, v138
	v_mul_f32_e32 v136, v136, v136
	v_fmac_f32_e32 v138, v137, v137
	v_fmac_f32_e32 v136, v135, v135
	v_add_f32_e32 v135, v138, v136
	v_fmamk_f32 v136, v133, 0xbc800000, v9
	v_fmamk_f32 v138, v133, 0xbc800000, v7
	v_add_f32_e32 v134, v135, v134
	v_fmamk_f32 v135, v133, 0xbc800000, v8
	v_fmamk_f32 v137, v133, 0xbc800000, v6
	v_mul_f32_e32 v138, v138, v138
	v_mul_f32_e32 v136, v136, v136
	v_fmac_f32_e32 v138, v137, v137
	v_fmac_f32_e32 v136, v135, v135
	v_add_f32_e32 v135, v138, v136
	v_add_f32_e32 v134, v135, v134
	v_mov_b32_e32 v135, v134
	s_nop 1
	v_permlane16_swap_b32_e32 v135, v134
	v_add_f32_e32 v134, v134, v135
	ds_bpermute_b32 v135, v130, v134
	s_and_saveexec_b64 s[2:3], vcc
	s_movk_i32 s35, 0x2000
	s_cbranch_execz .LBB0_1673
	s_lshl_b32 s22, s5, 11
	s_add_i32 s22, s14, s22
	v_mul_f32_e32 v136, 0x3c800000, v133
	s_waitcnt lgkmcnt(0)
	v_add_f32_e32 v137, v134, v135
	v_lshl_add_u32 v133, v154, 5, s22
	ds_write_b64 v133, v[136:137] offset:512
; __device__ __forceinline__ float shx(float v, int mask, int lane) { return __int_as_float(__builtin_amdgcn_ds_bpermute((lane ^ mask) << 2, __float_as_int(v))); }
;     __device__ __forceinline__ void run(const Acc& v, const Unit& u, int wr, int wc, int fr, int fq, LAS unsigned char* sl, int wid, int lane) const {
;     ...
;                 float sm = 0.f;
; #pragma unroll
;                 for (int bj = 0; bj < 2; ++bj)
; #pragma unroll
;                     for (int n = 0; n < 2; ++n) { const f32x4 x = v[ai][bj][m][n]; sm += (x[0] + x[1]) + (x[2] + x[3]); }
;                 sm += shx(sm, 16, lane); sm += shx(sm, 32, lane);
;                 const float mw = sm * (1.0f / 64.0f); float q = 0.f;
; #pragma unroll
;                 for (int bj = 0; bj < 2; ++bj)
; #pragma unroll
;                     for (int n = 0; n < 2; ++n) { const f32x4 d = v[ai][bj][m][n] - mw; q += (d[0] * d[0] + d[1] * d[1]) + (d[2] * d[2] + d[3] * d[3]); }
;                 q += shx(q, 16, lane); q += shx(q, 32, lane);
;                 if (fq == 0) P[(ai * 128 + wr * 64 + m * 16 + fr) * 4 + wc] = (f32x2){mw, q};
.LBB0_1673:
	s_or_b64 exec, exec, s[2:3]
	v_mov_b32_e32 v134, v39
	s_waitcnt lgkmcnt(0)
	v_mov_b32_e32 v135, v40
	v_mov_b32_e32 v136, v38
	v_mov_b32_e32 v137, v41
	v_pk_add_f32 v[134:135], v[134:135], v[136:137]
	v_mov_b32_e32 v136, v31
	v_mov_b32_e32 v137, v32
	v_mov_b32_e32 v138, v30
	v_mov_b32_e32 v139, v33
	v_pk_add_f32 v[136:137], v[136:137], v[138:139]
	v_add_f32_e32 v133, v134, v135
	v_pk_add_f32 v[136:137], v[136:137], v[136:137] op_sel_hi:[0,1]
	v_add_f32_e32 v135, 0, v133
	v_add_f32_e32 v139, v26, v27
	v_add_f32_e32 v141, v28, v29
	v_mov_b32_e32 v138, v22
	v_mov_b32_e32 v140, v23
	v_mov_b32_e32 v136, v24
	v_mov_b32_e32 v134, v25
	v_pk_add_f32 v[138:139], v[138:139], v[140:141]
	v_pk_add_f32 v[134:135], v[136:137], v[134:135]
	s_nop 0
	v_pk_add_f32 v[134:135], v[138:139], v[134:135]
	s_nop 0
	v_add_f32_e32 v133, v134, v135
	v_mov_b32_e32 v134, v133
	s_nop 1
	v_permlane16_swap_b32_e32 v134, v133
	v_add_f32_e32 v133, v133, v134
	v_mov_b32_e32 v134, v133
	s_nop 1
	v_permlane32_swap_b32_e32 v134, v133
	v_add_f32_e32 v133, v133, v134
	v_fmamk_f32 v135, v133, 0xbc800000, v41
	v_fmamk_f32 v137, v133, 0xbc800000, v39
	v_fmamk_f32 v134, v133, 0xbc800000, v40
	v_fmamk_f32 v136, v133, 0xbc800000, v38
	v_mul_f32_e32 v137, v137, v137
	v_mul_f32_e32 v135, v135, v135
	v_fmac_f32_e32 v137, v136, v136
	v_fmac_f32_e32 v135, v134, v134
	v_fmamk_f32 v136, v133, 0xbc800000, v33
	v_fmamk_f32 v138, v133, 0xbc800000, v31
	v_add_f32_e32 v134, v137, v135
	v_fmamk_f32 v135, v133, 0xbc800000, v32
	v_fmamk_f32 v137, v133, 0xbc800000, v30
	v_mul_f32_e32 v138, v138, v138
	v_mul_f32_e32 v136, v136, v136
	v_fmac_f32_e32 v138, v137, v137
	v_fmac_f32_e32 v136, v135, v135
	v_add_f32_e32 v135, v138, v136
	v_fmamk_f32 v136, v133, 0xbc800000, v29
	v_fmamk_f32 v138, v133, 0xbc800000, v27
	v_add_f32_e32 v134, v134, v135
	v_fmamk_f32 v135, v133, 0xbc800000, v28
	v_fmamk_f32 v137, v133, 0xbc800000, v26
	v_mul_f32_e32 v138, v138, v138
	v_mul_f32_e32 v136, v136, v136
	v_fmac_f32_e32 v138, v137, v137
	v_fmac_f32_e32 v136, v135, v135
	v_add_f32_e32 v135, v138, v136
	v_fmamk_f32 v136, v133, 0xbc800000, v25
	v_fmamk_f32 v138, v133, 0xbc800000, v23
	v_add_f32_e32 v134, v135, v134
	v_fmamk_f32 v135, v133, 0xbc800000, v24
	v_fmamk_f32 v137, v133, 0xbc800000, v22
	v_mul_f32_e32 v138, v138, v138
	v_mul_f32_e32 v136, v136, v136
	v_fmac_f32_e32 v138, v137, v137
	v_fmac_f32_e32 v136, v135, v135
	v_add_f32_e32 v135, v138, v136
	v_add_f32_e32 v134, v135, v134
	v_mov_b32_e32 v135, v134
	s_nop 1
	v_permlane16_swap_b32_e32 v135, v134
	v_add_f32_e32 v134, v134, v135
	ds_bpermute_b32 v135, v130, v134
	s_and_saveexec_b64 s[2:3], vcc
	s_cbranch_execz .LBB0_1675
	s_lshl_b32 s22, s5, 11
	s_add_i32 s22, s14, s22
	v_mul_f32_e32 v136, 0x3c800000, v133
	s_waitcnt lgkmcnt(0)
	v_add_f32_e32 v137, v134, v135
	v_lshl_add_u32 v133, v154, 5, s22
	ds_write_b64 v133, v[136:137] offset:1024
.LBB0_1675:
	s_or_b64 exec, exec, s[2:3]
	v_mov_b32_e32 v134, v59
	s_waitcnt lgkmcnt(0)
	v_mov_b32_e32 v135, v60
	v_mov_b32_e32 v136, v58
	v_mov_b32_e32 v137, v61
	v_pk_add_f32 v[134:135], v[134:135], v[136:137]
	v_mov_b32_e32 v136, v55
	v_mov_b32_e32 v137, v56
	v_mov_b32_e32 v138, v54
	v_mov_b32_e32 v139, v57
	v_pk_add_f32 v[136:137], v[136:137], v[138:139]
	v_add_f32_e32 v133, v134, v135
	v_pk_add_f32 v[136:137], v[136:137], v[136:137] op_sel_hi:[0,1]
	v_add_f32_e32 v135, 0, v133
	v_add_f32_e32 v139, v50, v51
	v_add_f32_e32 v141, v52, v53
	v_mov_b32_e32 v138, v46
	v_mov_b32_e32 v140, v47
	v_mov_b32_e32 v136, v48
	v_mov_b32_e32 v134, v49
	v_pk_add_f32 v[138:139], v[138:139], v[140:141]
	v_pk_add_f32 v[134:135], v[136:137], v[134:135]
	s_nop 0
	v_pk_add_f32 v[134:135], v[138:139], v[134:135]
	s_nop 0
	v_add_f32_e32 v133, v134, v135
	v_mov_b32_e32 v134, v133
	s_nop 1
	v_permlane16_swap_b32_e32 v134, v133
	v_add_f32_e32 v133, v133, v134
	v_mov_b32_e32 v134, v133
	s_nop 1
	v_permlane32_swap_b32_e32 v134, v133
	v_add_f32_e32 v133, v133, v134
	v_fmamk_f32 v135, v133, 0xbc800000, v61
	v_fmamk_f32 v137, v133, 0xbc800000, v59
	v_fmamk_f32 v134, v133, 0xbc800000, v60
	v_fmamk_f32 v136, v133, 0xbc800000, v58
	v_mul_f32_e32 v137, v137, v137
	v_mul_f32_e32 v135, v135, v135
	v_fmac_f32_e32 v137, v136, v136
	v_fmac_f32_e32 v135, v134, v134
	v_fmamk_f32 v136, v133, 0xbc800000, v57
	v_fmamk_f32 v138, v133, 0xbc800000, v55
	v_add_f32_e32 v134, v137, v135
	v_fmamk_f32 v135, v133, 0xbc800000, v56
	v_fmamk_f32 v137, v133, 0xbc800000, v54
	v_mul_f32_e32 v138, v138, v138
	v_mul_f32_e32 v136, v136, v136
	v_fmac_f32_e32 v138, v137, v137
	v_fmac_f32_e32 v136, v135, v135
	v_add_f32_e32 v135, v138, v136
	v_fmamk_f32 v136, v133, 0xbc800000, v53
	v_fmamk_f32 v138, v133, 0xbc800000, v51
	v_add_f32_e32 v134, v134, v135
	v_fmamk_f32 v135, v133, 0xbc800000, v52
	v_fmamk_f32 v137, v133, 0xbc800000, v50
	v_mul_f32_e32 v138, v138, v138
	v_mul_f32_e32 v136, v136, v136
	v_fmac_f32_e32 v138, v137, v137
	v_fmac_f32_e32 v136, v135, v135
	v_add_f32_e32 v135, v138, v136
	v_fmamk_f32 v136, v133, 0xbc800000, v49
	v_fmamk_f32 v138, v133, 0xbc800000, v47
	v_add_f32_e32 v134, v135, v134
	v_fmamk_f32 v135, v133, 0xbc800000, v48
	v_fmamk_f32 v137, v133, 0xbc800000, v46
	v_mul_f32_e32 v138, v138, v138
	v_mul_f32_e32 v136, v136, v136
	v_fmac_f32_e32 v138, v137, v137
	v_fmac_f32_e32 v136, v135, v135
	v_add_f32_e32 v135, v138, v136
	v_add_f32_e32 v134, v135, v134
	v_mov_b32_e32 v135, v134
	s_nop 1
	v_permlane16_swap_b32_e32 v135, v134
	v_add_f32_e32 v134, v134, v135
	ds_bpermute_b32 v135, v130, v134
	s_and_saveexec_b64 s[2:3], vcc
	s_cbranch_execz .LBB0_1677
	s_lshl_b32 s22, s5, 11
	s_add_i32 s22, s14, s22
	v_mul_f32_e32 v136, 0x3c800000, v133
	s_waitcnt lgkmcnt(0)
	v_add_f32_e32 v137, v134, v135
	v_lshl_add_u32 v133, v154, 5, s22
	ds_write_b64 v133, v[136:137] offset:1536
; __device__ __forceinline__ float shx(float v, int mask, int lane) { return __int_as_float(__builtin_amdgcn_ds_bpermute((lane ^ mask) << 2, __float_as_int(v))); }
;     __device__ __forceinline__ void run(const Acc& v, const Unit& u, int wr, int wc, int fr, int fq, LAS unsigned char* sl, int wid, int lane) const {
;     ...
;                 float sm = 0.f;
; #pragma unroll
;                 for (int bj = 0; bj < 2; ++bj)
; #pragma unroll
;                     for (int n = 0; n < 2; ++n) { const f32x4 x = v[ai][bj][m][n]; sm += (x[0] + x[1]) + (x[2] + x[3]); }
;                 sm += shx(sm, 16, lane); sm += shx(sm, 32, lane);
;                 const float mw = sm * (1.0f / 64.0f); float q = 0.f;
; #pragma unroll
;                 for (int bj = 0; bj < 2; ++bj)
; #pragma unroll
;                     for (int n = 0; n < 2; ++n) { const f32x4 d = v[ai][bj][m][n] - mw; q += (d[0] * d[0] + d[1] * d[1]) + (d[2] * d[2] + d[3] * d[3]); }
;                 q += shx(q, 16, lane); q += shx(q, 32, lane);
;                 if (fq == 0) P[(ai * 128 + wr * 64 + m * 16 + fr) * 4 + wc] = (f32x2){mw, q};
.LBB0_1677:
	s_or_b64 exec, exec, s[2:3]
	v_mov_b32_e32 v134, v79
	s_waitcnt lgkmcnt(0)
	v_mov_b32_e32 v135, v80
	v_mov_b32_e32 v136, v78
	v_mov_b32_e32 v137, v81
	v_pk_add_f32 v[134:135], v[134:135], v[136:137]
	v_mov_b32_e32 v136, v75
	v_mov_b32_e32 v137, v76
	v_mov_b32_e32 v138, v74
	v_mov_b32_e32 v139, v77
	v_pk_add_f32 v[136:137], v[136:137], v[138:139]
	v_add_f32_e32 v133, v134, v135
	v_pk_add_f32 v[136:137], v[136:137], v[136:137] op_sel_hi:[0,1]
	v_add_f32_e32 v135, 0, v133
	v_add_f32_e32 v139, v70, v71
	v_add_f32_e32 v141, v72, v73
	v_mov_b32_e32 v138, v66
	v_mov_b32_e32 v140, v67
	v_mov_b32_e32 v136, v68
	v_mov_b32_e32 v134, v69
	v_pk_add_f32 v[138:139], v[138:139], v[140:141]
	v_pk_add_f32 v[134:135], v[136:137], v[134:135]
	s_nop 0
	v_pk_add_f32 v[134:135], v[138:139], v[134:135]
	s_nop 0
	v_add_f32_e32 v133, v134, v135
	v_mov_b32_e32 v134, v133
	s_nop 1
	v_permlane16_swap_b32_e32 v134, v133
	v_add_f32_e32 v133, v133, v134
	v_mov_b32_e32 v134, v133
	s_nop 1
	v_permlane32_swap_b32_e32 v134, v133
	v_add_f32_e32 v133, v133, v134
	v_fmamk_f32 v135, v133, 0xbc800000, v81
	v_fmamk_f32 v137, v133, 0xbc800000, v79
	v_fmamk_f32 v134, v133, 0xbc800000, v80
	v_fmamk_f32 v136, v133, 0xbc800000, v78
	v_mul_f32_e32 v137, v137, v137
	v_mul_f32_e32 v135, v135, v135
	v_fmac_f32_e32 v137, v136, v136
	v_fmac_f32_e32 v135, v134, v134
	v_fmamk_f32 v136, v133, 0xbc800000, v77
	v_fmamk_f32 v138, v133, 0xbc800000, v75
	v_add_f32_e32 v134, v137, v135
	v_fmamk_f32 v135, v133, 0xbc800000, v76
	v_fmamk_f32 v137, v133, 0xbc800000, v74
	v_mul_f32_e32 v138, v138, v138
	v_mul_f32_e32 v136, v136, v136
	v_fmac_f32_e32 v138, v137, v137
	v_fmac_f32_e32 v136, v135, v135
	v_add_f32_e32 v135, v138, v136
	v_fmamk_f32 v136, v133, 0xbc800000, v73
	v_fmamk_f32 v138, v133, 0xbc800000, v71
	v_add_f32_e32 v134, v134, v135
	v_fmamk_f32 v135, v133, 0xbc800000, v72
	v_fmamk_f32 v137, v133, 0xbc800000, v70
	v_mul_f32_e32 v138, v138, v138
	v_mul_f32_e32 v136, v136, v136
	v_fmac_f32_e32 v138, v137, v137
	v_fmac_f32_e32 v136, v135, v135
	v_add_f32_e32 v135, v138, v136
	v_fmamk_f32 v136, v133, 0xbc800000, v69
	v_fmamk_f32 v138, v133, 0xbc800000, v67
	v_add_f32_e32 v134, v135, v134
	v_fmamk_f32 v135, v133, 0xbc800000, v68
	v_fmamk_f32 v137, v133, 0xbc800000, v66
	v_mul_f32_e32 v138, v138, v138
	v_mul_f32_e32 v136, v136, v136
	v_fmac_f32_e32 v138, v137, v137
	v_fmac_f32_e32 v136, v135, v135
	v_add_f32_e32 v135, v138, v136
	v_add_f32_e32 v134, v135, v134
	v_mov_b32_e32 v135, v134
	s_nop 1
	v_permlane16_swap_b32_e32 v135, v134
	v_add_f32_e32 v134, v134, v135
	ds_bpermute_b32 v135, v130, v134
	s_and_saveexec_b64 s[2:3], vcc
	s_cbranch_execz .LBB0_1679
	s_lshl_b32 s22, s5, 11
	s_add_i32 s22, s14, s22
	v_mul_f32_e32 v136, 0x3c800000, v133
	s_waitcnt lgkmcnt(0)
	v_add_f32_e32 v137, v134, v135
	v_lshl_add_u32 v133, v154, 5, s22
	ds_write_b64 v133, v[136:137] offset:4096
.LBB0_1679:
	s_or_b64 exec, exec, s[2:3]
	v_mov_b32_e32 v134, v99
	s_waitcnt lgkmcnt(0)
	v_mov_b32_e32 v135, v100
	v_mov_b32_e32 v136, v98
	v_mov_b32_e32 v137, v101
	v_pk_add_f32 v[134:135], v[134:135], v[136:137]
	v_mov_b32_e32 v136, v95
	v_mov_b32_e32 v137, v96
	v_mov_b32_e32 v138, v94
	v_mov_b32_e32 v139, v97
	v_pk_add_f32 v[136:137], v[136:137], v[138:139]
	v_add_f32_e32 v133, v134, v135
	v_pk_add_f32 v[136:137], v[136:137], v[136:137] op_sel_hi:[0,1]
	v_add_f32_e32 v135, 0, v133
	v_add_f32_e32 v139, v90, v91
	v_add_f32_e32 v141, v92, v93
	v_mov_b32_e32 v138, v86
	v_mov_b32_e32 v140, v87
	v_mov_b32_e32 v136, v88
	v_mov_b32_e32 v134, v89
	v_pk_add_f32 v[138:139], v[138:139], v[140:141]
	v_pk_add_f32 v[134:135], v[136:137], v[134:135]
	s_nop 0
	v_pk_add_f32 v[134:135], v[138:139], v[134:135]
	s_nop 0
	v_add_f32_e32 v133, v134, v135
	v_mov_b32_e32 v134, v133
	s_nop 1
	v_permlane16_swap_b32_e32 v134, v133
	v_add_f32_e32 v133, v133, v134
	v_mov_b32_e32 v134, v133
	s_nop 1
	v_permlane32_swap_b32_e32 v134, v133
	v_add_f32_e32 v133, v133, v134
	v_fmamk_f32 v135, v133, 0xbc800000, v101
	v_fmamk_f32 v137, v133, 0xbc800000, v99
	v_fmamk_f32 v134, v133, 0xbc800000, v100
	v_fmamk_f32 v136, v133, 0xbc800000, v98
	v_mul_f32_e32 v137, v137, v137
	v_mul_f32_e32 v135, v135, v135
	v_fmac_f32_e32 v137, v136, v136
	v_fmac_f32_e32 v135, v134, v134
	v_fmamk_f32 v136, v133, 0xbc800000, v97
	v_fmamk_f32 v138, v133, 0xbc800000, v95
	v_add_f32_e32 v134, v137, v135
	v_fmamk_f32 v135, v133, 0xbc800000, v96
	v_fmamk_f32 v137, v133, 0xbc800000, v94
	v_mul_f32_e32 v138, v138, v138
	v_mul_f32_e32 v136, v136, v136
	v_fmac_f32_e32 v138, v137, v137
	v_fmac_f32_e32 v136, v135, v135
	v_add_f32_e32 v135, v138, v136
	v_fmamk_f32 v136, v133, 0xbc800000, v93
	v_fmamk_f32 v138, v133, 0xbc800000, v91
	v_add_f32_e32 v134, v134, v135
	v_fmamk_f32 v135, v133, 0xbc800000, v92
	v_fmamk_f32 v137, v133, 0xbc800000, v90
	v_mul_f32_e32 v138, v138, v138
	v_mul_f32_e32 v136, v136, v136
	v_fmac_f32_e32 v138, v137, v137
	v_fmac_f32_e32 v136, v135, v135
	v_add_f32_e32 v135, v138, v136
	v_fmamk_f32 v136, v133, 0xbc800000, v89
	v_fmamk_f32 v138, v133, 0xbc800000, v87
	v_add_f32_e32 v134, v135, v134
	v_fmamk_f32 v135, v133, 0xbc800000, v88
	v_fmamk_f32 v137, v133, 0xbc800000, v86
	v_mul_f32_e32 v138, v138, v138
	v_mul_f32_e32 v136, v136, v136
	v_fmac_f32_e32 v138, v137, v137
	v_fmac_f32_e32 v136, v135, v135
	v_add_f32_e32 v135, v138, v136
	v_add_f32_e32 v134, v135, v134
	v_mov_b32_e32 v135, v134
	s_nop 1
	v_permlane16_swap_b32_e32 v135, v134
	v_add_f32_e32 v134, v134, v135
	ds_bpermute_b32 v135, v130, v134
	s_and_saveexec_b64 s[2:3], vcc
	s_cbranch_execz .LBB0_1681
	s_lshl_b32 s22, s5, 11
	s_add_i32 s22, s14, s22
	v_mul_f32_e32 v136, 0x3c800000, v133
	s_waitcnt lgkmcnt(0)
	v_add_f32_e32 v137, v134, v135
	v_lshl_add_u32 v133, v154, 5, s22
	ds_write_b64 v133, v[136:137] offset:4608
; __device__ __forceinline__ float shx(float v, int mask, int lane) { return __int_as_float(__builtin_amdgcn_ds_bpermute((lane ^ mask) << 2, __float_as_int(v))); }
;     __device__ __forceinline__ void run(const Acc& v, const Unit& u, int wr, int wc, int fr, int fq, LAS unsigned char* sl, int wid, int lane) const {
;     ...
;                 float sm = 0.f;
; #pragma unroll
;                 for (int bj = 0; bj < 2; ++bj)
; #pragma unroll
;                     for (int n = 0; n < 2; ++n) { const f32x4 x = v[ai][bj][m][n]; sm += (x[0] + x[1]) + (x[2] + x[3]); }
;                 sm += shx(sm, 16, lane); sm += shx(sm, 32, lane);
;                 const float mw = sm * (1.0f / 64.0f); float q = 0.f;
; #pragma unroll
;                 for (int bj = 0; bj < 2; ++bj)
; #pragma unroll
;                     for (int n = 0; n < 2; ++n) { const f32x4 d = v[ai][bj][m][n] - mw; q += (d[0] * d[0] + d[1] * d[1]) + (d[2] * d[2] + d[3] * d[3]); }
;                 q += shx(q, 16, lane); q += shx(q, 32, lane);
;                 if (fq == 0) P[(ai * 128 + wr * 64 + m * 16 + fr) * 4 + wc] = (f32x2){mw, q};
.LBB0_1681:
	s_or_b64 exec, exec, s[2:3]
	v_mov_b32_e32 v134, v127
	s_waitcnt lgkmcnt(0)
	v_mov_b32_e32 v135, v128
	v_mov_b32_e32 v136, v126
	v_mov_b32_e32 v137, v129
	v_pk_add_f32 v[134:135], v[134:135], v[136:137]
	v_mov_b32_e32 v136, v123
	v_mov_b32_e32 v137, v124
	v_mov_b32_e32 v138, v122
	v_mov_b32_e32 v139, v125
	v_pk_add_f32 v[136:137], v[136:137], v[138:139]
	v_add_f32_e32 v133, v134, v135
	v_pk_add_f32 v[136:137], v[136:137], v[136:137] op_sel_hi:[0,1]
	v_add_f32_e32 v135, 0, v133
	v_add_f32_e32 v139, v118, v119
	v_add_f32_e32 v141, v120, v121
	v_mov_b32_e32 v138, v114
	v_mov_b32_e32 v140, v115
	v_mov_b32_e32 v136, v116
	v_mov_b32_e32 v134, v117
	v_pk_add_f32 v[138:139], v[138:139], v[140:141]
	v_pk_add_f32 v[134:135], v[136:137], v[134:135]
	s_nop 0
	v_pk_add_f32 v[134:135], v[138:139], v[134:135]
	s_nop 0
	v_add_f32_e32 v133, v134, v135
	v_mov_b32_e32 v134, v133
	s_nop 1
	v_permlane16_swap_b32_e32 v134, v133
	v_add_f32_e32 v133, v133, v134
	v_mov_b32_e32 v134, v133
	s_nop 1
	v_permlane32_swap_b32_e32 v134, v133
	v_add_f32_e32 v133, v133, v134
	v_fmamk_f32 v135, v133, 0xbc800000, v129
	v_fmamk_f32 v137, v133, 0xbc800000, v127
	v_fmamk_f32 v134, v133, 0xbc800000, v128
	v_fmamk_f32 v136, v133, 0xbc800000, v126
	v_mul_f32_e32 v137, v137, v137
	v_mul_f32_e32 v135, v135, v135
	v_fmac_f32_e32 v137, v136, v136
	v_fmac_f32_e32 v135, v134, v134
	v_fmamk_f32 v136, v133, 0xbc800000, v125
	v_fmamk_f32 v138, v133, 0xbc800000, v123
	v_add_f32_e32 v134, v137, v135
	v_fmamk_f32 v135, v133, 0xbc800000, v124
	v_fmamk_f32 v137, v133, 0xbc800000, v122
	v_mul_f32_e32 v138, v138, v138
	v_mul_f32_e32 v136, v136, v136
	v_fmac_f32_e32 v138, v137, v137
	v_fmac_f32_e32 v136, v135, v135
	v_add_f32_e32 v135, v138, v136
	v_fmamk_f32 v136, v133, 0xbc800000, v121
	v_fmamk_f32 v138, v133, 0xbc800000, v119
	v_add_f32_e32 v134, v134, v135
	v_fmamk_f32 v135, v133, 0xbc800000, v120
	v_fmamk_f32 v137, v133, 0xbc800000, v118
	v_mul_f32_e32 v138, v138, v138
	v_mul_f32_e32 v136, v136, v136
	v_fmac_f32_e32 v138, v137, v137
	v_fmac_f32_e32 v136, v135, v135
	v_add_f32_e32 v135, v138, v136
	v_fmamk_f32 v136, v133, 0xbc800000, v117
	v_fmamk_f32 v138, v133, 0xbc800000, v115
	v_add_f32_e32 v134, v135, v134
	v_fmamk_f32 v135, v133, 0xbc800000, v116
	v_fmamk_f32 v137, v133, 0xbc800000, v114
	v_mul_f32_e32 v138, v138, v138
	v_mul_f32_e32 v136, v136, v136
	v_fmac_f32_e32 v138, v137, v137
	v_fmac_f32_e32 v136, v135, v135
	v_add_f32_e32 v135, v138, v136
	v_add_f32_e32 v134, v135, v134
	v_mov_b32_e32 v135, v134
	s_nop 1
	v_permlane16_swap_b32_e32 v135, v134
	v_add_f32_e32 v134, v134, v135
	ds_bpermute_b32 v135, v130, v134
	s_and_saveexec_b64 s[2:3], vcc
	s_cbranch_execz .LBB0_1683
	s_lshl_b32 s22, s5, 11
	s_add_i32 s22, s14, s22
	v_mul_f32_e32 v136, 0x3c800000, v133
	s_waitcnt lgkmcnt(0)
	v_add_f32_e32 v137, v134, v135
	v_lshl_add_u32 v133, v154, 5, s22
	ds_write_b64 v133, v[136:137] offset:5120
.LBB0_1683:
	s_or_b64 exec, exec, s[2:3]
	v_mov_b32_e32 v134, v111
	s_waitcnt lgkmcnt(0)
	v_mov_b32_e32 v135, v112
	v_mov_b32_e32 v136, v110
	v_mov_b32_e32 v137, v113
	v_pk_add_f32 v[134:135], v[134:135], v[136:137]
	v_mov_b32_e32 v136, v107
	v_mov_b32_e32 v137, v108
	v_mov_b32_e32 v138, v106
	v_mov_b32_e32 v139, v109
	v_pk_add_f32 v[136:137], v[136:137], v[138:139]
	v_add_f32_e32 v133, v134, v135
	v_pk_add_f32 v[136:137], v[136:137], v[136:137] op_sel_hi:[0,1]
	v_add_f32_e32 v135, 0, v133
	v_add_f32_e32 v139, v102, v103
	v_add_f32_e32 v141, v104, v105
	v_mov_b32_e32 v138, v82
	v_mov_b32_e32 v140, v83
	v_mov_b32_e32 v136, v84
	v_mov_b32_e32 v134, v85
	v_pk_add_f32 v[138:139], v[138:139], v[140:141]
	v_pk_add_f32 v[134:135], v[136:137], v[134:135]
	s_nop 0
	v_pk_add_f32 v[134:135], v[138:139], v[134:135]
	s_nop 0
	v_add_f32_e32 v133, v134, v135
	v_mov_b32_e32 v134, v133
	s_nop 1
	v_permlane16_swap_b32_e32 v134, v133
	v_add_f32_e32 v133, v133, v134
	v_mov_b32_e32 v134, v133
	s_nop 1
	v_permlane32_swap_b32_e32 v134, v133
	v_add_f32_e32 v133, v133, v134
	v_fmamk_f32 v135, v133, 0xbc800000, v113
	v_fmamk_f32 v137, v133, 0xbc800000, v111
	v_fmamk_f32 v134, v133, 0xbc800000, v112
	v_fmamk_f32 v136, v133, 0xbc800000, v110
	v_mul_f32_e32 v137, v137, v137
	v_mul_f32_e32 v135, v135, v135
	v_fmac_f32_e32 v137, v136, v136
	v_fmac_f32_e32 v135, v134, v134
	v_fmamk_f32 v136, v133, 0xbc800000, v109
	v_fmamk_f32 v138, v133, 0xbc800000, v107
	v_add_f32_e32 v134, v137, v135
	v_fmamk_f32 v135, v133, 0xbc800000, v108
	v_fmamk_f32 v137, v133, 0xbc800000, v106
	v_mul_f32_e32 v138, v138, v138
	v_mul_f32_e32 v136, v136, v136
	v_fmac_f32_e32 v138, v137, v137
	v_fmac_f32_e32 v136, v135, v135
	v_add_f32_e32 v135, v138, v136
	v_fmamk_f32 v136, v133, 0xbc800000, v105
	v_fmamk_f32 v138, v133, 0xbc800000, v103
	v_add_f32_e32 v134, v134, v135
	v_fmamk_f32 v135, v133, 0xbc800000, v104
	v_fmamk_f32 v137, v133, 0xbc800000, v102
	v_mul_f32_e32 v138, v138, v138
	v_mul_f32_e32 v136, v136, v136
	v_fmac_f32_e32 v138, v137, v137
	v_fmac_f32_e32 v136, v135, v135
	v_add_f32_e32 v135, v138, v136
	v_fmamk_f32 v136, v133, 0xbc800000, v85
	v_fmamk_f32 v138, v133, 0xbc800000, v83
	v_add_f32_e32 v134, v135, v134
	v_fmamk_f32 v135, v133, 0xbc800000, v84
	v_fmamk_f32 v137, v133, 0xbc800000, v82
	v_mul_f32_e32 v138, v138, v138
	v_mul_f32_e32 v136, v136, v136
	v_fmac_f32_e32 v138, v137, v137
	v_fmac_f32_e32 v136, v135, v135
	v_add_f32_e32 v135, v138, v136
	v_add_f32_e32 v134, v135, v134
	ds_bpermute_b32 v131, v131, v134
	s_waitcnt lgkmcnt(0)
	v_add_f32_e32 v131, v134, v131
	ds_bpermute_b32 v130, v130, v131
	s_and_saveexec_b64 s[2:3], vcc
	s_cbranch_execz .LBB0_1685
	s_lshl_b32 s22, s5, 11
	s_add_i32 s14, s14, s22
	v_mul_f32_e32 v134, 0x3c800000, v133
	s_waitcnt lgkmcnt(0)
	v_add_f32_e32 v135, v131, v130
	v_lshl_add_u32 v130, v154, 5, s14
	ds_write_b64 v130, v[134:135] offset:5632

; #define EPI_ROWS(ai, m) _Pragma("unroll") for (int ai = 0; ai < 2; ++ai) _Pragma("unroll") for (int m = 0; m < 4; ++m)
; #define EPI_COLS(bj, n) _Pragma("unroll") for (int bj = 0; bj < 2; ++bj) _Pragma("unroll") for (int n = 0; n < 2; ++n)
;     __device__ __forceinline__ void fused(Acc& acc, const Unit& u, int wr, int wc, int fr, int fq) const {
;         const int colb = u.pn * 256 + wc * 32 + fq * 4;
;         f32x4 gv[2][2];
;         { const float* gp = gate + (size_t)((u.pm * 256) >> 11) * MODW + colb;
;           EPI_COLS(bj, n) gv[bj][n] = *(const f32x4*)(gp + bj * 128 + n * 16); }
;         EPI_ROWS(ai, m) { const int row = u.pm * 256 + ai * 128 + wr * 64 + m * 16 + fr; const float* hp = H + (size_t)row * D + colb;
;             EPI_COLS(bj, n) { const int co = bj * 128 + n * 16; acc[ai][bj][m][n] = *(const f32x4*)(hp + co) * ALPHA + gv[bj][n] * acc[ai][bj][m][n]; }
;             asm volatile("" : "+v"(acc[ai][0][m][0]), "+v"(acc[ai][0][m][1]), "+v"(acc[ai][1][m][0]), "+v"(acc[ai][1][m][1]));
;             if (m == 3) asm volatile("" ::: "memory"); }
.LBB0_1861:
	v_readlane_b32 s16, v255, 44
	s_mul_i32 s14, s16, 0x3c000
	s_add_u32 s14, s8, s14
	s_mul_hi_u32 s16, s16, 0x3c000
	s_addc_u32 s16, s9, s16
	s_add_u32 s51, s14, 0x100000
	s_addc_u32 s52, s16, 0
	s_waitcnt vmcnt(0)
	s_barrier
	s_lshl_b32 s14, s4, 8
	s_lshl_b32 s16, s59, 5
	s_add_i32 s16, s16, s14
	s_ashr_i32 s14, s58, 3
	v_lshl_add_u32 v178, v157, 2, s16
	s_mul_i32 s50, s14, 0xc000
	v_readlane_b32 s17, v255, 45
	s_mul_hi_i32 s24, s14, 0xc000
	s_add_u32 s16, s51, s50
	v_ashrrev_i32_e32 v179, 31, v178
	s_addc_u32 s17, s52, s24
	v_lshlrev_b64 v[154:155], 2, v[178:179]
	s_lshl_b32 s40, s58, 8
	v_lshl_add_u32 v0, s5, 6, v156
	v_lshl_add_u64 v[122:123], s[16:17], 0, v[154:155]
	s_mov_b64 s[16:17], 0xa000
	s_mov_b32 s95, 0xa000
	v_add_u32_e32 v214, s40, v0
	v_lshl_add_u64 v[124:125], v[122:123], 0, s[16:17]
	v_add_co_u32_e32 v122, vcc, s95, v122
	v_ashrrev_i32_e32 v215, 31, v214
	s_nop 0
	v_addc_co_u32_e32 v123, vcc, 0, v123, vcc
	v_lshlrev_b64 v[216:217], 13, v[214:215]
	global_load_dwordx4 v[150:153], v[122:123], off
	global_load_dwordx4 v[146:149], v[124:125], off offset:64
	global_load_dwordx4 v[142:145], v[124:125], off offset:512
	global_load_dwordx4 v[138:141], v[124:125], off offset:576
	v_add_u32_e32 v208, 16, v214
	v_ashrrev_i32_e32 v209, 31, v208
	v_lshlrev_b64 v[212:213], 13, v[208:209]
	v_add_u32_e32 v204, 32, v214
	v_ashrrev_i32_e32 v205, 31, v204
	v_lshlrev_b64 v[210:211], 13, v[204:205]
	v_add_u32_e32 v200, 48, v214
	v_ashrrev_i32_e32 v201, 31, v200
	v_lshlrev_b64 v[206:207], 13, v[200:201]
	v_add_u32_e32 v190, 0x80, v214
	v_ashrrev_i32_e32 v191, 31, v190
	v_lshlrev_b64 v[202:203], 13, v[190:191]
	v_add_u32_e32 v186, 0x90, v214
	v_ashrrev_i32_e32 v187, 31, v186
	v_lshlrev_b64 v[198:199], 13, v[186:187]
	v_add_u32_e32 v184, 0xa0, v214
	v_ashrrev_i32_e32 v185, 31, v184
	v_lshlrev_b64 v[188:189], 13, v[184:185]
	v_add_u32_e32 v180, 0xb0, v214
	v_ashrrev_i32_e32 v181, 31, v180
	v_lshlrev_b64 v[182:183], 13, v[180:181]
	v_cmp_eq_u32_e32 vcc, 0, v157
	v_lshl_add_u64 v[176:177], s[2:3], 0, v[216:217]
	v_lshl_add_u64 v[176:177], v[176:177], 0, v[154:155]
	global_load_dwordx4 v[160:163], v[176:177], off
	global_load_dwordx4 v[164:167], v[176:177], off offset:64
	global_load_dwordx4 v[168:171], v[176:177], off offset:512
	global_load_dwordx4 v[172:175], v[176:177], off offset:576
	v_lshl_add_u64 v[176:177], s[2:3], 0, v[212:213]
	v_lshl_add_u64 v[176:177], v[176:177], 0, v[154:155]
	global_load_dwordx4 v[192:195], v[176:177], off
	global_load_dwordx4 v[218:221], v[176:177], off offset:64
	global_load_dwordx4 v[222:225], v[176:177], off offset:512
	global_load_dwordx4 v[226:229], v[176:177], off offset:576
	s_waitcnt vmcnt(4)
	v_pk_mul_f32 v[124:125], v[162:163], s[84:85] op_sel_hi:[1,0]
	v_pk_mul_f32 v[122:123], v[160:161], s[84:85] op_sel_hi:[1,0]
	v_pk_fma_f32 v[124:125], v[120:121], v[152:153], v[124:125]
	v_pk_fma_f32 v[122:123], v[118:119], v[150:151], v[122:123]
	v_pk_mul_f32 v[120:121], v[166:167], s[84:85] op_sel_hi:[1,0]
	v_pk_mul_f32 v[118:119], v[164:165], s[84:85] op_sel_hi:[1,0]
	v_pk_fma_f32 v[128:129], v[116:117], v[148:149], v[120:121]
	v_pk_fma_f32 v[126:127], v[114:115], v[146:147], v[118:119]
	v_pk_mul_f32 v[116:117], v[170:171], s[84:85] op_sel_hi:[1,0]
	v_pk_mul_f32 v[114:115], v[168:169], s[84:85] op_sel_hi:[1,0]
	v_pk_fma_f32 v[100:101], v[100:101], v[144:145], v[116:117]
	v_pk_fma_f32 v[98:99], v[98:99], v[142:143], v[114:115]
	v_pk_mul_f32 v[114:115], v[172:173], s[84:85] op_sel_hi:[1,0]
	v_pk_mul_f32 v[116:117], v[174:175], s[84:85] op_sel_hi:[1,0]
	v_lshl_add_u64 v[176:177], s[2:3], 0, v[210:211]
	v_lshl_add_u64 v[176:177], v[176:177], 0, v[154:155]
	global_load_dwordx4 v[160:163], v[176:177], off
	global_load_dwordx4 v[164:167], v[176:177], off offset:64
	global_load_dwordx4 v[168:171], v[176:177], off offset:512
	global_load_dwordx4 v[172:175], v[176:177], off offset:576
	v_pk_fma_f32 v[102:103], v[102:103], v[138:139], v[114:115]
	v_pk_fma_f32 v[104:105], v[104:105], v[140:141], v[116:117]
	s_waitcnt vmcnt(4)
	v_pk_mul_f32 v[116:117], v[194:195], s[84:85] op_sel_hi:[1,0]
	v_pk_mul_f32 v[114:115], v[192:193], s[84:85] op_sel_hi:[1,0]
	v_pk_fma_f32 v[116:117], v[112:113], v[152:153], v[116:117]
	v_pk_fma_f32 v[114:115], v[110:111], v[150:151], v[114:115]
	v_pk_mul_f32 v[112:113], v[220:221], s[84:85] op_sel_hi:[1,0]
	v_pk_mul_f32 v[110:111], v[218:219], s[84:85] op_sel_hi:[1,0]
	v_pk_fma_f32 v[120:121], v[108:109], v[148:149], v[112:113]
	v_pk_fma_f32 v[118:119], v[106:107], v[146:147], v[110:111]
	v_pk_mul_f32 v[108:109], v[224:225], s[84:85] op_sel_hi:[1,0]
	v_pk_mul_f32 v[106:107], v[222:223], s[84:85] op_sel_hi:[1,0]
	v_pk_fma_f32 v[92:93], v[92:93], v[144:145], v[108:109]
	v_pk_fma_f32 v[90:91], v[90:91], v[142:143], v[106:107]
	v_pk_mul_f32 v[106:107], v[226:227], s[84:85] op_sel_hi:[1,0]
	v_pk_mul_f32 v[108:109], v[228:229], s[84:85] op_sel_hi:[1,0]
	v_lshl_add_u64 v[176:177], s[2:3], 0, v[206:207]
	v_lshl_add_u64 v[176:177], v[176:177], 0, v[154:155]
	global_load_dwordx4 v[192:195], v[176:177], off
	global_load_dwordx4 v[218:221], v[176:177], off offset:64
	global_load_dwordx4 v[222:225], v[176:177], off offset:512
	global_load_dwordx4 v[226:229], v[176:177], off offset:576
	v_pk_fma_f32 v[94:95], v[94:95], v[138:139], v[106:107]
	v_pk_fma_f32 v[96:97], v[96:97], v[140:141], v[108:109]
	s_waitcnt vmcnt(4)
; #define EPI_ROWS(ai, m) _Pragma("unroll") for (int ai = 0; ai < 2; ++ai) _Pragma("unroll") for (int m = 0; m < 4; ++m)
; #define EPI_COLS(bj, n) _Pragma("unroll") for (int bj = 0; bj < 2; ++bj) _Pragma("unroll") for (int n = 0; n < 2; ++n)
;     __device__ __forceinline__ void fused(Acc& acc, const Unit& u, int wr, int wc, int fr, int fq) const {
;     ...
;         EPI_ROWS(ai, m) { const int row = u.pm * 256 + ai * 128 + wr * 64 + m * 16 + fr; const float* hp = H + (size_t)row * D + colb;
;             EPI_COLS(bj, n) { const int co = bj * 128 + n * 16; acc[ai][bj][m][n] = *(const f32x4*)(hp + co) * ALPHA + gv[bj][n] * acc[ai][bj][m][n]; }
;             asm volatile("" : "+v"(acc[ai][0][m][0]), "+v"(acc[ai][0][m][1]), "+v"(acc[ai][1][m][0]), "+v"(acc[ai][1][m][1]));
;             if (m == 3) asm volatile("" ::: "memory"); }
	v_pk_mul_f32 v[108:109], v[162:163], s[84:85] op_sel_hi:[1,0]
	v_pk_mul_f32 v[106:107], v[160:161], s[84:85] op_sel_hi:[1,0]
	v_pk_fma_f32 v[108:109], v[88:89], v[152:153], v[108:109]
	v_pk_fma_f32 v[106:107], v[86:87], v[150:151], v[106:107]
	v_pk_mul_f32 v[88:89], v[166:167], s[84:85] op_sel_hi:[1,0]
	v_pk_mul_f32 v[86:87], v[164:165], s[84:85] op_sel_hi:[1,0]
	v_pk_fma_f32 v[112:113], v[84:85], v[148:149], v[88:89]
	v_pk_fma_f32 v[110:111], v[82:83], v[146:147], v[86:87]
	v_pk_mul_f32 v[84:85], v[170:171], s[84:85] op_sel_hi:[1,0]
	v_pk_mul_f32 v[82:83], v[168:169], s[84:85] op_sel_hi:[1,0]
	v_pk_fma_f32 v[68:69], v[68:69], v[144:145], v[84:85]
	v_pk_fma_f32 v[66:67], v[66:67], v[142:143], v[82:83]
	v_pk_mul_f32 v[82:83], v[172:173], s[84:85] op_sel_hi:[1,0]
	v_pk_mul_f32 v[84:85], v[174:175], s[84:85] op_sel_hi:[1,0]
	v_lshl_add_u64 v[176:177], s[2:3], 0, v[202:203]
	v_lshl_add_u64 v[176:177], v[176:177], 0, v[154:155]
	global_load_dwordx4 v[160:163], v[176:177], off
	global_load_dwordx4 v[164:167], v[176:177], off offset:64
	global_load_dwordx4 v[168:171], v[176:177], off offset:512
	global_load_dwordx4 v[172:175], v[176:177], off offset:576
	v_pk_fma_f32 v[70:71], v[70:71], v[138:139], v[82:83]
	v_pk_fma_f32 v[72:73], v[72:73], v[140:141], v[84:85]
	s_waitcnt vmcnt(4)
	v_pk_mul_f32 v[84:85], v[194:195], s[84:85] op_sel_hi:[1,0]
	v_pk_mul_f32 v[82:83], v[192:193], s[84:85] op_sel_hi:[1,0]
	v_pk_fma_f32 v[84:85], v[80:81], v[152:153], v[84:85]
	v_pk_fma_f32 v[82:83], v[78:79], v[150:151], v[82:83]
	v_pk_mul_f32 v[80:81], v[220:221], s[84:85] op_sel_hi:[1,0]
	v_pk_mul_f32 v[78:79], v[218:219], s[84:85] op_sel_hi:[1,0]
	v_pk_fma_f32 v[88:89], v[76:77], v[148:149], v[80:81]
	v_pk_fma_f32 v[86:87], v[74:75], v[146:147], v[78:79]
	v_pk_mul_f32 v[76:77], v[224:225], s[84:85] op_sel_hi:[1,0]
	v_pk_mul_f32 v[74:75], v[222:223], s[84:85] op_sel_hi:[1,0]
	v_pk_fma_f32 v[52:53], v[52:53], v[144:145], v[76:77]
	v_pk_fma_f32 v[50:51], v[50:51], v[142:143], v[74:75]
	v_pk_mul_f32 v[76:77], v[228:229], s[84:85] op_sel_hi:[1,0]
	v_pk_mul_f32 v[74:75], v[226:227], s[84:85] op_sel_hi:[1,0]
	v_lshl_add_u64 v[176:177], s[2:3], 0, v[198:199]
	v_lshl_add_u64 v[176:177], v[176:177], 0, v[154:155]
	global_load_dwordx4 v[192:195], v[176:177], off
	global_load_dwordx4 v[218:221], v[176:177], off offset:64
	global_load_dwordx4 v[222:225], v[176:177], off offset:512
	global_load_dwordx4 v[226:229], v[176:177], off offset:576
	v_pk_fma_f32 v[56:57], v[56:57], v[140:141], v[76:77]
	v_pk_fma_f32 v[54:55], v[54:55], v[138:139], v[74:75]
	s_waitcnt vmcnt(4)
	v_pk_mul_f32 v[76:77], v[162:163], s[84:85] op_sel_hi:[1,0]
	v_pk_mul_f32 v[74:75], v[160:161], s[84:85] op_sel_hi:[1,0]
	v_pk_fma_f32 v[76:77], v[64:65], v[152:153], v[76:77]
	v_pk_fma_f32 v[74:75], v[62:63], v[150:151], v[74:75]
	v_pk_mul_f32 v[64:65], v[166:167], s[84:85] op_sel_hi:[1,0]
	v_pk_mul_f32 v[62:63], v[164:165], s[84:85] op_sel_hi:[1,0]
	v_pk_fma_f32 v[80:81], v[60:61], v[148:149], v[64:65]
	v_pk_fma_f32 v[78:79], v[58:59], v[146:147], v[62:63]
	v_pk_mul_f32 v[60:61], v[170:171], s[84:85] op_sel_hi:[1,0]
	v_pk_mul_f32 v[58:59], v[168:169], s[84:85] op_sel_hi:[1,0]
	v_pk_fma_f32 v[44:45], v[44:45], v[144:145], v[60:61]
	v_pk_fma_f32 v[42:43], v[42:43], v[142:143], v[58:59]
	v_pk_mul_f32 v[58:59], v[172:173], s[84:85] op_sel_hi:[1,0]
	v_pk_mul_f32 v[60:61], v[174:175], s[84:85] op_sel_hi:[1,0]
	v_lshl_add_u64 v[176:177], s[2:3], 0, v[188:189]
	v_lshl_add_u64 v[176:177], v[176:177], 0, v[154:155]
	global_load_dwordx4 v[160:163], v[176:177], off
	global_load_dwordx4 v[164:167], v[176:177], off offset:64
	global_load_dwordx4 v[168:171], v[176:177], off offset:512
	global_load_dwordx4 v[172:175], v[176:177], off offset:576
	v_pk_fma_f32 v[46:47], v[46:47], v[138:139], v[58:59]
	v_pk_fma_f32 v[48:49], v[48:49], v[140:141], v[60:61]
	s_waitcnt vmcnt(4)
	v_pk_mul_f32 v[60:61], v[194:195], s[84:85] op_sel_hi:[1,0]
	v_pk_mul_f32 v[58:59], v[192:193], s[84:85] op_sel_hi:[1,0]
	v_pk_fma_f32 v[60:61], v[40:41], v[152:153], v[60:61]
	v_pk_fma_f32 v[58:59], v[38:39], v[150:151], v[58:59]
	v_pk_mul_f32 v[40:41], v[220:221], s[84:85] op_sel_hi:[1,0]
	v_pk_mul_f32 v[38:39], v[218:219], s[84:85] op_sel_hi:[1,0]
	v_pk_fma_f32 v[64:65], v[36:37], v[148:149], v[40:41]
	v_pk_fma_f32 v[62:63], v[34:35], v[146:147], v[38:39]
	v_pk_mul_f32 v[36:37], v[224:225], s[84:85] op_sel_hi:[1,0]
	v_pk_mul_f32 v[34:35], v[222:223], s[84:85] op_sel_hi:[1,0]
	v_pk_fma_f32 v[28:29], v[28:29], v[144:145], v[36:37]
	v_pk_fma_f32 v[26:27], v[26:27], v[142:143], v[34:35]
	v_pk_mul_f32 v[34:35], v[226:227], s[84:85] op_sel_hi:[1,0]
	v_pk_mul_f32 v[36:37], v[228:229], s[84:85] op_sel_hi:[1,0]
	v_lshl_add_u64 v[176:177], s[2:3], 0, v[182:183]
	v_lshl_add_u64 v[176:177], v[176:177], 0, v[154:155]
	global_load_dwordx4 v[192:195], v[176:177], off
	global_load_dwordx4 v[218:221], v[176:177], off offset:64
	global_load_dwordx4 v[222:225], v[176:177], off offset:512
	global_load_dwordx4 v[226:229], v[176:177], off offset:576
	v_pk_fma_f32 v[30:31], v[30:31], v[138:139], v[34:35]
	v_pk_fma_f32 v[32:33], v[32:33], v[140:141], v[36:37]
	s_waitcnt vmcnt(4)
	v_pk_mul_f32 v[36:37], v[162:163], s[84:85] op_sel_hi:[1,0]
	v_pk_mul_f32 v[34:35], v[160:161], s[84:85] op_sel_hi:[1,0]
	v_pk_fma_f32 v[36:37], v[24:25], v[152:153], v[36:37]
	v_pk_fma_f32 v[34:35], v[22:23], v[150:151], v[34:35]
	v_pk_mul_f32 v[24:25], v[166:167], s[84:85] op_sel_hi:[1,0]
	v_pk_mul_f32 v[22:23], v[164:165], s[84:85] op_sel_hi:[1,0]
	v_pk_fma_f32 v[40:41], v[20:21], v[148:149], v[24:25]
	v_pk_fma_f32 v[38:39], v[18:19], v[146:147], v[22:23]
	v_pk_mul_f32 v[20:21], v[170:171], s[84:85] op_sel_hi:[1,0]
	v_pk_mul_f32 v[18:19], v[168:169], s[84:85] op_sel_hi:[1,0]
	v_pk_fma_f32 v[20:21], v[16:17], v[144:145], v[20:21]
	v_pk_fma_f32 v[18:19], v[14:15], v[142:143], v[18:19]
	v_pk_mul_f32 v[14:15], v[172:173], s[84:85] op_sel_hi:[1,0]
	v_pk_mul_f32 v[16:17], v[174:175], s[84:85] op_sel_hi:[1,0]
	v_pk_fma_f32 v[22:23], v[10:11], v[138:139], v[14:15]
	v_pk_fma_f32 v[24:25], v[12:13], v[140:141], v[16:17]
	s_waitcnt vmcnt(0)
; __device__ __forceinline__ float shx(float v, int mask, int lane) { return __int_as_float(__builtin_amdgcn_ds_bpermute((lane ^ mask) << 2, __float_as_int(v))); }
;     __device__ __forceinline__ void run(const Acc& v, const Unit& u, int wr, int wc, int fr, int fq, LAS unsigned char* sl, int wid, int lane) const {
;     ...
;                 float sm = 0.f;
; #pragma unroll
;                 for (int bj = 0; bj < 2; ++bj)
; #pragma unroll
;                     for (int n = 0; n < 2; ++n) { const f32x4 x = v[ai][bj][m][n]; sm += (x[0] + x[1]) + (x[2] + x[3]); }
;                 sm += shx(sm, 16, lane); sm += shx(sm, 32, lane);
;                 const float mw = sm * (1.0f / 64.0f); float q = 0.f;
; #pragma unroll
;                 for (int bj = 0; bj < 2; ++bj)
; #pragma unroll
;                     for (int n = 0; n < 2; ++n) { const f32x4 d = v[ai][bj][m][n] - mw; q += (d[0] * d[0] + d[1] * d[1]) + (d[2] * d[2] + d[3] * d[3]); }
;                 q += shx(q, 16, lane); q += shx(q, 32, lane);
;                 if (fq == 0) P[(ai * 128 + wr * 64 + m * 16 + fr) * 4 + wc] = (f32x2){mw, q};
	s_lshl_b32 s2, s59, 3
	s_add_i32 s14, s2, 0
	s_add_i32 s14, s14, 0x20000
	v_pk_mul_f32 v[12:13], v[194:195], s[84:85] op_sel_hi:[1,0]
	v_pk_mul_f32 v[10:11], v[192:193], s[84:85] op_sel_hi:[1,0]
	v_pk_fma_f32 v[16:17], v[136:137], v[152:153], v[12:13]
	v_pk_fma_f32 v[14:15], v[134:135], v[150:151], v[10:11]
	v_mov_b32_e32 v134, v123
	v_mov_b32_e32 v135, v124
	v_mov_b32_e32 v136, v122
	v_mov_b32_e32 v137, v125
	v_pk_add_f32 v[134:135], v[134:135], v[136:137]
	v_mov_b32_e32 v136, v127
	v_mov_b32_e32 v137, v128
	v_pk_mul_f32 v[12:13], v[220:221], s[84:85] op_sel_hi:[1,0]
	v_pk_mul_f32 v[10:11], v[218:219], s[84:85] op_sel_hi:[1,0]
	v_pk_fma_f32 v[12:13], v[132:133], v[148:149], v[12:13]
	v_pk_fma_f32 v[10:11], v[130:131], v[146:147], v[10:11]
	v_pk_mul_f32 v[132:133], v[224:225], s[84:85] op_sel_hi:[1,0]
	v_pk_mul_f32 v[130:131], v[222:223], s[84:85] op_sel_hi:[1,0]
	v_pk_fma_f32 v[8:9], v[8:9], v[144:145], v[132:133]
	v_pk_fma_f32 v[6:7], v[6:7], v[142:143], v[130:131]
	v_pk_mul_f32 v[130:131], v[226:227], s[84:85] op_sel_hi:[1,0]
	s_nop 0
	v_pk_fma_f32 v[2:3], v[2:3], v[138:139], v[130:131]
	v_mov_b32_e32 v138, v126
	v_mov_b32_e32 v139, v129
	v_pk_mul_f32 v[132:133], v[228:229], s[84:85] op_sel_hi:[1,0]
	v_pk_add_f32 v[136:137], v[136:137], v[138:139]
	v_pk_fma_f32 v[4:5], v[4:5], v[140:141], v[132:133]
	v_add_f32_e32 v133, v134, v135
	v_pk_add_f32 v[136:137], v[136:137], v[136:137] op_sel_hi:[0,1]
	v_add_f32_e32 v135, 0, v133
	v_add_f32_e32 v139, v98, v99
	v_add_f32_e32 v141, v100, v101
	v_mov_b32_e32 v138, v102
	v_mov_b32_e32 v140, v103
	v_mov_b32_e32 v136, v104
	v_mov_b32_e32 v134, v105
	v_lshl_add_u32 v132, v157, 4, v156
	v_pk_add_f32 v[138:139], v[138:139], v[140:141]
	v_pk_add_f32 v[134:135], v[136:137], v[134:135]
	v_lshlrev_b32_e32 v130, 2, v132
	v_pk_add_f32 v[134:135], v[138:139], v[134:135]
	v_xor_b32_e32 v131, 64, v130
	v_add_f32_e32 v133, v134, v135
	v_mov_b32_e32 v134, v133
	s_nop 1
	v_permlane16_swap_b32_e32 v134, v133
	v_xor_b32_e32 v130, 0x80, v130
	v_add_f32_e32 v133, v133, v134
	v_mov_b32_e32 v134, v133
	s_nop 1
	v_permlane32_swap_b32_e32 v134, v133
	v_add_f32_e32 v133, v133, v134
	v_fmamk_f32 v135, v133, 0xbc800000, v125
	v_fmamk_f32 v137, v133, 0xbc800000, v123
	v_fmamk_f32 v134, v133, 0xbc800000, v124
	v_fmamk_f32 v136, v133, 0xbc800000, v122
	v_mul_f32_e32 v137, v137, v137
	v_mul_f32_e32 v135, v135, v135
	v_fmac_f32_e32 v137, v136, v136
	v_fmac_f32_e32 v135, v134, v134
	v_fmamk_f32 v136, v133, 0xbc800000, v129
	v_fmamk_f32 v138, v133, 0xbc800000, v127
	v_add_f32_e32 v134, v137, v135
	v_fmamk_f32 v135, v133, 0xbc800000, v128
	v_fmamk_f32 v137, v133, 0xbc800000, v126
	v_mul_f32_e32 v138, v138, v138
	v_mul_f32_e32 v136, v136, v136
	v_fmac_f32_e32 v138, v137, v137
	v_fmac_f32_e32 v136, v135, v135
	v_add_f32_e32 v135, v138, v136
	v_fmamk_f32 v136, v133, 0xbc800000, v101
	v_fmamk_f32 v138, v133, 0xbc800000, v99
	v_add_f32_e32 v134, v134, v135
	v_fmamk_f32 v135, v133, 0xbc800000, v100
	v_fmamk_f32 v137, v133, 0xbc800000, v98
	v_mul_f32_e32 v138, v138, v138
	v_mul_f32_e32 v136, v136, v136
	v_fmac_f32_e32 v138, v137, v137
	v_fmac_f32_e32 v136, v135, v135
	v_add_f32_e32 v135, v138, v136
	v_fmamk_f32 v136, v133, 0xbc800000, v105
	v_fmamk_f32 v138, v133, 0xbc800000, v103
	v_add_f32_e32 v134, v135, v134
	v_fmamk_f32 v135, v133, 0xbc800000, v104
	v_fmamk_f32 v137, v133, 0xbc800000, v102
	v_mul_f32_e32 v138, v138, v138
	v_mul_f32_e32 v136, v136, v136
	v_fmac_f32_e32 v138, v137, v137
	v_fmac_f32_e32 v136, v135, v135
	v_add_f32_e32 v135, v138, v136
	v_add_f32_e32 v134, v135, v134
	v_mov_b32_e32 v135, v134
	s_nop 1
	v_permlane16_swap_b32_e32 v135, v134
	v_add_f32_e32 v134, v134, v135
	ds_bpermute_b32 v135, v130, v134
	s_and_saveexec_b64 s[2:3], vcc
	s_cbranch_execz .LBB0_1863
	s_lshl_b32 s16, s5, 11
	s_add_i32 s16, s14, s16
	v_mul_f32_e32 v136, 0x3c800000, v133
	s_waitcnt lgkmcnt(0)
	v_add_f32_e32 v137, v134, v135
	v_lshl_add_u32 v133, v156, 5, s16
	ds_write_b64 v133, v[136:137]
.LBB0_1863:
	s_or_b64 exec, exec, s[2:3]
	v_mov_b32_e32 v134, v115
	s_waitcnt lgkmcnt(0)
	v_mov_b32_e32 v135, v116
	v_mov_b32_e32 v136, v114
	v_mov_b32_e32 v137, v117
	v_pk_add_f32 v[134:135], v[134:135], v[136:137]
	v_mov_b32_e32 v136, v119
	v_mov_b32_e32 v137, v120
	v_mov_b32_e32 v138, v118
	v_mov_b32_e32 v139, v121
	v_pk_add_f32 v[136:137], v[136:137], v[138:139]
	v_add_f32_e32 v133, v134, v135
	v_pk_add_f32 v[136:137], v[136:137], v[136:137] op_sel_hi:[0,1]
	v_add_f32_e32 v135, 0, v133
	v_add_f32_e32 v139, v90, v91
	v_add_f32_e32 v141, v92, v93
	v_mov_b32_e32 v138, v94
	v_mov_b32_e32 v140, v95
	v_mov_b32_e32 v136, v96
	v_mov_b32_e32 v134, v97
	v_pk_add_f32 v[138:139], v[138:139], v[140:141]
	v_pk_add_f32 v[134:135], v[136:137], v[134:135]
	s_nop 0
	v_pk_add_f32 v[134:135], v[138:139], v[134:135]
	s_nop 0
	v_add_f32_e32 v133, v134, v135
	v_mov_b32_e32 v134, v133
	s_nop 1
	v_permlane16_swap_b32_e32 v134, v133
	v_add_f32_e32 v133, v133, v134
	v_mov_b32_e32 v134, v133
	s_nop 1
	v_permlane32_swap_b32_e32 v134, v133
	v_add_f32_e32 v133, v133, v134
	v_fmamk_f32 v135, v133, 0xbc800000, v117
	v_fmamk_f32 v137, v133, 0xbc800000, v115
	v_fmamk_f32 v134, v133, 0xbc800000, v116
	v_fmamk_f32 v136, v133, 0xbc800000, v114
	v_mul_f32_e32 v137, v137, v137
	v_mul_f32_e32 v135, v135, v135
	v_fmac_f32_e32 v137, v136, v136
	v_fmac_f32_e32 v135, v134, v134
	v_fmamk_f32 v136, v133, 0xbc800000, v121
	v_fmamk_f32 v138, v133, 0xbc800000, v119
	v_add_f32_e32 v134, v137, v135
	v_fmamk_f32 v135, v133, 0xbc800000, v120
	v_fmamk_f32 v137, v133, 0xbc800000, v118
	v_mul_f32_e32 v138, v138, v138
	v_mul_f32_e32 v136, v136, v136
	v_fmac_f32_e32 v138, v137, v137
	v_fmac_f32_e32 v136, v135, v135
	v_add_f32_e32 v135, v138, v136
	v_fmamk_f32 v136, v133, 0xbc800000, v93
	v_fmamk_f32 v138, v133, 0xbc800000, v91
	v_add_f32_e32 v134, v134, v135
	v_fmamk_f32 v135, v133, 0xbc800000, v92
	v_fmamk_f32 v137, v133, 0xbc800000, v90
	v_mul_f32_e32 v138, v138, v138
	v_mul_f32_e32 v136, v136, v136
	v_fmac_f32_e32 v138, v137, v137
	v_fmac_f32_e32 v136, v135, v135
	v_add_f32_e32 v135, v138, v136
	v_fmamk_f32 v136, v133, 0xbc800000, v97
	v_fmamk_f32 v138, v133, 0xbc800000, v95
	v_add_f32_e32 v134, v135, v134
	v_fmamk_f32 v135, v133, 0xbc800000, v96
	v_fmamk_f32 v137, v133, 0xbc800000, v94
	v_mul_f32_e32 v138, v138, v138
	v_mul_f32_e32 v136, v136, v136
	v_fmac_f32_e32 v138, v137, v137
	v_fmac_f32_e32 v136, v135, v135
	v_add_f32_e32 v135, v138, v136
	v_add_f32_e32 v134, v135, v134
	v_mov_b32_e32 v135, v134
	s_nop 1
	v_permlane16_swap_b32_e32 v135, v134
	v_add_f32_e32 v134, v134, v135
	ds_bpermute_b32 v135, v130, v134
	s_and_saveexec_b64 s[2:3], vcc
	s_load_dwordx2 s[90:91], s[0:1], 0xe0
	v_readlane_b32 s44, v255, 60
	v_readlane_b32 s96, v255, 36
	v_readlane_b32 s85, v255, 37
	v_readlane_b32 s97, v255, 40
	v_readlane_b32 s45, v255, 61
	v_readlane_b32 s27, v255, 62
	s_cbranch_execz .LBB0_1865
; __device__ __forceinline__ float shx(float v, int mask, int lane) { return __int_as_float(__builtin_amdgcn_ds_bpermute((lane ^ mask) << 2, __float_as_int(v))); }
;     __device__ __forceinline__ void run(const Acc& v, const Unit& u, int wr, int wc, int fr, int fq, LAS unsigned char* sl, int wid, int lane) const {
;     ...
;                 float sm = 0.f;
; #pragma unroll
;                 for (int bj = 0; bj < 2; ++bj)
; #pragma unroll
;                     for (int n = 0; n < 2; ++n) { const f32x4 x = v[ai][bj][m][n]; sm += (x[0] + x[1]) + (x[2] + x[3]); }
;                 sm += shx(sm, 16, lane); sm += shx(sm, 32, lane);
;                 const float mw = sm * (1.0f / 64.0f); float q = 0.f;
; #pragma unroll
;                 for (int bj = 0; bj < 2; ++bj)
; #pragma unroll
;                     for (int n = 0; n < 2; ++n) { const f32x4 d = v[ai][bj][m][n] - mw; q += (d[0] * d[0] + d[1] * d[1]) + (d[2] * d[2] + d[3] * d[3]); }
;                 q += shx(q, 16, lane); q += shx(q, 32, lane);
;                 if (fq == 0) P[(ai * 128 + wr * 64 + m * 16 + fr) * 4 + wc] = (f32x2){mw, q};
	s_lshl_b32 s16, s5, 11
	s_add_i32 s16, s14, s16
	v_mul_f32_e32 v136, 0x3c800000, v133
	s_waitcnt lgkmcnt(0)
	v_add_f32_e32 v137, v134, v135
	v_lshl_add_u32 v133, v156, 5, s16
	ds_write_b64 v133, v[136:137] offset:512
.LBB0_1865:
	s_or_b64 exec, exec, s[2:3]
	v_mov_b32_e32 v134, v107
	s_waitcnt lgkmcnt(0)
	v_mov_b32_e32 v135, v108
	v_mov_b32_e32 v136, v106
	v_mov_b32_e32 v137, v109
	v_pk_add_f32 v[134:135], v[134:135], v[136:137]
	v_mov_b32_e32 v136, v111
	v_mov_b32_e32 v137, v112
	v_mov_b32_e32 v138, v110
	v_mov_b32_e32 v139, v113
	v_pk_add_f32 v[136:137], v[136:137], v[138:139]
	v_add_f32_e32 v133, v134, v135
	v_pk_add_f32 v[136:137], v[136:137], v[136:137] op_sel_hi:[0,1]
	v_add_f32_e32 v135, 0, v133
	v_add_f32_e32 v139, v66, v67
	v_add_f32_e32 v141, v68, v69
	v_mov_b32_e32 v138, v70
	v_mov_b32_e32 v140, v71
	v_mov_b32_e32 v136, v72
	v_mov_b32_e32 v134, v73
	v_pk_add_f32 v[138:139], v[138:139], v[140:141]
	v_pk_add_f32 v[134:135], v[136:137], v[134:135]
	s_nop 0
	v_pk_add_f32 v[134:135], v[138:139], v[134:135]
	s_nop 0
	v_add_f32_e32 v133, v134, v135
	v_mov_b32_e32 v134, v133
	s_nop 1
	v_permlane16_swap_b32_e32 v134, v133
	v_add_f32_e32 v133, v133, v134
	v_mov_b32_e32 v134, v133
	s_nop 1
	v_permlane32_swap_b32_e32 v134, v133
	v_add_f32_e32 v133, v133, v134
	v_fmamk_f32 v135, v133, 0xbc800000, v109
	v_fmamk_f32 v137, v133, 0xbc800000, v107
	v_fmamk_f32 v134, v133, 0xbc800000, v108
	v_fmamk_f32 v136, v133, 0xbc800000, v106
	v_mul_f32_e32 v137, v137, v137
	v_mul_f32_e32 v135, v135, v135
	v_fmac_f32_e32 v137, v136, v136
	v_fmac_f32_e32 v135, v134, v134
	v_fmamk_f32 v136, v133, 0xbc800000, v113
	v_fmamk_f32 v138, v133, 0xbc800000, v111
	v_add_f32_e32 v134, v137, v135
	v_fmamk_f32 v135, v133, 0xbc800000, v112
	v_fmamk_f32 v137, v133, 0xbc800000, v110
	v_mul_f32_e32 v138, v138, v138
	v_mul_f32_e32 v136, v136, v136
	v_fmac_f32_e32 v138, v137, v137
	v_fmac_f32_e32 v136, v135, v135
	v_add_f32_e32 v135, v138, v136
	v_fmamk_f32 v136, v133, 0xbc800000, v69
	v_fmamk_f32 v138, v133, 0xbc800000, v67
	v_add_f32_e32 v134, v134, v135
	v_fmamk_f32 v135, v133, 0xbc800000, v68
	v_fmamk_f32 v137, v133, 0xbc800000, v66
	v_mul_f32_e32 v138, v138, v138
	v_mul_f32_e32 v136, v136, v136
	v_fmac_f32_e32 v138, v137, v137
	v_fmac_f32_e32 v136, v135, v135
	v_add_f32_e32 v135, v138, v136
	v_fmamk_f32 v136, v133, 0xbc800000, v73
	v_fmamk_f32 v138, v133, 0xbc800000, v71
	v_add_f32_e32 v134, v135, v134
	v_fmamk_f32 v135, v133, 0xbc800000, v72
	v_fmamk_f32 v137, v133, 0xbc800000, v70
	v_mul_f32_e32 v138, v138, v138
	v_mul_f32_e32 v136, v136, v136
	v_fmac_f32_e32 v138, v137, v137
	v_fmac_f32_e32 v136, v135, v135
	v_add_f32_e32 v135, v138, v136
	v_add_f32_e32 v134, v135, v134
	v_mov_b32_e32 v135, v134
	s_nop 1
	v_permlane16_swap_b32_e32 v135, v134
	v_add_f32_e32 v134, v134, v135
	ds_bpermute_b32 v135, v130, v134
	s_and_saveexec_b64 s[2:3], vcc
	s_cbranch_execz .LBB0_1867
	s_lshl_b32 s16, s5, 11
	s_add_i32 s16, s14, s16
	v_mul_f32_e32 v136, 0x3c800000, v133
	s_waitcnt lgkmcnt(0)
	v_add_f32_e32 v137, v134, v135
	v_lshl_add_u32 v133, v156, 5, s16
	ds_write_b64 v133, v[136:137] offset:1024
.LBB0_1867:
	s_or_b64 exec, exec, s[2:3]
	v_mov_b32_e32 v134, v83
	s_waitcnt lgkmcnt(0)
	v_mov_b32_e32 v135, v84
	v_mov_b32_e32 v136, v82
	v_mov_b32_e32 v137, v85
	v_pk_add_f32 v[134:135], v[134:135], v[136:137]
	v_mov_b32_e32 v136, v87
	v_mov_b32_e32 v137, v88
	v_mov_b32_e32 v138, v86
	v_mov_b32_e32 v139, v89
	v_pk_add_f32 v[136:137], v[136:137], v[138:139]
	v_add_f32_e32 v133, v134, v135
	v_pk_add_f32 v[136:137], v[136:137], v[136:137] op_sel_hi:[0,1]
	v_add_f32_e32 v135, 0, v133
	v_add_f32_e32 v139, v50, v51
	v_add_f32_e32 v141, v52, v53
	v_mov_b32_e32 v138, v54
	v_mov_b32_e32 v140, v55
	v_mov_b32_e32 v136, v56
	v_mov_b32_e32 v134, v57
	v_pk_add_f32 v[138:139], v[138:139], v[140:141]
	v_pk_add_f32 v[134:135], v[136:137], v[134:135]
	s_nop 0
	v_pk_add_f32 v[134:135], v[138:139], v[134:135]
	s_nop 0
	v_add_f32_e32 v133, v134, v135
	v_mov_b32_e32 v134, v133
	s_nop 1
	v_permlane16_swap_b32_e32 v134, v133
	v_add_f32_e32 v133, v133, v134
	v_mov_b32_e32 v134, v133
	s_nop 1
	v_permlane32_swap_b32_e32 v134, v133
	v_add_f32_e32 v133, v133, v134
	v_fmamk_f32 v135, v133, 0xbc800000, v85
	v_fmamk_f32 v137, v133, 0xbc800000, v83
	v_fmamk_f32 v134, v133, 0xbc800000, v84
	v_fmamk_f32 v136, v133, 0xbc800000, v82
	v_mul_f32_e32 v137, v137, v137
	v_mul_f32_e32 v135, v135, v135
	v_fmac_f32_e32 v137, v136, v136
	v_fmac_f32_e32 v135, v134, v134
	v_fmamk_f32 v136, v133, 0xbc800000, v89
	v_fmamk_f32 v138, v133, 0xbc800000, v87
	v_add_f32_e32 v134, v137, v135
	v_fmamk_f32 v135, v133, 0xbc800000, v88
	v_fmamk_f32 v137, v133, 0xbc800000, v86
	v_mul_f32_e32 v138, v138, v138
	v_mul_f32_e32 v136, v136, v136
	v_fmac_f32_e32 v138, v137, v137
	v_fmac_f32_e32 v136, v135, v135
	v_add_f32_e32 v135, v138, v136
	v_fmamk_f32 v136, v133, 0xbc800000, v53
	v_fmamk_f32 v138, v133, 0xbc800000, v51
	v_add_f32_e32 v134, v134, v135
	v_fmamk_f32 v135, v133, 0xbc800000, v52
	v_fmamk_f32 v137, v133, 0xbc800000, v50
	v_mul_f32_e32 v138, v138, v138
	v_mul_f32_e32 v136, v136, v136
	v_fmac_f32_e32 v138, v137, v137
	v_fmac_f32_e32 v136, v135, v135
	v_add_f32_e32 v135, v138, v136
	v_fmamk_f32 v136, v133, 0xbc800000, v57
	v_fmamk_f32 v138, v133, 0xbc800000, v55
	v_add_f32_e32 v134, v135, v134
	v_fmamk_f32 v135, v133, 0xbc800000, v56
	v_fmamk_f32 v137, v133, 0xbc800000, v54
	v_mul_f32_e32 v138, v138, v138
	v_mul_f32_e32 v136, v136, v136
	v_fmac_f32_e32 v138, v137, v137
	v_fmac_f32_e32 v136, v135, v135
	v_add_f32_e32 v135, v138, v136
	v_add_f32_e32 v134, v135, v134
	v_mov_b32_e32 v135, v134
	s_nop 1
	v_permlane16_swap_b32_e32 v135, v134
	v_add_f32_e32 v134, v134, v135
	ds_bpermute_b32 v135, v130, v134
	s_and_saveexec_b64 s[2:3], vcc
	s_cbranch_execz .LBB0_1869
	s_lshl_b32 s16, s5, 11
	s_add_i32 s16, s14, s16
	v_mul_f32_e32 v136, 0x3c800000, v133
	s_waitcnt lgkmcnt(0)
	v_add_f32_e32 v137, v134, v135
	v_lshl_add_u32 v133, v156, 5, s16
	ds_write_b64 v133, v[136:137] offset:1536
; __device__ __forceinline__ float shx(float v, int mask, int lane) { return __int_as_float(__builtin_amdgcn_ds_bpermute((lane ^ mask) << 2, __float_as_int(v))); }
;     __device__ __forceinline__ void run(const Acc& v, const Unit& u, int wr, int wc, int fr, int fq, LAS unsigned char* sl, int wid, int lane) const {
;     ...
;                 float sm = 0.f;
; #pragma unroll
;                 for (int bj = 0; bj < 2; ++bj)
; #pragma unroll
;                     for (int n = 0; n < 2; ++n) { const f32x4 x = v[ai][bj][m][n]; sm += (x[0] + x[1]) + (x[2] + x[3]); }
;                 sm += shx(sm, 16, lane); sm += shx(sm, 32, lane);
;                 const float mw = sm * (1.0f / 64.0f); float q = 0.f;
; #pragma unroll
;                 for (int bj = 0; bj < 2; ++bj)
; #pragma unroll
;                     for (int n = 0; n < 2; ++n) { const f32x4 d = v[ai][bj][m][n] - mw; q += (d[0] * d[0] + d[1] * d[1]) + (d[2] * d[2] + d[3] * d[3]); }
;                 q += shx(q, 16, lane); q += shx(q, 32, lane);
;                 if (fq == 0) P[(ai * 128 + wr * 64 + m * 16 + fr) * 4 + wc] = (f32x2){mw, q};
.LBB0_1869:
	s_or_b64 exec, exec, s[2:3]
	v_mov_b32_e32 v134, v75
	s_waitcnt lgkmcnt(0)
	v_mov_b32_e32 v135, v76
	v_mov_b32_e32 v136, v74
	v_mov_b32_e32 v137, v77
	v_pk_add_f32 v[134:135], v[134:135], v[136:137]
	v_mov_b32_e32 v136, v79
	v_mov_b32_e32 v137, v80
	v_mov_b32_e32 v138, v78
	v_mov_b32_e32 v139, v81
	v_pk_add_f32 v[136:137], v[136:137], v[138:139]
	v_add_f32_e32 v133, v134, v135
	v_pk_add_f32 v[136:137], v[136:137], v[136:137] op_sel_hi:[0,1]
	v_add_f32_e32 v135, 0, v133
	v_add_f32_e32 v139, v42, v43
	v_add_f32_e32 v141, v44, v45
	v_mov_b32_e32 v138, v46
	v_mov_b32_e32 v140, v47
	v_mov_b32_e32 v136, v48
	v_mov_b32_e32 v134, v49
	v_pk_add_f32 v[138:139], v[138:139], v[140:141]
	v_pk_add_f32 v[134:135], v[136:137], v[134:135]
	s_nop 0
	v_pk_add_f32 v[134:135], v[138:139], v[134:135]
	s_nop 0
	v_add_f32_e32 v133, v134, v135
	v_mov_b32_e32 v134, v133
	s_nop 1
	v_permlane16_swap_b32_e32 v134, v133
	v_add_f32_e32 v133, v133, v134
	v_mov_b32_e32 v134, v133
	s_nop 1
	v_permlane32_swap_b32_e32 v134, v133
	v_add_f32_e32 v133, v133, v134
	v_fmamk_f32 v135, v133, 0xbc800000, v77
	v_fmamk_f32 v137, v133, 0xbc800000, v75
	v_fmamk_f32 v134, v133, 0xbc800000, v76
	v_fmamk_f32 v136, v133, 0xbc800000, v74
	v_mul_f32_e32 v137, v137, v137
	v_mul_f32_e32 v135, v135, v135
	v_fmac_f32_e32 v137, v136, v136
	v_fmac_f32_e32 v135, v134, v134
	v_fmamk_f32 v136, v133, 0xbc800000, v81
	v_fmamk_f32 v138, v133, 0xbc800000, v79
	v_add_f32_e32 v134, v137, v135
	v_fmamk_f32 v135, v133, 0xbc800000, v80
	v_fmamk_f32 v137, v133, 0xbc800000, v78
	v_mul_f32_e32 v138, v138, v138
	v_mul_f32_e32 v136, v136, v136
	v_fmac_f32_e32 v138, v137, v137
	v_fmac_f32_e32 v136, v135, v135
	v_add_f32_e32 v135, v138, v136
	v_fmamk_f32 v136, v133, 0xbc800000, v45
	v_fmamk_f32 v138, v133, 0xbc800000, v43
	v_add_f32_e32 v134, v134, v135
	v_fmamk_f32 v135, v133, 0xbc800000, v44
	v_fmamk_f32 v137, v133, 0xbc800000, v42
	v_mul_f32_e32 v138, v138, v138
	v_mul_f32_e32 v136, v136, v136
	v_fmac_f32_e32 v138, v137, v137
	v_fmac_f32_e32 v136, v135, v135
	v_add_f32_e32 v135, v138, v136
	v_fmamk_f32 v136, v133, 0xbc800000, v49
	v_fmamk_f32 v138, v133, 0xbc800000, v47
	v_add_f32_e32 v134, v135, v134
	v_fmamk_f32 v135, v133, 0xbc800000, v48
	v_fmamk_f32 v137, v133, 0xbc800000, v46
	v_mul_f32_e32 v138, v138, v138
	v_mul_f32_e32 v136, v136, v136
	v_fmac_f32_e32 v138, v137, v137
	v_fmac_f32_e32 v136, v135, v135
	v_add_f32_e32 v135, v138, v136
	v_add_f32_e32 v134, v135, v134
	v_mov_b32_e32 v135, v134
	s_nop 1
	v_permlane16_swap_b32_e32 v135, v134
	v_add_f32_e32 v134, v134, v135
	ds_bpermute_b32 v135, v130, v134
	s_and_saveexec_b64 s[2:3], vcc
	s_cbranch_execz .LBB0_1871
	s_lshl_b32 s16, s5, 11
	s_add_i32 s16, s14, s16
	v_mul_f32_e32 v136, 0x3c800000, v133
	s_waitcnt lgkmcnt(0)
	v_add_f32_e32 v137, v134, v135
	v_lshl_add_u32 v133, v156, 5, s16
	ds_write_b64 v133, v[136:137] offset:4096
.LBB0_1871:
	s_or_b64 exec, exec, s[2:3]
	v_mov_b32_e32 v134, v59
	s_waitcnt lgkmcnt(0)
	v_mov_b32_e32 v135, v60
	v_mov_b32_e32 v136, v58
	v_mov_b32_e32 v137, v61
	v_pk_add_f32 v[134:135], v[134:135], v[136:137]
	v_mov_b32_e32 v136, v63
	v_mov_b32_e32 v137, v64
	v_mov_b32_e32 v138, v62
	v_mov_b32_e32 v139, v65
	v_pk_add_f32 v[136:137], v[136:137], v[138:139]
	v_add_f32_e32 v133, v134, v135
	v_pk_add_f32 v[136:137], v[136:137], v[136:137] op_sel_hi:[0,1]
	v_add_f32_e32 v135, 0, v133
	v_add_f32_e32 v139, v26, v27
	v_add_f32_e32 v141, v28, v29
	v_mov_b32_e32 v138, v30
	v_mov_b32_e32 v140, v31
	v_mov_b32_e32 v136, v32
	v_mov_b32_e32 v134, v33
	v_pk_add_f32 v[138:139], v[138:139], v[140:141]
	v_pk_add_f32 v[134:135], v[136:137], v[134:135]
	s_nop 0
	v_pk_add_f32 v[134:135], v[138:139], v[134:135]
	s_nop 0
	v_add_f32_e32 v133, v134, v135
	v_mov_b32_e32 v134, v133
	s_nop 1
	v_permlane16_swap_b32_e32 v134, v133
	v_add_f32_e32 v133, v133, v134
	v_mov_b32_e32 v134, v133
	s_nop 1
	v_permlane32_swap_b32_e32 v134, v133
	v_add_f32_e32 v133, v133, v134
	v_fmamk_f32 v135, v133, 0xbc800000, v61
	v_fmamk_f32 v137, v133, 0xbc800000, v59
	v_fmamk_f32 v134, v133, 0xbc800000, v60
	v_fmamk_f32 v136, v133, 0xbc800000, v58
	v_mul_f32_e32 v137, v137, v137
	v_mul_f32_e32 v135, v135, v135
	v_fmac_f32_e32 v137, v136, v136
	v_fmac_f32_e32 v135, v134, v134
	v_fmamk_f32 v136, v133, 0xbc800000, v65
	v_fmamk_f32 v138, v133, 0xbc800000, v63
	v_add_f32_e32 v134, v137, v135
	v_fmamk_f32 v135, v133, 0xbc800000, v64
	v_fmamk_f32 v137, v133, 0xbc800000, v62
	v_mul_f32_e32 v138, v138, v138
	v_mul_f32_e32 v136, v136, v136
	v_fmac_f32_e32 v138, v137, v137
	v_fmac_f32_e32 v136, v135, v135
	v_add_f32_e32 v135, v138, v136
	v_fmamk_f32 v136, v133, 0xbc800000, v29
	v_fmamk_f32 v138, v133, 0xbc800000, v27
	v_add_f32_e32 v134, v134, v135
	v_fmamk_f32 v135, v133, 0xbc800000, v28
	v_fmamk_f32 v137, v133, 0xbc800000, v26
	v_mul_f32_e32 v138, v138, v138
	v_mul_f32_e32 v136, v136, v136
	v_fmac_f32_e32 v138, v137, v137
	v_fmac_f32_e32 v136, v135, v135
	v_add_f32_e32 v135, v138, v136
	v_fmamk_f32 v136, v133, 0xbc800000, v33
	v_fmamk_f32 v138, v133, 0xbc800000, v31
	v_add_f32_e32 v134, v135, v134
	v_fmamk_f32 v135, v133, 0xbc800000, v32
	v_fmamk_f32 v137, v133, 0xbc800000, v30
	v_mul_f32_e32 v138, v138, v138
	v_mul_f32_e32 v136, v136, v136
	v_fmac_f32_e32 v138, v137, v137
	v_fmac_f32_e32 v136, v135, v135
	v_add_f32_e32 v135, v138, v136
	v_add_f32_e32 v134, v135, v134
	v_mov_b32_e32 v135, v134
	s_nop 1
	v_permlane16_swap_b32_e32 v135, v134
	v_add_f32_e32 v134, v134, v135
	ds_bpermute_b32 v135, v130, v134
	s_and_saveexec_b64 s[2:3], vcc
	s_cbranch_execz .LBB0_1873
	s_lshl_b32 s16, s5, 11
	s_add_i32 s16, s14, s16
	v_mul_f32_e32 v136, 0x3c800000, v133
	s_waitcnt lgkmcnt(0)
	v_add_f32_e32 v137, v134, v135
	v_lshl_add_u32 v133, v156, 5, s16
	ds_write_b64 v133, v[136:137] offset:4608
; __device__ __forceinline__ float shx(float v, int mask, int lane) { return __int_as_float(__builtin_amdgcn_ds_bpermute((lane ^ mask) << 2, __float_as_int(v))); }
;     __device__ __forceinline__ void run(const Acc& v, const Unit& u, int wr, int wc, int fr, int fq, LAS unsigned char* sl, int wid, int lane) const {
;     ...
;                 float sm = 0.f;
; #pragma unroll
;                 for (int bj = 0; bj < 2; ++bj)
; #pragma unroll
;                     for (int n = 0; n < 2; ++n) { const f32x4 x = v[ai][bj][m][n]; sm += (x[0] + x[1]) + (x[2] + x[3]); }
;                 sm += shx(sm, 16, lane); sm += shx(sm, 32, lane);
;                 const float mw = sm * (1.0f / 64.0f); float q = 0.f;
; #pragma unroll
;                 for (int bj = 0; bj < 2; ++bj)
; #pragma unroll
;                     for (int n = 0; n < 2; ++n) { const f32x4 d = v[ai][bj][m][n] - mw; q += (d[0] * d[0] + d[1] * d[1]) + (d[2] * d[2] + d[3] * d[3]); }
;                 q += shx(q, 16, lane); q += shx(q, 32, lane);
;                 if (fq == 0) P[(ai * 128 + wr * 64 + m * 16 + fr) * 4 + wc] = (f32x2){mw, q};
.LBB0_1873:
	s_or_b64 exec, exec, s[2:3]
	v_mov_b32_e32 v134, v35
	s_waitcnt lgkmcnt(0)
	v_mov_b32_e32 v135, v36
	v_mov_b32_e32 v136, v34
	v_mov_b32_e32 v137, v37
	v_pk_add_f32 v[134:135], v[134:135], v[136:137]
	v_mov_b32_e32 v136, v39
	v_mov_b32_e32 v137, v40
	v_mov_b32_e32 v138, v38
	v_mov_b32_e32 v139, v41
	v_pk_add_f32 v[136:137], v[136:137], v[138:139]
	v_add_f32_e32 v133, v134, v135
	v_pk_add_f32 v[136:137], v[136:137], v[136:137] op_sel_hi:[0,1]
	v_add_f32_e32 v135, 0, v133
	v_add_f32_e32 v139, v18, v19
	v_add_f32_e32 v141, v20, v21
	v_mov_b32_e32 v138, v22
	v_mov_b32_e32 v140, v23
	v_mov_b32_e32 v136, v24
	v_mov_b32_e32 v134, v25
	v_pk_add_f32 v[138:139], v[138:139], v[140:141]
	v_pk_add_f32 v[134:135], v[136:137], v[134:135]
	s_nop 0
	v_pk_add_f32 v[134:135], v[138:139], v[134:135]
	s_nop 0
	v_add_f32_e32 v133, v134, v135
	v_mov_b32_e32 v134, v133
	s_nop 1
	v_permlane16_swap_b32_e32 v134, v133
	v_add_f32_e32 v133, v133, v134
	v_mov_b32_e32 v134, v133
	s_nop 1
	v_permlane32_swap_b32_e32 v134, v133
	v_add_f32_e32 v133, v133, v134
	v_fmamk_f32 v135, v133, 0xbc800000, v37
	v_fmamk_f32 v137, v133, 0xbc800000, v35
	v_fmamk_f32 v134, v133, 0xbc800000, v36
	v_fmamk_f32 v136, v133, 0xbc800000, v34
	v_mul_f32_e32 v137, v137, v137
	v_mul_f32_e32 v135, v135, v135
	v_fmac_f32_e32 v137, v136, v136
	v_fmac_f32_e32 v135, v134, v134
	v_fmamk_f32 v136, v133, 0xbc800000, v41
	v_fmamk_f32 v138, v133, 0xbc800000, v39
	v_add_f32_e32 v134, v137, v135
	v_fmamk_f32 v135, v133, 0xbc800000, v40
	v_fmamk_f32 v137, v133, 0xbc800000, v38
	v_mul_f32_e32 v138, v138, v138
	v_mul_f32_e32 v136, v136, v136
	v_fmac_f32_e32 v138, v137, v137
	v_fmac_f32_e32 v136, v135, v135
	v_add_f32_e32 v135, v138, v136
	v_fmamk_f32 v136, v133, 0xbc800000, v21
	v_fmamk_f32 v138, v133, 0xbc800000, v19
	v_add_f32_e32 v134, v134, v135
	v_fmamk_f32 v135, v133, 0xbc800000, v20
	v_fmamk_f32 v137, v133, 0xbc800000, v18
	v_mul_f32_e32 v138, v138, v138
	v_mul_f32_e32 v136, v136, v136
	v_fmac_f32_e32 v138, v137, v137
	v_fmac_f32_e32 v136, v135, v135
	v_add_f32_e32 v135, v138, v136
	v_fmamk_f32 v136, v133, 0xbc800000, v25
	v_fmamk_f32 v138, v133, 0xbc800000, v23
	v_add_f32_e32 v134, v135, v134
	v_fmamk_f32 v135, v133, 0xbc800000, v24
	v_fmamk_f32 v137, v133, 0xbc800000, v22
	v_mul_f32_e32 v138, v138, v138
	v_mul_f32_e32 v136, v136, v136
	v_fmac_f32_e32 v138, v137, v137
	v_fmac_f32_e32 v136, v135, v135
	v_add_f32_e32 v135, v138, v136
	v_add_f32_e32 v134, v135, v134
	v_mov_b32_e32 v135, v134
	s_nop 1
	v_permlane16_swap_b32_e32 v135, v134
	v_add_f32_e32 v134, v134, v135
	ds_bpermute_b32 v135, v130, v134
	s_and_saveexec_b64 s[2:3], vcc
	s_cbranch_execz .LBB0_1875
	s_lshl_b32 s16, s5, 11
	s_add_i32 s16, s14, s16
	v_mul_f32_e32 v136, 0x3c800000, v133
	s_waitcnt lgkmcnt(0)
	v_add_f32_e32 v137, v134, v135
	v_lshl_add_u32 v133, v156, 5, s16
	ds_write_b64 v133, v[136:137] offset:5120
.LBB0_1875:
	s_or_b64 exec, exec, s[2:3]
	v_mov_b32_e32 v134, v15
	s_waitcnt lgkmcnt(0)
	v_mov_b32_e32 v135, v16
	v_mov_b32_e32 v136, v14
	v_mov_b32_e32 v137, v17
	v_pk_add_f32 v[134:135], v[134:135], v[136:137]
	v_mov_b32_e32 v136, v11
	v_mov_b32_e32 v137, v12
	v_mov_b32_e32 v138, v10
	v_mov_b32_e32 v139, v13
	v_pk_add_f32 v[136:137], v[136:137], v[138:139]
	v_add_f32_e32 v133, v134, v135
	v_pk_add_f32 v[136:137], v[136:137], v[136:137] op_sel_hi:[0,1]
	v_add_f32_e32 v135, 0, v133
	v_add_f32_e32 v139, v6, v7
	v_add_f32_e32 v141, v8, v9
	v_mov_b32_e32 v138, v2
	v_mov_b32_e32 v140, v3
	v_mov_b32_e32 v136, v4
	v_mov_b32_e32 v134, v5
	v_pk_add_f32 v[138:139], v[138:139], v[140:141]
	v_pk_add_f32 v[134:135], v[136:137], v[134:135]
	s_nop 0
	v_pk_add_f32 v[134:135], v[138:139], v[134:135]
	s_nop 0
	v_add_f32_e32 v133, v134, v135
	v_mov_b32_e32 v134, v133
	s_nop 1
	v_permlane16_swap_b32_e32 v134, v133
	v_add_f32_e32 v133, v133, v134
	v_mov_b32_e32 v134, v133
	s_nop 1
	v_permlane32_swap_b32_e32 v134, v133
	v_add_f32_e32 v133, v133, v134
	v_fmamk_f32 v135, v133, 0xbc800000, v17
	v_fmamk_f32 v137, v133, 0xbc800000, v15
	v_fmamk_f32 v134, v133, 0xbc800000, v16
	v_fmamk_f32 v136, v133, 0xbc800000, v14
	v_mul_f32_e32 v137, v137, v137
	v_mul_f32_e32 v135, v135, v135
	v_fmac_f32_e32 v137, v136, v136
	v_fmac_f32_e32 v135, v134, v134
	v_fmamk_f32 v136, v133, 0xbc800000, v13
	v_fmamk_f32 v138, v133, 0xbc800000, v11
	v_add_f32_e32 v134, v137, v135
	v_fmamk_f32 v135, v133, 0xbc800000, v12
	v_fmamk_f32 v137, v133, 0xbc800000, v10
	v_mul_f32_e32 v138, v138, v138
	v_mul_f32_e32 v136, v136, v136
	v_fmac_f32_e32 v138, v137, v137
	v_fmac_f32_e32 v136, v135, v135
	v_add_f32_e32 v135, v138, v136
	v_fmamk_f32 v136, v133, 0xbc800000, v9
	v_fmamk_f32 v138, v133, 0xbc800000, v7
	v_add_f32_e32 v134, v134, v135
	v_fmamk_f32 v135, v133, 0xbc800000, v8
	v_fmamk_f32 v137, v133, 0xbc800000, v6
	v_mul_f32_e32 v138, v138, v138
	v_mul_f32_e32 v136, v136, v136
	v_fmac_f32_e32 v138, v137, v137
	v_fmac_f32_e32 v136, v135, v135
	v_add_f32_e32 v135, v138, v136
	v_fmamk_f32 v136, v133, 0xbc800000, v5
	v_fmamk_f32 v138, v133, 0xbc800000, v3
	v_add_f32_e32 v134, v135, v134
	v_fmamk_f32 v135, v133, 0xbc800000, v4
	v_fmamk_f32 v137, v133, 0xbc800000, v2
	v_mul_f32_e32 v138, v138, v138
	v_mul_f32_e32 v136, v136, v136
	v_fmac_f32_e32 v138, v137, v137
	v_fmac_f32_e32 v136, v135, v135
	v_add_f32_e32 v135, v138, v136
	v_add_f32_e32 v134, v135, v134
	ds_bpermute_b32 v131, v131, v134
	s_waitcnt lgkmcnt(0)
	v_add_f32_e32 v131, v134, v131
	ds_bpermute_b32 v130, v130, v131
	s_and_saveexec_b64 s[2:3], vcc
	s_cbranch_execz .LBB0_1877
	s_lshl_b32 s16, s5, 11
	s_add_i32 s14, s14, s16
	v_mul_f32_e32 v134, 0x3c800000, v133
	s_waitcnt lgkmcnt(0)
	v_add_f32_e32 v135, v131, v130
	v_lshl_add_u32 v130, v156, 5, s14
	ds_write_b64 v130, v[134:135] offset:5632
